# P1 epilogue: straight-line silu and gelu(+LN stats) tile paths with packed math, in-place cvt, relu-based select (same erf polynomial, f32)
# speedup vs baseline: 1.0335x; 1.0244x over previous
.LBB0_135:
	s_ashr_i32 s73, s46, 1
	s_and_b32 s71, s46, 1
	s_cmp_lt_u32 s46, 4
	s_cbranch_scc1 .Lepi_plain
	s_cmp_eq_u32 s73, 4
	s_cbranch_scc1 .Lepi_plain
	s_cmp_eq_u32 s73, 6
	s_cbranch_scc1 .Lepi_gelu
	s_cmp_eq_u32 s73, 7
	s_cbranch_scc1 .Lepi_gelu
	s_cmp_lg_u32 s73, 2
	s_cbranch_scc1 .Lepi_silu
	s_lshl_b32 s30, s48, 8
	s_cmp_eq_u32 s57, 2
	s_cselect_b32 s47, 0x80, 0
	s_add_i32 s57, s30, s60
	s_add_i32 s57, s57, s47
	s_cmp_lg_u32 s73, 2
	s_mov_b64 s[48:49], -1
	s_cbranch_scc0 .LBB0_324
	s_cmp_lt_u32 s46, 2
	s_cbranch_scc1 .LBB0_148
	s_cmp_lt_i32 s73, 5
	s_cbranch_scc1 .LBB0_149
	s_mov_b64 s[84:85], 0
	s_cmp_gt_i32 s73, 5
	s_mov_b64 s[46:47], 0
	s_mov_b64 s[50:51], -1
	s_cbranch_scc0 .LBB0_146
	s_cmp_gt_i32 s73, 6
	s_cbranch_scc0 .LBB0_143
	s_cmp_eq_u32 s73, 7
	s_mov_b64 s[46:47], -1
	s_cbranch_scc0 .LBB0_142
	s_mov_b64 s[46:47], 0

.Lepi_silu:
	s_lshl_b32 s30, s48, 8
	s_cmp_eq_u32 s57, 2
	s_cselect_b32 s47, 0x80, 0
	s_add_i32 s30, s30, s60
	s_add_i32 s30, s30, s47
	s_cmp_lg_u32 s57, 0
	s_cselect_b32 s49, 1, 0
	v_readlane_b32 s50, v240, 9
	v_readlane_b32 s51, v240, 10
	s_movk_i32 s82, 0x1400
	s_lshl_b32 s83, s71, 9
	s_movk_i32 s81, 0x400
	s_cmp_eq_u32 s73, 8
	s_cselect_b32 s81, 0x800, s81
	s_add_i32 s83, s83, s81
	s_cmp_eq_u32 s73, 3
	s_cbranch_scc1 .Lepi_silu_go
	s_mov_b64 s[50:51], s[26:27]
	s_movk_i32 s82, 0xc00
.Lepi_silu_go:
	v_add_u32_e32 v133, s30, v232
	v_lshl_add_u32 v134, v234, 1, s83
	v_mad_u32_u24 v148, v133, s82, v134
	s_lshl_b32 s81, s82, 4
	s_mov_b32 s80, 0xbfb8aa3b
	v_pk_mul_f32 v[132:133], v[128:129], s[80:81] op_sel_hi:[1,0]
	v_pk_mul_f32 v[134:135], v[130:131], s[80:81] op_sel_hi:[1,0]
	v_pk_mul_f32 v[136:137], v[120:121], s[80:81] op_sel_hi:[1,0]
	v_pk_mul_f32 v[138:139], v[122:123], s[80:81] op_sel_hi:[1,0]
	v_exp_f32_e32 v132, v132
	v_exp_f32_e32 v133, v133
	v_exp_f32_e32 v134, v134
	v_exp_f32_e32 v135, v135
	v_exp_f32_e32 v136, v136
	v_exp_f32_e32 v137, v137
	v_exp_f32_e32 v138, v138
	v_exp_f32_e32 v139, v139
	v_pk_add_f32 v[132:133], v[132:133], 1.0 op_sel_hi:[1,0]
	v_pk_add_f32 v[134:135], v[134:135], 1.0 op_sel_hi:[1,0]
	v_pk_add_f32 v[136:137], v[136:137], 1.0 op_sel_hi:[1,0]
	v_pk_add_f32 v[138:139], v[138:139], 1.0 op_sel_hi:[1,0]
	v_rcp_f32_e32 v132, v132
	v_rcp_f32_e32 v133, v133
	v_rcp_f32_e32 v134, v134
	v_rcp_f32_e32 v135, v135
	v_rcp_f32_e32 v136, v136
	v_rcp_f32_e32 v137, v137
	v_rcp_f32_e32 v138, v138
	v_rcp_f32_e32 v139, v139
	v_pk_mul_f32 v[128:129], v[128:129], v[132:133]
	v_pk_mul_f32 v[130:131], v[130:131], v[134:135]
	v_pk_mul_f32 v[120:121], v[120:121], v[136:137]
	v_pk_mul_f32 v[122:123], v[122:123], v[138:139]
	v_cvt_pk_bf16_f32 v128, v128, v129
	v_cvt_pk_bf16_f32 v129, v130, v131
	v_cvt_pk_bf16_f32 v130, v120, v121
	v_cvt_pk_bf16_f32 v131, v122, v123
	global_store_dwordx4 v148, v[128:131], s[50:51] sc1
	v_pk_mul_f32 v[132:133], v[112:113], s[80:81] op_sel_hi:[1,0]
	v_pk_mul_f32 v[134:135], v[114:115], s[80:81] op_sel_hi:[1,0]
	v_pk_mul_f32 v[136:137], v[104:105], s[80:81] op_sel_hi:[1,0]
	v_pk_mul_f32 v[138:139], v[106:107], s[80:81] op_sel_hi:[1,0]
	v_exp_f32_e32 v132, v132
	v_exp_f32_e32 v133, v133
	v_exp_f32_e32 v134, v134
	v_exp_f32_e32 v135, v135
	v_exp_f32_e32 v136, v136
	v_exp_f32_e32 v137, v137
	v_exp_f32_e32 v138, v138
	v_exp_f32_e32 v139, v139
	v_pk_add_f32 v[132:133], v[132:133], 1.0 op_sel_hi:[1,0]
	v_pk_add_f32 v[134:135], v[134:135], 1.0 op_sel_hi:[1,0]
	v_pk_add_f32 v[136:137], v[136:137], 1.0 op_sel_hi:[1,0]
	v_pk_add_f32 v[138:139], v[138:139], 1.0 op_sel_hi:[1,0]
	v_rcp_f32_e32 v132, v132
	v_rcp_f32_e32 v133, v133
	v_rcp_f32_e32 v134, v134
	v_rcp_f32_e32 v135, v135
	v_rcp_f32_e32 v136, v136
	v_rcp_f32_e32 v137, v137
	v_rcp_f32_e32 v138, v138
	v_rcp_f32_e32 v139, v139
	v_pk_mul_f32 v[112:113], v[112:113], v[132:133]
	v_pk_mul_f32 v[114:115], v[114:115], v[134:135]
	v_pk_mul_f32 v[104:105], v[104:105], v[136:137]
	v_pk_mul_f32 v[106:107], v[106:107], v[138:139]
	v_cvt_pk_bf16_f32 v112, v112, v113
	v_cvt_pk_bf16_f32 v113, v114, v115
	v_cvt_pk_bf16_f32 v114, v104, v105
	v_cvt_pk_bf16_f32 v115, v106, v107
	global_store_dwordx4 v148, v[112:115], s[50:51] offset:256 sc1
	v_add_u32_e32 v148, s81, v148
	v_pk_mul_f32 v[132:133], v[124:125], s[80:81] op_sel_hi:[1,0]
	v_pk_mul_f32 v[134:135], v[126:127], s[80:81] op_sel_hi:[1,0]
	v_pk_mul_f32 v[136:137], v[116:117], s[80:81] op_sel_hi:[1,0]
	v_pk_mul_f32 v[138:139], v[118:119], s[80:81] op_sel_hi:[1,0]
	v_exp_f32_e32 v132, v132
	v_exp_f32_e32 v133, v133
	v_exp_f32_e32 v134, v134
	v_exp_f32_e32 v135, v135
	v_exp_f32_e32 v136, v136
	v_exp_f32_e32 v137, v137
	v_exp_f32_e32 v138, v138
	v_exp_f32_e32 v139, v139
	v_pk_add_f32 v[132:133], v[132:133], 1.0 op_sel_hi:[1,0]
	v_pk_add_f32 v[134:135], v[134:135], 1.0 op_sel_hi:[1,0]
	v_pk_add_f32 v[136:137], v[136:137], 1.0 op_sel_hi:[1,0]
	v_pk_add_f32 v[138:139], v[138:139], 1.0 op_sel_hi:[1,0]
	v_rcp_f32_e32 v132, v132
	v_rcp_f32_e32 v133, v133
	v_rcp_f32_e32 v134, v134
	v_rcp_f32_e32 v135, v135
	v_rcp_f32_e32 v136, v136
	v_rcp_f32_e32 v137, v137
	v_rcp_f32_e32 v138, v138
	v_rcp_f32_e32 v139, v139
	v_pk_mul_f32 v[124:125], v[124:125], v[132:133]
	v_pk_mul_f32 v[126:127], v[126:127], v[134:135]
	v_pk_mul_f32 v[116:117], v[116:117], v[136:137]
	v_pk_mul_f32 v[118:119], v[118:119], v[138:139]
	v_cvt_pk_bf16_f32 v124, v124, v125
	v_cvt_pk_bf16_f32 v125, v126, v127
	v_cvt_pk_bf16_f32 v126, v116, v117
	v_cvt_pk_bf16_f32 v127, v118, v119
	global_store_dwordx4 v148, v[124:127], s[50:51] sc1
	v_pk_mul_f32 v[132:133], v[108:109], s[80:81] op_sel_hi:[1,0]
	v_pk_mul_f32 v[134:135], v[110:111], s[80:81] op_sel_hi:[1,0]
	v_pk_mul_f32 v[136:137], v[100:101], s[80:81] op_sel_hi:[1,0]
	v_pk_mul_f32 v[138:139], v[102:103], s[80:81] op_sel_hi:[1,0]
	v_exp_f32_e32 v132, v132
	v_exp_f32_e32 v133, v133
	v_exp_f32_e32 v134, v134
	v_exp_f32_e32 v135, v135
	v_exp_f32_e32 v136, v136
	v_exp_f32_e32 v137, v137
	v_exp_f32_e32 v138, v138
	v_exp_f32_e32 v139, v139
	v_pk_add_f32 v[132:133], v[132:133], 1.0 op_sel_hi:[1,0]
	v_pk_add_f32 v[134:135], v[134:135], 1.0 op_sel_hi:[1,0]
	v_pk_add_f32 v[136:137], v[136:137], 1.0 op_sel_hi:[1,0]
	v_pk_add_f32 v[138:139], v[138:139], 1.0 op_sel_hi:[1,0]
	v_rcp_f32_e32 v132, v132
	v_rcp_f32_e32 v133, v133
	v_rcp_f32_e32 v134, v134
	v_rcp_f32_e32 v135, v135
	v_rcp_f32_e32 v136, v136
	v_rcp_f32_e32 v137, v137
	v_rcp_f32_e32 v138, v138
	v_rcp_f32_e32 v139, v139
	v_pk_mul_f32 v[108:109], v[108:109], v[132:133]
	v_pk_mul_f32 v[110:111], v[110:111], v[134:135]
	v_pk_mul_f32 v[100:101], v[100:101], v[136:137]
	v_pk_mul_f32 v[102:103], v[102:103], v[138:139]
	v_cvt_pk_bf16_f32 v108, v108, v109
	v_cvt_pk_bf16_f32 v109, v110, v111
	v_cvt_pk_bf16_f32 v110, v100, v101
	v_cvt_pk_bf16_f32 v111, v102, v103
	global_store_dwordx4 v148, v[108:111], s[50:51] offset:256 sc1
	v_add_u32_e32 v148, s81, v148
	v_pk_mul_f32 v[132:133], v[96:97], s[80:81] op_sel_hi:[1,0]
	v_pk_mul_f32 v[134:135], v[98:99], s[80:81] op_sel_hi:[1,0]
	v_pk_mul_f32 v[136:137], v[88:89], s[80:81] op_sel_hi:[1,0]
	v_pk_mul_f32 v[138:139], v[90:91], s[80:81] op_sel_hi:[1,0]
	v_exp_f32_e32 v132, v132
	v_exp_f32_e32 v133, v133
	v_exp_f32_e32 v134, v134
	v_exp_f32_e32 v135, v135
	v_exp_f32_e32 v136, v136
	v_exp_f32_e32 v137, v137
	v_exp_f32_e32 v138, v138
	v_exp_f32_e32 v139, v139
	v_pk_add_f32 v[132:133], v[132:133], 1.0 op_sel_hi:[1,0]
	v_pk_add_f32 v[134:135], v[134:135], 1.0 op_sel_hi:[1,0]
	v_pk_add_f32 v[136:137], v[136:137], 1.0 op_sel_hi:[1,0]
	v_pk_add_f32 v[138:139], v[138:139], 1.0 op_sel_hi:[1,0]
	v_rcp_f32_e32 v132, v132
	v_rcp_f32_e32 v133, v133
	v_rcp_f32_e32 v134, v134
	v_rcp_f32_e32 v135, v135
	v_rcp_f32_e32 v136, v136
	v_rcp_f32_e32 v137, v137
	v_rcp_f32_e32 v138, v138
	v_rcp_f32_e32 v139, v139
	v_pk_mul_f32 v[96:97], v[96:97], v[132:133]
	v_pk_mul_f32 v[98:99], v[98:99], v[134:135]
	v_pk_mul_f32 v[88:89], v[88:89], v[136:137]
	v_pk_mul_f32 v[90:91], v[90:91], v[138:139]
	v_cvt_pk_bf16_f32 v96, v96, v97
	v_cvt_pk_bf16_f32 v97, v98, v99
	v_cvt_pk_bf16_f32 v98, v88, v89
	v_cvt_pk_bf16_f32 v99, v90, v91
	global_store_dwordx4 v148, v[96:99], s[50:51] sc1
	v_pk_mul_f32 v[132:133], v[80:81], s[80:81] op_sel_hi:[1,0]
	v_pk_mul_f32 v[134:135], v[82:83], s[80:81] op_sel_hi:[1,0]
	v_pk_mul_f32 v[136:137], v[72:73], s[80:81] op_sel_hi:[1,0]
	v_pk_mul_f32 v[138:139], v[74:75], s[80:81] op_sel_hi:[1,0]
	v_exp_f32_e32 v132, v132
	v_exp_f32_e32 v133, v133
	v_exp_f32_e32 v134, v134
	v_exp_f32_e32 v135, v135
	v_exp_f32_e32 v136, v136
	v_exp_f32_e32 v137, v137
	v_exp_f32_e32 v138, v138
	v_exp_f32_e32 v139, v139
	v_pk_add_f32 v[132:133], v[132:133], 1.0 op_sel_hi:[1,0]
	v_pk_add_f32 v[134:135], v[134:135], 1.0 op_sel_hi:[1,0]
	v_pk_add_f32 v[136:137], v[136:137], 1.0 op_sel_hi:[1,0]
	v_pk_add_f32 v[138:139], v[138:139], 1.0 op_sel_hi:[1,0]
	v_rcp_f32_e32 v132, v132
	v_rcp_f32_e32 v133, v133
	v_rcp_f32_e32 v134, v134
	v_rcp_f32_e32 v135, v135
	v_rcp_f32_e32 v136, v136
	v_rcp_f32_e32 v137, v137
	v_rcp_f32_e32 v138, v138
	v_rcp_f32_e32 v139, v139
	v_pk_mul_f32 v[80:81], v[80:81], v[132:133]
	v_pk_mul_f32 v[82:83], v[82:83], v[134:135]
	v_pk_mul_f32 v[72:73], v[72:73], v[136:137]
	v_pk_mul_f32 v[74:75], v[74:75], v[138:139]
	v_cvt_pk_bf16_f32 v80, v80, v81
	v_cvt_pk_bf16_f32 v81, v82, v83
	v_cvt_pk_bf16_f32 v82, v72, v73
	v_cvt_pk_bf16_f32 v83, v74, v75
	global_store_dwordx4 v148, v[80:83], s[50:51] offset:256 sc1
	v_add_u32_e32 v148, s81, v148
	v_pk_mul_f32 v[132:133], v[92:93], s[80:81] op_sel_hi:[1,0]
	v_pk_mul_f32 v[134:135], v[94:95], s[80:81] op_sel_hi:[1,0]
	v_pk_mul_f32 v[136:137], v[84:85], s[80:81] op_sel_hi:[1,0]
	v_pk_mul_f32 v[138:139], v[86:87], s[80:81] op_sel_hi:[1,0]
	v_exp_f32_e32 v132, v132
	v_exp_f32_e32 v133, v133
	v_exp_f32_e32 v134, v134
	v_exp_f32_e32 v135, v135
	v_exp_f32_e32 v136, v136
	v_exp_f32_e32 v137, v137
	v_exp_f32_e32 v138, v138
	v_exp_f32_e32 v139, v139
	v_pk_add_f32 v[132:133], v[132:133], 1.0 op_sel_hi:[1,0]
	v_pk_add_f32 v[134:135], v[134:135], 1.0 op_sel_hi:[1,0]
	v_pk_add_f32 v[136:137], v[136:137], 1.0 op_sel_hi:[1,0]
	v_pk_add_f32 v[138:139], v[138:139], 1.0 op_sel_hi:[1,0]
	v_rcp_f32_e32 v132, v132
	v_rcp_f32_e32 v133, v133
	v_rcp_f32_e32 v134, v134
	v_rcp_f32_e32 v135, v135
	v_rcp_f32_e32 v136, v136
	v_rcp_f32_e32 v137, v137
	v_rcp_f32_e32 v138, v138
	v_rcp_f32_e32 v139, v139
	v_pk_mul_f32 v[92:93], v[92:93], v[132:133]
	v_pk_mul_f32 v[94:95], v[94:95], v[134:135]
	v_pk_mul_f32 v[84:85], v[84:85], v[136:137]
	v_pk_mul_f32 v[86:87], v[86:87], v[138:139]
	v_cvt_pk_bf16_f32 v92, v92, v93
	v_cvt_pk_bf16_f32 v93, v94, v95
	v_cvt_pk_bf16_f32 v94, v84, v85
	v_cvt_pk_bf16_f32 v95, v86, v87
	global_store_dwordx4 v148, v[92:95], s[50:51] sc1
	v_pk_mul_f32 v[132:133], v[76:77], s[80:81] op_sel_hi:[1,0]
	v_pk_mul_f32 v[134:135], v[78:79], s[80:81] op_sel_hi:[1,0]
	v_pk_mul_f32 v[136:137], v[68:69], s[80:81] op_sel_hi:[1,0]
	v_pk_mul_f32 v[138:139], v[70:71], s[80:81] op_sel_hi:[1,0]
	v_exp_f32_e32 v132, v132
	v_exp_f32_e32 v133, v133
	v_exp_f32_e32 v134, v134
	v_exp_f32_e32 v135, v135
	v_exp_f32_e32 v136, v136
	v_exp_f32_e32 v137, v137
	v_exp_f32_e32 v138, v138
	v_exp_f32_e32 v139, v139
	v_pk_add_f32 v[132:133], v[132:133], 1.0 op_sel_hi:[1,0]
	v_pk_add_f32 v[134:135], v[134:135], 1.0 op_sel_hi:[1,0]
	v_pk_add_f32 v[136:137], v[136:137], 1.0 op_sel_hi:[1,0]
	v_pk_add_f32 v[138:139], v[138:139], 1.0 op_sel_hi:[1,0]
	v_rcp_f32_e32 v132, v132
	v_rcp_f32_e32 v133, v133
	v_rcp_f32_e32 v134, v134
	v_rcp_f32_e32 v135, v135
	v_rcp_f32_e32 v136, v136
	v_rcp_f32_e32 v137, v137
	v_rcp_f32_e32 v138, v138
	v_rcp_f32_e32 v139, v139
	v_pk_mul_f32 v[76:77], v[76:77], v[132:133]
	v_pk_mul_f32 v[78:79], v[78:79], v[134:135]
	v_pk_mul_f32 v[68:69], v[68:69], v[136:137]
	v_pk_mul_f32 v[70:71], v[70:71], v[138:139]
	v_cvt_pk_bf16_f32 v76, v76, v77
	v_cvt_pk_bf16_f32 v77, v78, v79
	v_cvt_pk_bf16_f32 v78, v68, v69
	v_cvt_pk_bf16_f32 v79, v70, v71
	global_store_dwordx4 v148, v[76:79], s[50:51] offset:256 sc1
	s_mul_i32 s30, s81, 5
	v_add_u32_e32 v148, s30, v148
	s_cmp_lg_u32 s49, 0
	s_cbranch_scc1 .LBB0_326
	v_pk_mul_f32 v[132:133], v[64:65], s[80:81] op_sel_hi:[1,0]
	v_pk_mul_f32 v[134:135], v[66:67], s[80:81] op_sel_hi:[1,0]
	v_pk_mul_f32 v[136:137], v[56:57], s[80:81] op_sel_hi:[1,0]
	v_pk_mul_f32 v[138:139], v[58:59], s[80:81] op_sel_hi:[1,0]
	v_exp_f32_e32 v132, v132
	v_exp_f32_e32 v133, v133
	v_exp_f32_e32 v134, v134
	v_exp_f32_e32 v135, v135
	v_exp_f32_e32 v136, v136
	v_exp_f32_e32 v137, v137
	v_exp_f32_e32 v138, v138
	v_exp_f32_e32 v139, v139
	v_pk_add_f32 v[132:133], v[132:133], 1.0 op_sel_hi:[1,0]
	v_pk_add_f32 v[134:135], v[134:135], 1.0 op_sel_hi:[1,0]
	v_pk_add_f32 v[136:137], v[136:137], 1.0 op_sel_hi:[1,0]
	v_pk_add_f32 v[138:139], v[138:139], 1.0 op_sel_hi:[1,0]
	v_rcp_f32_e32 v132, v132
	v_rcp_f32_e32 v133, v133
	v_rcp_f32_e32 v134, v134
	v_rcp_f32_e32 v135, v135
	v_rcp_f32_e32 v136, v136
	v_rcp_f32_e32 v137, v137
	v_rcp_f32_e32 v138, v138
	v_rcp_f32_e32 v139, v139
	v_pk_mul_f32 v[64:65], v[64:65], v[132:133]
	v_pk_mul_f32 v[66:67], v[66:67], v[134:135]
	v_pk_mul_f32 v[56:57], v[56:57], v[136:137]
	v_pk_mul_f32 v[58:59], v[58:59], v[138:139]
	v_cvt_pk_bf16_f32 v64, v64, v65
	v_cvt_pk_bf16_f32 v65, v66, v67
	v_cvt_pk_bf16_f32 v66, v56, v57
	v_cvt_pk_bf16_f32 v67, v58, v59
	global_store_dwordx4 v148, v[64:67], s[50:51] sc1
	v_pk_mul_f32 v[132:133], v[48:49], s[80:81] op_sel_hi:[1,0]
	v_pk_mul_f32 v[134:135], v[50:51], s[80:81] op_sel_hi:[1,0]
	v_pk_mul_f32 v[136:137], v[40:41], s[80:81] op_sel_hi:[1,0]
	v_pk_mul_f32 v[138:139], v[42:43], s[80:81] op_sel_hi:[1,0]
	v_exp_f32_e32 v132, v132
	v_exp_f32_e32 v133, v133
	v_exp_f32_e32 v134, v134
	v_exp_f32_e32 v135, v135
	v_exp_f32_e32 v136, v136
	v_exp_f32_e32 v137, v137
	v_exp_f32_e32 v138, v138
	v_exp_f32_e32 v139, v139
	v_pk_add_f32 v[132:133], v[132:133], 1.0 op_sel_hi:[1,0]
	v_pk_add_f32 v[134:135], v[134:135], 1.0 op_sel_hi:[1,0]
	v_pk_add_f32 v[136:137], v[136:137], 1.0 op_sel_hi:[1,0]
	v_pk_add_f32 v[138:139], v[138:139], 1.0 op_sel_hi:[1,0]
	v_rcp_f32_e32 v132, v132
	v_rcp_f32_e32 v133, v133
	v_rcp_f32_e32 v134, v134
	v_rcp_f32_e32 v135, v135
	v_rcp_f32_e32 v136, v136
	v_rcp_f32_e32 v137, v137
	v_rcp_f32_e32 v138, v138
	v_rcp_f32_e32 v139, v139
	v_pk_mul_f32 v[48:49], v[48:49], v[132:133]
	v_pk_mul_f32 v[50:51], v[50:51], v[134:135]
	v_pk_mul_f32 v[40:41], v[40:41], v[136:137]
	v_pk_mul_f32 v[42:43], v[42:43], v[138:139]
	v_cvt_pk_bf16_f32 v48, v48, v49
	v_cvt_pk_bf16_f32 v49, v50, v51
	v_cvt_pk_bf16_f32 v50, v40, v41
	v_cvt_pk_bf16_f32 v51, v42, v43
	global_store_dwordx4 v148, v[48:51], s[50:51] offset:256 sc1
	v_add_u32_e32 v148, s81, v148
	v_pk_mul_f32 v[132:133], v[60:61], s[80:81] op_sel_hi:[1,0]
	v_pk_mul_f32 v[134:135], v[62:63], s[80:81] op_sel_hi:[1,0]
	v_pk_mul_f32 v[136:137], v[52:53], s[80:81] op_sel_hi:[1,0]
	v_pk_mul_f32 v[138:139], v[54:55], s[80:81] op_sel_hi:[1,0]
	v_exp_f32_e32 v132, v132
	v_exp_f32_e32 v133, v133
	v_exp_f32_e32 v134, v134
	v_exp_f32_e32 v135, v135
	v_exp_f32_e32 v136, v136
	v_exp_f32_e32 v137, v137
	v_exp_f32_e32 v138, v138
	v_exp_f32_e32 v139, v139
	v_pk_add_f32 v[132:133], v[132:133], 1.0 op_sel_hi:[1,0]
	v_pk_add_f32 v[134:135], v[134:135], 1.0 op_sel_hi:[1,0]
	v_pk_add_f32 v[136:137], v[136:137], 1.0 op_sel_hi:[1,0]
	v_pk_add_f32 v[138:139], v[138:139], 1.0 op_sel_hi:[1,0]
	v_rcp_f32_e32 v132, v132
	v_rcp_f32_e32 v133, v133
	v_rcp_f32_e32 v134, v134
	v_rcp_f32_e32 v135, v135
	v_rcp_f32_e32 v136, v136
	v_rcp_f32_e32 v137, v137
	v_rcp_f32_e32 v138, v138
	v_rcp_f32_e32 v139, v139
	v_pk_mul_f32 v[60:61], v[60:61], v[132:133]
	v_pk_mul_f32 v[62:63], v[62:63], v[134:135]
	v_pk_mul_f32 v[52:53], v[52:53], v[136:137]
	v_pk_mul_f32 v[54:55], v[54:55], v[138:139]
	v_cvt_pk_bf16_f32 v60, v60, v61
	v_cvt_pk_bf16_f32 v61, v62, v63
	v_cvt_pk_bf16_f32 v62, v52, v53
	v_cvt_pk_bf16_f32 v63, v54, v55
	global_store_dwordx4 v148, v[60:63], s[50:51] sc1
	v_pk_mul_f32 v[132:133], v[44:45], s[80:81] op_sel_hi:[1,0]
	v_pk_mul_f32 v[134:135], v[46:47], s[80:81] op_sel_hi:[1,0]
	v_pk_mul_f32 v[136:137], v[36:37], s[80:81] op_sel_hi:[1,0]
	v_pk_mul_f32 v[138:139], v[38:39], s[80:81] op_sel_hi:[1,0]
	v_exp_f32_e32 v132, v132
	v_exp_f32_e32 v133, v133
	v_exp_f32_e32 v134, v134
	v_exp_f32_e32 v135, v135
	v_exp_f32_e32 v136, v136
	v_exp_f32_e32 v137, v137
	v_exp_f32_e32 v138, v138
	v_exp_f32_e32 v139, v139
	v_pk_add_f32 v[132:133], v[132:133], 1.0 op_sel_hi:[1,0]
	v_pk_add_f32 v[134:135], v[134:135], 1.0 op_sel_hi:[1,0]
	v_pk_add_f32 v[136:137], v[136:137], 1.0 op_sel_hi:[1,0]
	v_pk_add_f32 v[138:139], v[138:139], 1.0 op_sel_hi:[1,0]
	v_rcp_f32_e32 v132, v132
	v_rcp_f32_e32 v133, v133
	v_rcp_f32_e32 v134, v134
	v_rcp_f32_e32 v135, v135
	v_rcp_f32_e32 v136, v136
	v_rcp_f32_e32 v137, v137
	v_rcp_f32_e32 v138, v138
	v_rcp_f32_e32 v139, v139
	v_pk_mul_f32 v[44:45], v[44:45], v[132:133]
	v_pk_mul_f32 v[46:47], v[46:47], v[134:135]
	v_pk_mul_f32 v[36:37], v[36:37], v[136:137]
	v_pk_mul_f32 v[38:39], v[38:39], v[138:139]
	v_cvt_pk_bf16_f32 v44, v44, v45
	v_cvt_pk_bf16_f32 v45, v46, v47
	v_cvt_pk_bf16_f32 v46, v36, v37
	v_cvt_pk_bf16_f32 v47, v38, v39
	global_store_dwordx4 v148, v[44:47], s[50:51] offset:256 sc1
	v_add_u32_e32 v148, s81, v148
	v_pk_mul_f32 v[132:133], v[32:33], s[80:81] op_sel_hi:[1,0]
	v_pk_mul_f32 v[134:135], v[34:35], s[80:81] op_sel_hi:[1,0]
	v_pk_mul_f32 v[136:137], v[24:25], s[80:81] op_sel_hi:[1,0]
	v_pk_mul_f32 v[138:139], v[26:27], s[80:81] op_sel_hi:[1,0]
	v_exp_f32_e32 v132, v132
	v_exp_f32_e32 v133, v133
	v_exp_f32_e32 v134, v134
	v_exp_f32_e32 v135, v135
	v_exp_f32_e32 v136, v136
	v_exp_f32_e32 v137, v137
	v_exp_f32_e32 v138, v138
	v_exp_f32_e32 v139, v139
	v_pk_add_f32 v[132:133], v[132:133], 1.0 op_sel_hi:[1,0]
	v_pk_add_f32 v[134:135], v[134:135], 1.0 op_sel_hi:[1,0]
	v_pk_add_f32 v[136:137], v[136:137], 1.0 op_sel_hi:[1,0]
	v_pk_add_f32 v[138:139], v[138:139], 1.0 op_sel_hi:[1,0]
	v_rcp_f32_e32 v132, v132
	v_rcp_f32_e32 v133, v133
	v_rcp_f32_e32 v134, v134
	v_rcp_f32_e32 v135, v135
	v_rcp_f32_e32 v136, v136
	v_rcp_f32_e32 v137, v137
	v_rcp_f32_e32 v138, v138
	v_rcp_f32_e32 v139, v139
	v_pk_mul_f32 v[32:33], v[32:33], v[132:133]
	v_pk_mul_f32 v[34:35], v[34:35], v[134:135]
	v_pk_mul_f32 v[24:25], v[24:25], v[136:137]
	v_pk_mul_f32 v[26:27], v[26:27], v[138:139]
	v_cvt_pk_bf16_f32 v32, v32, v33
	v_cvt_pk_bf16_f32 v33, v34, v35
	v_cvt_pk_bf16_f32 v34, v24, v25
	v_cvt_pk_bf16_f32 v35, v26, v27
	global_store_dwordx4 v148, v[32:35], s[50:51] sc1
	v_pk_mul_f32 v[132:133], v[16:17], s[80:81] op_sel_hi:[1,0]
	v_pk_mul_f32 v[134:135], v[18:19], s[80:81] op_sel_hi:[1,0]
	v_pk_mul_f32 v[136:137], v[8:9], s[80:81] op_sel_hi:[1,0]
	v_pk_mul_f32 v[138:139], v[10:11], s[80:81] op_sel_hi:[1,0]
	v_exp_f32_e32 v132, v132
	v_exp_f32_e32 v133, v133
	v_exp_f32_e32 v134, v134
	v_exp_f32_e32 v135, v135
	v_exp_f32_e32 v136, v136
	v_exp_f32_e32 v137, v137
	v_exp_f32_e32 v138, v138
	v_exp_f32_e32 v139, v139
	v_pk_add_f32 v[132:133], v[132:133], 1.0 op_sel_hi:[1,0]
	v_pk_add_f32 v[134:135], v[134:135], 1.0 op_sel_hi:[1,0]
	v_pk_add_f32 v[136:137], v[136:137], 1.0 op_sel_hi:[1,0]
	v_pk_add_f32 v[138:139], v[138:139], 1.0 op_sel_hi:[1,0]
	v_rcp_f32_e32 v132, v132
	v_rcp_f32_e32 v133, v133
	v_rcp_f32_e32 v134, v134
	v_rcp_f32_e32 v135, v135
	v_rcp_f32_e32 v136, v136
	v_rcp_f32_e32 v137, v137
	v_rcp_f32_e32 v138, v138
	v_rcp_f32_e32 v139, v139
	v_pk_mul_f32 v[16:17], v[16:17], v[132:133]
	v_pk_mul_f32 v[18:19], v[18:19], v[134:135]
	v_pk_mul_f32 v[8:9], v[8:9], v[136:137]
	v_pk_mul_f32 v[10:11], v[10:11], v[138:139]
	v_cvt_pk_bf16_f32 v16, v16, v17
	v_cvt_pk_bf16_f32 v17, v18, v19
	v_cvt_pk_bf16_f32 v18, v8, v9
	v_cvt_pk_bf16_f32 v19, v10, v11
	global_store_dwordx4 v148, v[16:19], s[50:51] offset:256 sc1
	v_add_u32_e32 v148, s81, v148
	v_pk_mul_f32 v[132:133], v[28:29], s[80:81] op_sel_hi:[1,0]
	v_pk_mul_f32 v[134:135], v[30:31], s[80:81] op_sel_hi:[1,0]
	v_pk_mul_f32 v[136:137], v[20:21], s[80:81] op_sel_hi:[1,0]
	v_pk_mul_f32 v[138:139], v[22:23], s[80:81] op_sel_hi:[1,0]
	v_exp_f32_e32 v132, v132
	v_exp_f32_e32 v133, v133
	v_exp_f32_e32 v134, v134
	v_exp_f32_e32 v135, v135
	v_exp_f32_e32 v136, v136
	v_exp_f32_e32 v137, v137
	v_exp_f32_e32 v138, v138
	v_exp_f32_e32 v139, v139
	v_pk_add_f32 v[132:133], v[132:133], 1.0 op_sel_hi:[1,0]
	v_pk_add_f32 v[134:135], v[134:135], 1.0 op_sel_hi:[1,0]
	v_pk_add_f32 v[136:137], v[136:137], 1.0 op_sel_hi:[1,0]
	v_pk_add_f32 v[138:139], v[138:139], 1.0 op_sel_hi:[1,0]
	v_rcp_f32_e32 v132, v132
	v_rcp_f32_e32 v133, v133
	v_rcp_f32_e32 v134, v134
	v_rcp_f32_e32 v135, v135
	v_rcp_f32_e32 v136, v136
	v_rcp_f32_e32 v137, v137
	v_rcp_f32_e32 v138, v138
	v_rcp_f32_e32 v139, v139
	v_pk_mul_f32 v[28:29], v[28:29], v[132:133]
	v_pk_mul_f32 v[30:31], v[30:31], v[134:135]
	v_pk_mul_f32 v[20:21], v[20:21], v[136:137]
	v_pk_mul_f32 v[22:23], v[22:23], v[138:139]
	v_cvt_pk_bf16_f32 v28, v28, v29
	v_cvt_pk_bf16_f32 v29, v30, v31
	v_cvt_pk_bf16_f32 v30, v20, v21
	v_cvt_pk_bf16_f32 v31, v22, v23
	global_store_dwordx4 v148, v[28:31], s[50:51] sc1
	v_pk_mul_f32 v[132:133], v[12:13], s[80:81] op_sel_hi:[1,0]
	v_pk_mul_f32 v[134:135], v[14:15], s[80:81] op_sel_hi:[1,0]
	v_pk_mul_f32 v[136:137], v[4:5], s[80:81] op_sel_hi:[1,0]
	v_pk_mul_f32 v[138:139], v[6:7], s[80:81] op_sel_hi:[1,0]
	v_exp_f32_e32 v132, v132
	v_exp_f32_e32 v133, v133
	v_exp_f32_e32 v134, v134
	v_exp_f32_e32 v135, v135
	v_exp_f32_e32 v136, v136
	v_exp_f32_e32 v137, v137
	v_exp_f32_e32 v138, v138
	v_exp_f32_e32 v139, v139
	v_pk_add_f32 v[132:133], v[132:133], 1.0 op_sel_hi:[1,0]
	v_pk_add_f32 v[134:135], v[134:135], 1.0 op_sel_hi:[1,0]
	v_pk_add_f32 v[136:137], v[136:137], 1.0 op_sel_hi:[1,0]
	v_pk_add_f32 v[138:139], v[138:139], 1.0 op_sel_hi:[1,0]
	v_rcp_f32_e32 v132, v132
	v_rcp_f32_e32 v133, v133
	v_rcp_f32_e32 v134, v134
	v_rcp_f32_e32 v135, v135
	v_rcp_f32_e32 v136, v136
	v_rcp_f32_e32 v137, v137
	v_rcp_f32_e32 v138, v138
	v_rcp_f32_e32 v139, v139
	v_pk_mul_f32 v[12:13], v[12:13], v[132:133]
	v_pk_mul_f32 v[14:15], v[14:15], v[134:135]
	v_pk_mul_f32 v[4:5], v[4:5], v[136:137]
	v_pk_mul_f32 v[6:7], v[6:7], v[138:139]
	v_cvt_pk_bf16_f32 v12, v12, v13
	v_cvt_pk_bf16_f32 v13, v14, v15
	v_cvt_pk_bf16_f32 v14, v4, v5
	v_cvt_pk_bf16_f32 v15, v6, v7
	global_store_dwordx4 v148, v[12:15], s[50:51] offset:256 sc1
	s_branch .LBB0_326
.Lepi_gelu:
	s_lshl_b32 s30, s48, 8
	s_cmp_eq_u32 s57, 2
	s_cselect_b32 s47, 0x80, 0
	s_add_i32 s30, s30, s60
	s_add_i32 s30, s30, s47
	s_cmp_lg_u32 s57, 0
	s_cselect_b32 s49, 1, 0
	v_readlane_b32 s50, v240, 9
	v_readlane_b32 s51, v240, 10
	s_movk_i32 s82, 0x1400
	s_lshl_b32 s83, s71, 9
	s_movk_i32 s81, 0xc00
	s_cmp_eq_u32 s73, 7
	s_cselect_b32 s81, 0x1000, s81
	s_add_i32 s83, s83, s81
	v_add_u32_e32 v133, s30, v232
	v_lshl_add_u32 v134, v234, 1, s83
	v_mad_u32_u24 v148, v133, s82, v134
	s_lshl_b32 s81, s82, 4
	s_lshl_b32 s30, s71, 2
	s_add_i32 s30, s30, s16
	s_lshl_b32 s30, s30, 3
	v_lshl_add_u32 v149, v133, 6, s30
	v_xor_b32_e32 v150, 16, v230
	v_xor_b32_e32 v151, 32, v230
	v_lshlrev_b32_e32 v150, 2, v150
	v_lshlrev_b32_e32 v151, 2, v151
	s_mov_b32 s80, 0xbf38aa3b
	s_mov_b32 s82, 0xbe11a98e
	s_mov_b32 s84, 0x3e6d3388
	s_mov_b32 s86, 0x3f07dc22
	s_mov_b32 s88, 0x3f35f0e3
	s_mov_b32 s48, 0x3e027906
	v_mov_b32_e32 v0, 0xbf3a00e3
	s_cmp_eq_u32 s73, 7
	s_cbranch_scc0 .Lepi_gelu6
	v_and_b32_e32 v132, 0x7fffffff, v128
	v_and_b32_e32 v133, 0x7fffffff, v129
	v_and_b32_e32 v134, 0x7fffffff, v130
	v_and_b32_e32 v135, 0x7fffffff, v131
	v_pk_mul_f32 v[144:145], v[128:129], v[128:129]
	v_pk_mul_f32 v[146:147], v[130:131], v[130:131]
	v_pk_fma_f32 v[136:137], v[132:133], s[84:85], 1.0 op_sel_hi:[1,0,0]
	v_pk_fma_f32 v[138:139], v[134:135], s[84:85], 1.0 op_sel_hi:[1,0,0]
	v_pk_mul_f32 v[144:145], v[144:145], s[80:81] op_sel_hi:[1,0]
	v_pk_mul_f32 v[146:147], v[146:147], s[80:81] op_sel_hi:[1,0]
	v_rcp_f32_e32 v136, v136
	v_rcp_f32_e32 v137, v137
	v_rcp_f32_e32 v138, v138
	v_rcp_f32_e32 v139, v139
	v_exp_f32_e32 v144, v144
	v_exp_f32_e32 v145, v145
	v_exp_f32_e32 v146, v146
	v_exp_f32_e32 v147, v147
	v_pk_fma_f32 v[140:141], v[136:137], s[86:87], v[0:1] op_sel_hi:[1,0,0]
	v_pk_fma_f32 v[142:143], v[138:139], s[86:87], v[0:1] op_sel_hi:[1,0,0]
	v_pk_fma_f32 v[140:141], v[136:137], v[140:141], s[88:89] op_sel_hi:[1,1,0]
	v_pk_fma_f32 v[142:143], v[138:139], v[142:143], s[88:89] op_sel_hi:[1,1,0]
	v_pk_fma_f32 v[140:141], v[136:137], v[140:141], s[82:83] op_sel_hi:[1,1,0]
	v_pk_fma_f32 v[142:143], v[138:139], v[142:143], s[82:83] op_sel_hi:[1,1,0]
	v_pk_fma_f32 v[140:141], v[136:137], v[140:141], s[48:49] op_sel_hi:[1,1,0]
	v_pk_fma_f32 v[142:143], v[138:139], v[142:143], s[48:49] op_sel_hi:[1,1,0]
	v_pk_mul_f32 v[140:141], v[136:137], v[140:141]
	v_pk_mul_f32 v[142:143], v[138:139], v[142:143]
	v_pk_mul_f32 v[140:141], v[140:141], v[144:145]
	v_pk_mul_f32 v[142:143], v[142:143], v[146:147]
	v_max_f32_e32 v128, 0, v128
	v_max_f32_e32 v129, 0, v129
	v_max_f32_e32 v130, 0, v130
	v_max_f32_e32 v131, 0, v131
	v_pk_fma_f32 v[128:129], v[132:133], v[140:141], v[128:129] neg_lo:[1,0,0] neg_hi:[1,0,0]
	v_pk_fma_f32 v[130:131], v[134:135], v[142:143], v[130:131] neg_lo:[1,0,0] neg_hi:[1,0,0]
	v_pk_add_f32 v[2:3], v[128:129], v[130:131]
	v_pk_mul_f32 v[152:153], v[128:129], v[128:129]
	v_pk_fma_f32 v[152:153], v[130:131], v[130:131], v[152:153]
	v_and_b32_e32 v132, 0x7fffffff, v120
	v_and_b32_e32 v133, 0x7fffffff, v121
	v_and_b32_e32 v134, 0x7fffffff, v122
	v_and_b32_e32 v135, 0x7fffffff, v123
	v_pk_mul_f32 v[144:145], v[120:121], v[120:121]
	v_pk_mul_f32 v[146:147], v[122:123], v[122:123]
	v_pk_fma_f32 v[136:137], v[132:133], s[84:85], 1.0 op_sel_hi:[1,0,0]
	v_pk_fma_f32 v[138:139], v[134:135], s[84:85], 1.0 op_sel_hi:[1,0,0]
	v_pk_mul_f32 v[144:145], v[144:145], s[80:81] op_sel_hi:[1,0]
	v_pk_mul_f32 v[146:147], v[146:147], s[80:81] op_sel_hi:[1,0]
	v_rcp_f32_e32 v136, v136
	v_rcp_f32_e32 v137, v137
	v_rcp_f32_e32 v138, v138
	v_rcp_f32_e32 v139, v139
	v_exp_f32_e32 v144, v144
	v_exp_f32_e32 v145, v145
	v_exp_f32_e32 v146, v146
	v_exp_f32_e32 v147, v147
	v_pk_fma_f32 v[140:141], v[136:137], s[86:87], v[0:1] op_sel_hi:[1,0,0]
	v_pk_fma_f32 v[142:143], v[138:139], s[86:87], v[0:1] op_sel_hi:[1,0,0]
	v_pk_fma_f32 v[140:141], v[136:137], v[140:141], s[88:89] op_sel_hi:[1,1,0]
	v_pk_fma_f32 v[142:143], v[138:139], v[142:143], s[88:89] op_sel_hi:[1,1,0]
	v_pk_fma_f32 v[140:141], v[136:137], v[140:141], s[82:83] op_sel_hi:[1,1,0]
	v_pk_fma_f32 v[142:143], v[138:139], v[142:143], s[82:83] op_sel_hi:[1,1,0]
	v_pk_fma_f32 v[140:141], v[136:137], v[140:141], s[48:49] op_sel_hi:[1,1,0]
	v_pk_fma_f32 v[142:143], v[138:139], v[142:143], s[48:49] op_sel_hi:[1,1,0]
	v_pk_mul_f32 v[140:141], v[136:137], v[140:141]
	v_pk_mul_f32 v[142:143], v[138:139], v[142:143]
	v_pk_mul_f32 v[140:141], v[140:141], v[144:145]
	v_pk_mul_f32 v[142:143], v[142:143], v[146:147]
	v_max_f32_e32 v120, 0, v120
	v_max_f32_e32 v121, 0, v121
	v_max_f32_e32 v122, 0, v122
	v_max_f32_e32 v123, 0, v123
	v_pk_fma_f32 v[120:121], v[132:133], v[140:141], v[120:121] neg_lo:[1,0,0] neg_hi:[1,0,0]
	v_pk_fma_f32 v[122:123], v[134:135], v[142:143], v[122:123] neg_lo:[1,0,0] neg_hi:[1,0,0]
	v_pk_add_f32 v[2:3], v[2:3], v[120:121]
	v_pk_fma_f32 v[152:153], v[120:121], v[120:121], v[152:153]
	v_pk_add_f32 v[2:3], v[2:3], v[122:123]
	v_pk_fma_f32 v[152:153], v[122:123], v[122:123], v[152:153]
	v_cvt_pk_bf16_f32 v128, v128, v129
	v_cvt_pk_bf16_f32 v129, v130, v131
	v_cvt_pk_bf16_f32 v130, v120, v121
	v_cvt_pk_bf16_f32 v131, v122, v123
	global_store_dwordx4 v148, v[128:131], s[50:51] sc1
	v_and_b32_e32 v132, 0x7fffffff, v112
	v_and_b32_e32 v133, 0x7fffffff, v113
	v_and_b32_e32 v134, 0x7fffffff, v114
	v_and_b32_e32 v135, 0x7fffffff, v115
	v_pk_mul_f32 v[144:145], v[112:113], v[112:113]
	v_pk_mul_f32 v[146:147], v[114:115], v[114:115]
	v_pk_fma_f32 v[136:137], v[132:133], s[84:85], 1.0 op_sel_hi:[1,0,0]
	v_pk_fma_f32 v[138:139], v[134:135], s[84:85], 1.0 op_sel_hi:[1,0,0]
	v_pk_mul_f32 v[144:145], v[144:145], s[80:81] op_sel_hi:[1,0]
	v_pk_mul_f32 v[146:147], v[146:147], s[80:81] op_sel_hi:[1,0]
	v_rcp_f32_e32 v136, v136
	v_rcp_f32_e32 v137, v137
	v_rcp_f32_e32 v138, v138
	v_rcp_f32_e32 v139, v139
	v_exp_f32_e32 v144, v144
	v_exp_f32_e32 v145, v145
	v_exp_f32_e32 v146, v146
	v_exp_f32_e32 v147, v147
	v_pk_fma_f32 v[140:141], v[136:137], s[86:87], v[0:1] op_sel_hi:[1,0,0]
	v_pk_fma_f32 v[142:143], v[138:139], s[86:87], v[0:1] op_sel_hi:[1,0,0]
	v_pk_fma_f32 v[140:141], v[136:137], v[140:141], s[88:89] op_sel_hi:[1,1,0]
	v_pk_fma_f32 v[142:143], v[138:139], v[142:143], s[88:89] op_sel_hi:[1,1,0]
	v_pk_fma_f32 v[140:141], v[136:137], v[140:141], s[82:83] op_sel_hi:[1,1,0]
	v_pk_fma_f32 v[142:143], v[138:139], v[142:143], s[82:83] op_sel_hi:[1,1,0]
	v_pk_fma_f32 v[140:141], v[136:137], v[140:141], s[48:49] op_sel_hi:[1,1,0]
	v_pk_fma_f32 v[142:143], v[138:139], v[142:143], s[48:49] op_sel_hi:[1,1,0]
	v_pk_mul_f32 v[140:141], v[136:137], v[140:141]
	v_pk_mul_f32 v[142:143], v[138:139], v[142:143]
	v_pk_mul_f32 v[140:141], v[140:141], v[144:145]
	v_pk_mul_f32 v[142:143], v[142:143], v[146:147]
	v_max_f32_e32 v112, 0, v112
	v_max_f32_e32 v113, 0, v113
	v_max_f32_e32 v114, 0, v114
	v_max_f32_e32 v115, 0, v115
	v_pk_fma_f32 v[112:113], v[132:133], v[140:141], v[112:113] neg_lo:[1,0,0] neg_hi:[1,0,0]
	v_pk_fma_f32 v[114:115], v[134:135], v[142:143], v[114:115] neg_lo:[1,0,0] neg_hi:[1,0,0]
	v_pk_add_f32 v[2:3], v[2:3], v[112:113]
	v_pk_fma_f32 v[152:153], v[112:113], v[112:113], v[152:153]
	v_pk_add_f32 v[2:3], v[2:3], v[114:115]
	v_pk_fma_f32 v[152:153], v[114:115], v[114:115], v[152:153]
	v_and_b32_e32 v132, 0x7fffffff, v104
	v_and_b32_e32 v133, 0x7fffffff, v105
	v_and_b32_e32 v134, 0x7fffffff, v106
	v_and_b32_e32 v135, 0x7fffffff, v107
	v_pk_mul_f32 v[144:145], v[104:105], v[104:105]
	v_pk_mul_f32 v[146:147], v[106:107], v[106:107]
	v_pk_fma_f32 v[136:137], v[132:133], s[84:85], 1.0 op_sel_hi:[1,0,0]
	v_pk_fma_f32 v[138:139], v[134:135], s[84:85], 1.0 op_sel_hi:[1,0,0]
	v_pk_mul_f32 v[144:145], v[144:145], s[80:81] op_sel_hi:[1,0]
	v_pk_mul_f32 v[146:147], v[146:147], s[80:81] op_sel_hi:[1,0]
	v_rcp_f32_e32 v136, v136
	v_rcp_f32_e32 v137, v137
	v_rcp_f32_e32 v138, v138
	v_rcp_f32_e32 v139, v139
	v_exp_f32_e32 v144, v144
	v_exp_f32_e32 v145, v145
	v_exp_f32_e32 v146, v146
	v_exp_f32_e32 v147, v147
	v_pk_fma_f32 v[140:141], v[136:137], s[86:87], v[0:1] op_sel_hi:[1,0,0]
	v_pk_fma_f32 v[142:143], v[138:139], s[86:87], v[0:1] op_sel_hi:[1,0,0]
	v_pk_fma_f32 v[140:141], v[136:137], v[140:141], s[88:89] op_sel_hi:[1,1,0]
	v_pk_fma_f32 v[142:143], v[138:139], v[142:143], s[88:89] op_sel_hi:[1,1,0]
	v_pk_fma_f32 v[140:141], v[136:137], v[140:141], s[82:83] op_sel_hi:[1,1,0]
	v_pk_fma_f32 v[142:143], v[138:139], v[142:143], s[82:83] op_sel_hi:[1,1,0]
	v_pk_fma_f32 v[140:141], v[136:137], v[140:141], s[48:49] op_sel_hi:[1,1,0]
	v_pk_fma_f32 v[142:143], v[138:139], v[142:143], s[48:49] op_sel_hi:[1,1,0]
	v_pk_mul_f32 v[140:141], v[136:137], v[140:141]
	v_pk_mul_f32 v[142:143], v[138:139], v[142:143]
	v_pk_mul_f32 v[140:141], v[140:141], v[144:145]
	v_pk_mul_f32 v[142:143], v[142:143], v[146:147]
	v_max_f32_e32 v104, 0, v104
	v_max_f32_e32 v105, 0, v105
	v_max_f32_e32 v106, 0, v106
	v_max_f32_e32 v107, 0, v107
	v_pk_fma_f32 v[104:105], v[132:133], v[140:141], v[104:105] neg_lo:[1,0,0] neg_hi:[1,0,0]
	v_pk_fma_f32 v[106:107], v[134:135], v[142:143], v[106:107] neg_lo:[1,0,0] neg_hi:[1,0,0]
	v_pk_add_f32 v[2:3], v[2:3], v[104:105]
	v_pk_fma_f32 v[152:153], v[104:105], v[104:105], v[152:153]
	v_pk_add_f32 v[2:3], v[2:3], v[106:107]
	v_pk_fma_f32 v[152:153], v[106:107], v[106:107], v[152:153]
	v_cvt_pk_bf16_f32 v112, v112, v113
	v_cvt_pk_bf16_f32 v113, v114, v115
	v_cvt_pk_bf16_f32 v114, v104, v105
	v_cvt_pk_bf16_f32 v115, v106, v107
	global_store_dwordx4 v148, v[112:115], s[50:51] offset:256 sc1
	v_add_f32_e32 v2, v2, v3
	v_add_f32_e32 v3, v152, v153
	ds_bpermute_b32 v132, v150, v2
	ds_bpermute_b32 v133, v150, v3
	s_waitcnt lgkmcnt(0)
	v_pk_add_f32 v[2:3], v[2:3], v[132:133]
	ds_bpermute_b32 v132, v151, v2
	ds_bpermute_b32 v133, v151, v3
	s_waitcnt lgkmcnt(0)
	v_pk_add_f32 v[2:3], v[2:3], v[132:133]
	s_and_saveexec_b64 s[46:47], s[38:39]
	global_store_dwordx2 v149, v[2:3], s[66:67]
	s_mov_b64 exec, s[46:47]
	v_add_u32_e32 v148, s81, v148
	v_add_u32_e32 v149, 0x400, v149
	v_and_b32_e32 v132, 0x7fffffff, v124
	v_and_b32_e32 v133, 0x7fffffff, v125
	v_and_b32_e32 v134, 0x7fffffff, v126
	v_and_b32_e32 v135, 0x7fffffff, v127
	v_pk_mul_f32 v[144:145], v[124:125], v[124:125]
	v_pk_mul_f32 v[146:147], v[126:127], v[126:127]
	v_pk_fma_f32 v[136:137], v[132:133], s[84:85], 1.0 op_sel_hi:[1,0,0]
	v_pk_fma_f32 v[138:139], v[134:135], s[84:85], 1.0 op_sel_hi:[1,0,0]
	v_pk_mul_f32 v[144:145], v[144:145], s[80:81] op_sel_hi:[1,0]
	v_pk_mul_f32 v[146:147], v[146:147], s[80:81] op_sel_hi:[1,0]
	v_rcp_f32_e32 v136, v136
	v_rcp_f32_e32 v137, v137
	v_rcp_f32_e32 v138, v138
	v_rcp_f32_e32 v139, v139
	v_exp_f32_e32 v144, v144
	v_exp_f32_e32 v145, v145
	v_exp_f32_e32 v146, v146
	v_exp_f32_e32 v147, v147
	v_pk_fma_f32 v[140:141], v[136:137], s[86:87], v[0:1] op_sel_hi:[1,0,0]
	v_pk_fma_f32 v[142:143], v[138:139], s[86:87], v[0:1] op_sel_hi:[1,0,0]
	v_pk_fma_f32 v[140:141], v[136:137], v[140:141], s[88:89] op_sel_hi:[1,1,0]
	v_pk_fma_f32 v[142:143], v[138:139], v[142:143], s[88:89] op_sel_hi:[1,1,0]
	v_pk_fma_f32 v[140:141], v[136:137], v[140:141], s[82:83] op_sel_hi:[1,1,0]
	v_pk_fma_f32 v[142:143], v[138:139], v[142:143], s[82:83] op_sel_hi:[1,1,0]
	v_pk_fma_f32 v[140:141], v[136:137], v[140:141], s[48:49] op_sel_hi:[1,1,0]
	v_pk_fma_f32 v[142:143], v[138:139], v[142:143], s[48:49] op_sel_hi:[1,1,0]
	v_pk_mul_f32 v[140:141], v[136:137], v[140:141]
	v_pk_mul_f32 v[142:143], v[138:139], v[142:143]
	v_pk_mul_f32 v[140:141], v[140:141], v[144:145]
	v_pk_mul_f32 v[142:143], v[142:143], v[146:147]
	v_max_f32_e32 v124, 0, v124
	v_max_f32_e32 v125, 0, v125
	v_max_f32_e32 v126, 0, v126
	v_max_f32_e32 v127, 0, v127
	v_pk_fma_f32 v[124:125], v[132:133], v[140:141], v[124:125] neg_lo:[1,0,0] neg_hi:[1,0,0]
	v_pk_fma_f32 v[126:127], v[134:135], v[142:143], v[126:127] neg_lo:[1,0,0] neg_hi:[1,0,0]
	v_pk_add_f32 v[2:3], v[124:125], v[126:127]
	v_pk_mul_f32 v[152:153], v[124:125], v[124:125]
	v_pk_fma_f32 v[152:153], v[126:127], v[126:127], v[152:153]
	v_and_b32_e32 v132, 0x7fffffff, v116
	v_and_b32_e32 v133, 0x7fffffff, v117
	v_and_b32_e32 v134, 0x7fffffff, v118
	v_and_b32_e32 v135, 0x7fffffff, v119
	v_pk_mul_f32 v[144:145], v[116:117], v[116:117]
	v_pk_mul_f32 v[146:147], v[118:119], v[118:119]
	v_pk_fma_f32 v[136:137], v[132:133], s[84:85], 1.0 op_sel_hi:[1,0,0]
	v_pk_fma_f32 v[138:139], v[134:135], s[84:85], 1.0 op_sel_hi:[1,0,0]
	v_pk_mul_f32 v[144:145], v[144:145], s[80:81] op_sel_hi:[1,0]
	v_pk_mul_f32 v[146:147], v[146:147], s[80:81] op_sel_hi:[1,0]
	v_rcp_f32_e32 v136, v136
	v_rcp_f32_e32 v137, v137
	v_rcp_f32_e32 v138, v138
	v_rcp_f32_e32 v139, v139
	v_exp_f32_e32 v144, v144
	v_exp_f32_e32 v145, v145
	v_exp_f32_e32 v146, v146
	v_exp_f32_e32 v147, v147
	v_pk_fma_f32 v[140:141], v[136:137], s[86:87], v[0:1] op_sel_hi:[1,0,0]
	v_pk_fma_f32 v[142:143], v[138:139], s[86:87], v[0:1] op_sel_hi:[1,0,0]
	v_pk_fma_f32 v[140:141], v[136:137], v[140:141], s[88:89] op_sel_hi:[1,1,0]
	v_pk_fma_f32 v[142:143], v[138:139], v[142:143], s[88:89] op_sel_hi:[1,1,0]
	v_pk_fma_f32 v[140:141], v[136:137], v[140:141], s[82:83] op_sel_hi:[1,1,0]
	v_pk_fma_f32 v[142:143], v[138:139], v[142:143], s[82:83] op_sel_hi:[1,1,0]
	v_pk_fma_f32 v[140:141], v[136:137], v[140:141], s[48:49] op_sel_hi:[1,1,0]
	v_pk_fma_f32 v[142:143], v[138:139], v[142:143], s[48:49] op_sel_hi:[1,1,0]
	v_pk_mul_f32 v[140:141], v[136:137], v[140:141]
	v_pk_mul_f32 v[142:143], v[138:139], v[142:143]
	v_pk_mul_f32 v[140:141], v[140:141], v[144:145]
	v_pk_mul_f32 v[142:143], v[142:143], v[146:147]
	v_max_f32_e32 v116, 0, v116
	v_max_f32_e32 v117, 0, v117
	v_max_f32_e32 v118, 0, v118
	v_max_f32_e32 v119, 0, v119
	v_pk_fma_f32 v[116:117], v[132:133], v[140:141], v[116:117] neg_lo:[1,0,0] neg_hi:[1,0,0]
	v_pk_fma_f32 v[118:119], v[134:135], v[142:143], v[118:119] neg_lo:[1,0,0] neg_hi:[1,0,0]
	v_pk_add_f32 v[2:3], v[2:3], v[116:117]
	v_pk_fma_f32 v[152:153], v[116:117], v[116:117], v[152:153]
	v_pk_add_f32 v[2:3], v[2:3], v[118:119]
	v_pk_fma_f32 v[152:153], v[118:119], v[118:119], v[152:153]
	v_cvt_pk_bf16_f32 v124, v124, v125
	v_cvt_pk_bf16_f32 v125, v126, v127
	v_cvt_pk_bf16_f32 v126, v116, v117
	v_cvt_pk_bf16_f32 v127, v118, v119
	global_store_dwordx4 v148, v[124:127], s[50:51] sc1
	v_and_b32_e32 v132, 0x7fffffff, v108
	v_and_b32_e32 v133, 0x7fffffff, v109
	v_and_b32_e32 v134, 0x7fffffff, v110
	v_and_b32_e32 v135, 0x7fffffff, v111
	v_pk_mul_f32 v[144:145], v[108:109], v[108:109]
	v_pk_mul_f32 v[146:147], v[110:111], v[110:111]
	v_pk_fma_f32 v[136:137], v[132:133], s[84:85], 1.0 op_sel_hi:[1,0,0]
	v_pk_fma_f32 v[138:139], v[134:135], s[84:85], 1.0 op_sel_hi:[1,0,0]
	v_pk_mul_f32 v[144:145], v[144:145], s[80:81] op_sel_hi:[1,0]
	v_pk_mul_f32 v[146:147], v[146:147], s[80:81] op_sel_hi:[1,0]
	v_rcp_f32_e32 v136, v136
	v_rcp_f32_e32 v137, v137
	v_rcp_f32_e32 v138, v138
	v_rcp_f32_e32 v139, v139
	v_exp_f32_e32 v144, v144
	v_exp_f32_e32 v145, v145
	v_exp_f32_e32 v146, v146
	v_exp_f32_e32 v147, v147
	v_pk_fma_f32 v[140:141], v[136:137], s[86:87], v[0:1] op_sel_hi:[1,0,0]
	v_pk_fma_f32 v[142:143], v[138:139], s[86:87], v[0:1] op_sel_hi:[1,0,0]
	v_pk_fma_f32 v[140:141], v[136:137], v[140:141], s[88:89] op_sel_hi:[1,1,0]
	v_pk_fma_f32 v[142:143], v[138:139], v[142:143], s[88:89] op_sel_hi:[1,1,0]
	v_pk_fma_f32 v[140:141], v[136:137], v[140:141], s[82:83] op_sel_hi:[1,1,0]
	v_pk_fma_f32 v[142:143], v[138:139], v[142:143], s[82:83] op_sel_hi:[1,1,0]
	v_pk_fma_f32 v[140:141], v[136:137], v[140:141], s[48:49] op_sel_hi:[1,1,0]
	v_pk_fma_f32 v[142:143], v[138:139], v[142:143], s[48:49] op_sel_hi:[1,1,0]
	v_pk_mul_f32 v[140:141], v[136:137], v[140:141]
	v_pk_mul_f32 v[142:143], v[138:139], v[142:143]
	v_pk_mul_f32 v[140:141], v[140:141], v[144:145]
	v_pk_mul_f32 v[142:143], v[142:143], v[146:147]
	v_max_f32_e32 v108, 0, v108
	v_max_f32_e32 v109, 0, v109
	v_max_f32_e32 v110, 0, v110
	v_max_f32_e32 v111, 0, v111
	v_pk_fma_f32 v[108:109], v[132:133], v[140:141], v[108:109] neg_lo:[1,0,0] neg_hi:[1,0,0]
	v_pk_fma_f32 v[110:111], v[134:135], v[142:143], v[110:111] neg_lo:[1,0,0] neg_hi:[1,0,0]
	v_pk_add_f32 v[2:3], v[2:3], v[108:109]
	v_pk_fma_f32 v[152:153], v[108:109], v[108:109], v[152:153]
	v_pk_add_f32 v[2:3], v[2:3], v[110:111]
	v_pk_fma_f32 v[152:153], v[110:111], v[110:111], v[152:153]
	v_and_b32_e32 v132, 0x7fffffff, v100
	v_and_b32_e32 v133, 0x7fffffff, v101
	v_and_b32_e32 v134, 0x7fffffff, v102
	v_and_b32_e32 v135, 0x7fffffff, v103
	v_pk_mul_f32 v[144:145], v[100:101], v[100:101]
	v_pk_mul_f32 v[146:147], v[102:103], v[102:103]
	v_pk_fma_f32 v[136:137], v[132:133], s[84:85], 1.0 op_sel_hi:[1,0,0]
	v_pk_fma_f32 v[138:139], v[134:135], s[84:85], 1.0 op_sel_hi:[1,0,0]
	v_pk_mul_f32 v[144:145], v[144:145], s[80:81] op_sel_hi:[1,0]
	v_pk_mul_f32 v[146:147], v[146:147], s[80:81] op_sel_hi:[1,0]
	v_rcp_f32_e32 v136, v136
	v_rcp_f32_e32 v137, v137
	v_rcp_f32_e32 v138, v138
	v_rcp_f32_e32 v139, v139
	v_exp_f32_e32 v144, v144
	v_exp_f32_e32 v145, v145
	v_exp_f32_e32 v146, v146
	v_exp_f32_e32 v147, v147
	v_pk_fma_f32 v[140:141], v[136:137], s[86:87], v[0:1] op_sel_hi:[1,0,0]
	v_pk_fma_f32 v[142:143], v[138:139], s[86:87], v[0:1] op_sel_hi:[1,0,0]
	v_pk_fma_f32 v[140:141], v[136:137], v[140:141], s[88:89] op_sel_hi:[1,1,0]
	v_pk_fma_f32 v[142:143], v[138:139], v[142:143], s[88:89] op_sel_hi:[1,1,0]
	v_pk_fma_f32 v[140:141], v[136:137], v[140:141], s[82:83] op_sel_hi:[1,1,0]
	v_pk_fma_f32 v[142:143], v[138:139], v[142:143], s[82:83] op_sel_hi:[1,1,0]
	v_pk_fma_f32 v[140:141], v[136:137], v[140:141], s[48:49] op_sel_hi:[1,1,0]
	v_pk_fma_f32 v[142:143], v[138:139], v[142:143], s[48:49] op_sel_hi:[1,1,0]
	v_pk_mul_f32 v[140:141], v[136:137], v[140:141]
	v_pk_mul_f32 v[142:143], v[138:139], v[142:143]
	v_pk_mul_f32 v[140:141], v[140:141], v[144:145]
	v_pk_mul_f32 v[142:143], v[142:143], v[146:147]
	v_max_f32_e32 v100, 0, v100
	v_max_f32_e32 v101, 0, v101
	v_max_f32_e32 v102, 0, v102
	v_max_f32_e32 v103, 0, v103
	v_pk_fma_f32 v[100:101], v[132:133], v[140:141], v[100:101] neg_lo:[1,0,0] neg_hi:[1,0,0]
	v_pk_fma_f32 v[102:103], v[134:135], v[142:143], v[102:103] neg_lo:[1,0,0] neg_hi:[1,0,0]
	v_pk_add_f32 v[2:3], v[2:3], v[100:101]
	v_pk_fma_f32 v[152:153], v[100:101], v[100:101], v[152:153]
	v_pk_add_f32 v[2:3], v[2:3], v[102:103]
	v_pk_fma_f32 v[152:153], v[102:103], v[102:103], v[152:153]
	v_cvt_pk_bf16_f32 v108, v108, v109
	v_cvt_pk_bf16_f32 v109, v110, v111
	v_cvt_pk_bf16_f32 v110, v100, v101
	v_cvt_pk_bf16_f32 v111, v102, v103
	global_store_dwordx4 v148, v[108:111], s[50:51] offset:256 sc1
	v_add_f32_e32 v2, v2, v3
	v_add_f32_e32 v3, v152, v153
	ds_bpermute_b32 v132, v150, v2
	ds_bpermute_b32 v133, v150, v3
	s_waitcnt lgkmcnt(0)
	v_pk_add_f32 v[2:3], v[2:3], v[132:133]
	ds_bpermute_b32 v132, v151, v2
	ds_bpermute_b32 v133, v151, v3
	s_waitcnt lgkmcnt(0)
	v_pk_add_f32 v[2:3], v[2:3], v[132:133]
	s_and_saveexec_b64 s[46:47], s[38:39]
	global_store_dwordx2 v149, v[2:3], s[66:67]
	s_mov_b64 exec, s[46:47]
	v_add_u32_e32 v148, s81, v148
	v_add_u32_e32 v149, 0x400, v149
	v_and_b32_e32 v132, 0x7fffffff, v96
	v_and_b32_e32 v133, 0x7fffffff, v97
	v_and_b32_e32 v134, 0x7fffffff, v98
	v_and_b32_e32 v135, 0x7fffffff, v99
	v_pk_mul_f32 v[144:145], v[96:97], v[96:97]
	v_pk_mul_f32 v[146:147], v[98:99], v[98:99]
	v_pk_fma_f32 v[136:137], v[132:133], s[84:85], 1.0 op_sel_hi:[1,0,0]
	v_pk_fma_f32 v[138:139], v[134:135], s[84:85], 1.0 op_sel_hi:[1,0,0]
	v_pk_mul_f32 v[144:145], v[144:145], s[80:81] op_sel_hi:[1,0]
	v_pk_mul_f32 v[146:147], v[146:147], s[80:81] op_sel_hi:[1,0]
	v_rcp_f32_e32 v136, v136
	v_rcp_f32_e32 v137, v137
	v_rcp_f32_e32 v138, v138
	v_rcp_f32_e32 v139, v139
	v_exp_f32_e32 v144, v144
	v_exp_f32_e32 v145, v145
	v_exp_f32_e32 v146, v146
	v_exp_f32_e32 v147, v147
	v_pk_fma_f32 v[140:141], v[136:137], s[86:87], v[0:1] op_sel_hi:[1,0,0]
	v_pk_fma_f32 v[142:143], v[138:139], s[86:87], v[0:1] op_sel_hi:[1,0,0]
	v_pk_fma_f32 v[140:141], v[136:137], v[140:141], s[88:89] op_sel_hi:[1,1,0]
	v_pk_fma_f32 v[142:143], v[138:139], v[142:143], s[88:89] op_sel_hi:[1,1,0]
	v_pk_fma_f32 v[140:141], v[136:137], v[140:141], s[82:83] op_sel_hi:[1,1,0]
	v_pk_fma_f32 v[142:143], v[138:139], v[142:143], s[82:83] op_sel_hi:[1,1,0]
	v_pk_fma_f32 v[140:141], v[136:137], v[140:141], s[48:49] op_sel_hi:[1,1,0]
	v_pk_fma_f32 v[142:143], v[138:139], v[142:143], s[48:49] op_sel_hi:[1,1,0]
	v_pk_mul_f32 v[140:141], v[136:137], v[140:141]
	v_pk_mul_f32 v[142:143], v[138:139], v[142:143]
	v_pk_mul_f32 v[140:141], v[140:141], v[144:145]
	v_pk_mul_f32 v[142:143], v[142:143], v[146:147]
	v_max_f32_e32 v96, 0, v96
	v_max_f32_e32 v97, 0, v97
	v_max_f32_e32 v98, 0, v98
	v_max_f32_e32 v99, 0, v99
	v_pk_fma_f32 v[96:97], v[132:133], v[140:141], v[96:97] neg_lo:[1,0,0] neg_hi:[1,0,0]
	v_pk_fma_f32 v[98:99], v[134:135], v[142:143], v[98:99] neg_lo:[1,0,0] neg_hi:[1,0,0]
	v_pk_add_f32 v[2:3], v[96:97], v[98:99]
	v_pk_mul_f32 v[152:153], v[96:97], v[96:97]
	v_pk_fma_f32 v[152:153], v[98:99], v[98:99], v[152:153]
	v_and_b32_e32 v132, 0x7fffffff, v88
	v_and_b32_e32 v133, 0x7fffffff, v89
	v_and_b32_e32 v134, 0x7fffffff, v90
	v_and_b32_e32 v135, 0x7fffffff, v91
	v_pk_mul_f32 v[144:145], v[88:89], v[88:89]
	v_pk_mul_f32 v[146:147], v[90:91], v[90:91]
	v_pk_fma_f32 v[136:137], v[132:133], s[84:85], 1.0 op_sel_hi:[1,0,0]
	v_pk_fma_f32 v[138:139], v[134:135], s[84:85], 1.0 op_sel_hi:[1,0,0]
	v_pk_mul_f32 v[144:145], v[144:145], s[80:81] op_sel_hi:[1,0]
	v_pk_mul_f32 v[146:147], v[146:147], s[80:81] op_sel_hi:[1,0]
	v_rcp_f32_e32 v136, v136
	v_rcp_f32_e32 v137, v137
	v_rcp_f32_e32 v138, v138
	v_rcp_f32_e32 v139, v139
	v_exp_f32_e32 v144, v144
	v_exp_f32_e32 v145, v145
	v_exp_f32_e32 v146, v146
	v_exp_f32_e32 v147, v147
	v_pk_fma_f32 v[140:141], v[136:137], s[86:87], v[0:1] op_sel_hi:[1,0,0]
	v_pk_fma_f32 v[142:143], v[138:139], s[86:87], v[0:1] op_sel_hi:[1,0,0]
	v_pk_fma_f32 v[140:141], v[136:137], v[140:141], s[88:89] op_sel_hi:[1,1,0]
	v_pk_fma_f32 v[142:143], v[138:139], v[142:143], s[88:89] op_sel_hi:[1,1,0]
	v_pk_fma_f32 v[140:141], v[136:137], v[140:141], s[82:83] op_sel_hi:[1,1,0]
	v_pk_fma_f32 v[142:143], v[138:139], v[142:143], s[82:83] op_sel_hi:[1,1,0]
	v_pk_fma_f32 v[140:141], v[136:137], v[140:141], s[48:49] op_sel_hi:[1,1,0]
	v_pk_fma_f32 v[142:143], v[138:139], v[142:143], s[48:49] op_sel_hi:[1,1,0]
	v_pk_mul_f32 v[140:141], v[136:137], v[140:141]
	v_pk_mul_f32 v[142:143], v[138:139], v[142:143]
	v_pk_mul_f32 v[140:141], v[140:141], v[144:145]
	v_pk_mul_f32 v[142:143], v[142:143], v[146:147]
	v_max_f32_e32 v88, 0, v88
	v_max_f32_e32 v89, 0, v89
	v_max_f32_e32 v90, 0, v90
	v_max_f32_e32 v91, 0, v91
	v_pk_fma_f32 v[88:89], v[132:133], v[140:141], v[88:89] neg_lo:[1,0,0] neg_hi:[1,0,0]
	v_pk_fma_f32 v[90:91], v[134:135], v[142:143], v[90:91] neg_lo:[1,0,0] neg_hi:[1,0,0]
	v_pk_add_f32 v[2:3], v[2:3], v[88:89]
	v_pk_fma_f32 v[152:153], v[88:89], v[88:89], v[152:153]
	v_pk_add_f32 v[2:3], v[2:3], v[90:91]
	v_pk_fma_f32 v[152:153], v[90:91], v[90:91], v[152:153]
	v_cvt_pk_bf16_f32 v96, v96, v97
	v_cvt_pk_bf16_f32 v97, v98, v99
	v_cvt_pk_bf16_f32 v98, v88, v89
	v_cvt_pk_bf16_f32 v99, v90, v91
	global_store_dwordx4 v148, v[96:99], s[50:51] sc1
	v_and_b32_e32 v132, 0x7fffffff, v80
	v_and_b32_e32 v133, 0x7fffffff, v81
	v_and_b32_e32 v134, 0x7fffffff, v82
	v_and_b32_e32 v135, 0x7fffffff, v83
	v_pk_mul_f32 v[144:145], v[80:81], v[80:81]
	v_pk_mul_f32 v[146:147], v[82:83], v[82:83]
	v_pk_fma_f32 v[136:137], v[132:133], s[84:85], 1.0 op_sel_hi:[1,0,0]
	v_pk_fma_f32 v[138:139], v[134:135], s[84:85], 1.0 op_sel_hi:[1,0,0]
	v_pk_mul_f32 v[144:145], v[144:145], s[80:81] op_sel_hi:[1,0]
	v_pk_mul_f32 v[146:147], v[146:147], s[80:81] op_sel_hi:[1,0]
	v_rcp_f32_e32 v136, v136
	v_rcp_f32_e32 v137, v137
	v_rcp_f32_e32 v138, v138
	v_rcp_f32_e32 v139, v139
	v_exp_f32_e32 v144, v144
	v_exp_f32_e32 v145, v145
	v_exp_f32_e32 v146, v146
	v_exp_f32_e32 v147, v147
	v_pk_fma_f32 v[140:141], v[136:137], s[86:87], v[0:1] op_sel_hi:[1,0,0]
	v_pk_fma_f32 v[142:143], v[138:139], s[86:87], v[0:1] op_sel_hi:[1,0,0]
	v_pk_fma_f32 v[140:141], v[136:137], v[140:141], s[88:89] op_sel_hi:[1,1,0]
	v_pk_fma_f32 v[142:143], v[138:139], v[142:143], s[88:89] op_sel_hi:[1,1,0]
	v_pk_fma_f32 v[140:141], v[136:137], v[140:141], s[82:83] op_sel_hi:[1,1,0]
	v_pk_fma_f32 v[142:143], v[138:139], v[142:143], s[82:83] op_sel_hi:[1,1,0]
	v_pk_fma_f32 v[140:141], v[136:137], v[140:141], s[48:49] op_sel_hi:[1,1,0]
	v_pk_fma_f32 v[142:143], v[138:139], v[142:143], s[48:49] op_sel_hi:[1,1,0]
	v_pk_mul_f32 v[140:141], v[136:137], v[140:141]
	v_pk_mul_f32 v[142:143], v[138:139], v[142:143]
	v_pk_mul_f32 v[140:141], v[140:141], v[144:145]
	v_pk_mul_f32 v[142:143], v[142:143], v[146:147]
	v_max_f32_e32 v80, 0, v80
	v_max_f32_e32 v81, 0, v81
	v_max_f32_e32 v82, 0, v82
	v_max_f32_e32 v83, 0, v83
	v_pk_fma_f32 v[80:81], v[132:133], v[140:141], v[80:81] neg_lo:[1,0,0] neg_hi:[1,0,0]
	v_pk_fma_f32 v[82:83], v[134:135], v[142:143], v[82:83] neg_lo:[1,0,0] neg_hi:[1,0,0]
	v_pk_add_f32 v[2:3], v[2:3], v[80:81]
	v_pk_fma_f32 v[152:153], v[80:81], v[80:81], v[152:153]
	v_pk_add_f32 v[2:3], v[2:3], v[82:83]
	v_pk_fma_f32 v[152:153], v[82:83], v[82:83], v[152:153]
	v_and_b32_e32 v132, 0x7fffffff, v72
	v_and_b32_e32 v133, 0x7fffffff, v73
	v_and_b32_e32 v134, 0x7fffffff, v74
	v_and_b32_e32 v135, 0x7fffffff, v75
	v_pk_mul_f32 v[144:145], v[72:73], v[72:73]
	v_pk_mul_f32 v[146:147], v[74:75], v[74:75]
	v_pk_fma_f32 v[136:137], v[132:133], s[84:85], 1.0 op_sel_hi:[1,0,0]
	v_pk_fma_f32 v[138:139], v[134:135], s[84:85], 1.0 op_sel_hi:[1,0,0]
	v_pk_mul_f32 v[144:145], v[144:145], s[80:81] op_sel_hi:[1,0]
	v_pk_mul_f32 v[146:147], v[146:147], s[80:81] op_sel_hi:[1,0]
	v_rcp_f32_e32 v136, v136
	v_rcp_f32_e32 v137, v137
	v_rcp_f32_e32 v138, v138
	v_rcp_f32_e32 v139, v139
	v_exp_f32_e32 v144, v144
	v_exp_f32_e32 v145, v145
	v_exp_f32_e32 v146, v146
	v_exp_f32_e32 v147, v147
	v_pk_fma_f32 v[140:141], v[136:137], s[86:87], v[0:1] op_sel_hi:[1,0,0]
	v_pk_fma_f32 v[142:143], v[138:139], s[86:87], v[0:1] op_sel_hi:[1,0,0]
	v_pk_fma_f32 v[140:141], v[136:137], v[140:141], s[88:89] op_sel_hi:[1,1,0]
	v_pk_fma_f32 v[142:143], v[138:139], v[142:143], s[88:89] op_sel_hi:[1,1,0]
	v_pk_fma_f32 v[140:141], v[136:137], v[140:141], s[82:83] op_sel_hi:[1,1,0]
	v_pk_fma_f32 v[142:143], v[138:139], v[142:143], s[82:83] op_sel_hi:[1,1,0]
	v_pk_fma_f32 v[140:141], v[136:137], v[140:141], s[48:49] op_sel_hi:[1,1,0]
	v_pk_fma_f32 v[142:143], v[138:139], v[142:143], s[48:49] op_sel_hi:[1,1,0]
	v_pk_mul_f32 v[140:141], v[136:137], v[140:141]
	v_pk_mul_f32 v[142:143], v[138:139], v[142:143]
	v_pk_mul_f32 v[140:141], v[140:141], v[144:145]
	v_pk_mul_f32 v[142:143], v[142:143], v[146:147]
	v_max_f32_e32 v72, 0, v72
	v_max_f32_e32 v73, 0, v73
	v_max_f32_e32 v74, 0, v74
	v_max_f32_e32 v75, 0, v75
	v_pk_fma_f32 v[72:73], v[132:133], v[140:141], v[72:73] neg_lo:[1,0,0] neg_hi:[1,0,0]
	v_pk_fma_f32 v[74:75], v[134:135], v[142:143], v[74:75] neg_lo:[1,0,0] neg_hi:[1,0,0]
	v_pk_add_f32 v[2:3], v[2:3], v[72:73]
	v_pk_fma_f32 v[152:153], v[72:73], v[72:73], v[152:153]
	v_pk_add_f32 v[2:3], v[2:3], v[74:75]
	v_pk_fma_f32 v[152:153], v[74:75], v[74:75], v[152:153]
	v_cvt_pk_bf16_f32 v80, v80, v81
	v_cvt_pk_bf16_f32 v81, v82, v83
	v_cvt_pk_bf16_f32 v82, v72, v73
	v_cvt_pk_bf16_f32 v83, v74, v75
	global_store_dwordx4 v148, v[80:83], s[50:51] offset:256 sc1
	v_add_f32_e32 v2, v2, v3
	v_add_f32_e32 v3, v152, v153
	ds_bpermute_b32 v132, v150, v2
	ds_bpermute_b32 v133, v150, v3
	s_waitcnt lgkmcnt(0)
	v_pk_add_f32 v[2:3], v[2:3], v[132:133]
	ds_bpermute_b32 v132, v151, v2
	ds_bpermute_b32 v133, v151, v3
	s_waitcnt lgkmcnt(0)
	v_pk_add_f32 v[2:3], v[2:3], v[132:133]
	s_and_saveexec_b64 s[46:47], s[38:39]
	global_store_dwordx2 v149, v[2:3], s[66:67]
	s_mov_b64 exec, s[46:47]
	v_add_u32_e32 v148, s81, v148
	v_add_u32_e32 v149, 0x400, v149
	v_and_b32_e32 v132, 0x7fffffff, v92
	v_and_b32_e32 v133, 0x7fffffff, v93
	v_and_b32_e32 v134, 0x7fffffff, v94
	v_and_b32_e32 v135, 0x7fffffff, v95
	v_pk_mul_f32 v[144:145], v[92:93], v[92:93]
	v_pk_mul_f32 v[146:147], v[94:95], v[94:95]
	v_pk_fma_f32 v[136:137], v[132:133], s[84:85], 1.0 op_sel_hi:[1,0,0]
	v_pk_fma_f32 v[138:139], v[134:135], s[84:85], 1.0 op_sel_hi:[1,0,0]
	v_pk_mul_f32 v[144:145], v[144:145], s[80:81] op_sel_hi:[1,0]
	v_pk_mul_f32 v[146:147], v[146:147], s[80:81] op_sel_hi:[1,0]
	v_rcp_f32_e32 v136, v136
	v_rcp_f32_e32 v137, v137
	v_rcp_f32_e32 v138, v138
	v_rcp_f32_e32 v139, v139
	v_exp_f32_e32 v144, v144
	v_exp_f32_e32 v145, v145
	v_exp_f32_e32 v146, v146
	v_exp_f32_e32 v147, v147
	v_pk_fma_f32 v[140:141], v[136:137], s[86:87], v[0:1] op_sel_hi:[1,0,0]
	v_pk_fma_f32 v[142:143], v[138:139], s[86:87], v[0:1] op_sel_hi:[1,0,0]
	v_pk_fma_f32 v[140:141], v[136:137], v[140:141], s[88:89] op_sel_hi:[1,1,0]
	v_pk_fma_f32 v[142:143], v[138:139], v[142:143], s[88:89] op_sel_hi:[1,1,0]
	v_pk_fma_f32 v[140:141], v[136:137], v[140:141], s[82:83] op_sel_hi:[1,1,0]
	v_pk_fma_f32 v[142:143], v[138:139], v[142:143], s[82:83] op_sel_hi:[1,1,0]
	v_pk_fma_f32 v[140:141], v[136:137], v[140:141], s[48:49] op_sel_hi:[1,1,0]
	v_pk_fma_f32 v[142:143], v[138:139], v[142:143], s[48:49] op_sel_hi:[1,1,0]
	v_pk_mul_f32 v[140:141], v[136:137], v[140:141]
	v_pk_mul_f32 v[142:143], v[138:139], v[142:143]
	v_pk_mul_f32 v[140:141], v[140:141], v[144:145]
	v_pk_mul_f32 v[142:143], v[142:143], v[146:147]
	v_max_f32_e32 v92, 0, v92
	v_max_f32_e32 v93, 0, v93
	v_max_f32_e32 v94, 0, v94
	v_max_f32_e32 v95, 0, v95
	v_pk_fma_f32 v[92:93], v[132:133], v[140:141], v[92:93] neg_lo:[1,0,0] neg_hi:[1,0,0]
	v_pk_fma_f32 v[94:95], v[134:135], v[142:143], v[94:95] neg_lo:[1,0,0] neg_hi:[1,0,0]
	v_pk_add_f32 v[2:3], v[92:93], v[94:95]
	v_pk_mul_f32 v[152:153], v[92:93], v[92:93]
	v_pk_fma_f32 v[152:153], v[94:95], v[94:95], v[152:153]
	v_and_b32_e32 v132, 0x7fffffff, v84
	v_and_b32_e32 v133, 0x7fffffff, v85
	v_and_b32_e32 v134, 0x7fffffff, v86
	v_and_b32_e32 v135, 0x7fffffff, v87
	v_pk_mul_f32 v[144:145], v[84:85], v[84:85]
	v_pk_mul_f32 v[146:147], v[86:87], v[86:87]
	v_pk_fma_f32 v[136:137], v[132:133], s[84:85], 1.0 op_sel_hi:[1,0,0]
	v_pk_fma_f32 v[138:139], v[134:135], s[84:85], 1.0 op_sel_hi:[1,0,0]
	v_pk_mul_f32 v[144:145], v[144:145], s[80:81] op_sel_hi:[1,0]
	v_pk_mul_f32 v[146:147], v[146:147], s[80:81] op_sel_hi:[1,0]
	v_rcp_f32_e32 v136, v136
	v_rcp_f32_e32 v137, v137
	v_rcp_f32_e32 v138, v138
	v_rcp_f32_e32 v139, v139
	v_exp_f32_e32 v144, v144
	v_exp_f32_e32 v145, v145
	v_exp_f32_e32 v146, v146
	v_exp_f32_e32 v147, v147
	v_pk_fma_f32 v[140:141], v[136:137], s[86:87], v[0:1] op_sel_hi:[1,0,0]
	v_pk_fma_f32 v[142:143], v[138:139], s[86:87], v[0:1] op_sel_hi:[1,0,0]
	v_pk_fma_f32 v[140:141], v[136:137], v[140:141], s[88:89] op_sel_hi:[1,1,0]
	v_pk_fma_f32 v[142:143], v[138:139], v[142:143], s[88:89] op_sel_hi:[1,1,0]
	v_pk_fma_f32 v[140:141], v[136:137], v[140:141], s[82:83] op_sel_hi:[1,1,0]
	v_pk_fma_f32 v[142:143], v[138:139], v[142:143], s[82:83] op_sel_hi:[1,1,0]
	v_pk_fma_f32 v[140:141], v[136:137], v[140:141], s[48:49] op_sel_hi:[1,1,0]
	v_pk_fma_f32 v[142:143], v[138:139], v[142:143], s[48:49] op_sel_hi:[1,1,0]
	v_pk_mul_f32 v[140:141], v[136:137], v[140:141]
	v_pk_mul_f32 v[142:143], v[138:139], v[142:143]
	v_pk_mul_f32 v[140:141], v[140:141], v[144:145]
	v_pk_mul_f32 v[142:143], v[142:143], v[146:147]
	v_max_f32_e32 v84, 0, v84
	v_max_f32_e32 v85, 0, v85
	v_max_f32_e32 v86, 0, v86
	v_max_f32_e32 v87, 0, v87
	v_pk_fma_f32 v[84:85], v[132:133], v[140:141], v[84:85] neg_lo:[1,0,0] neg_hi:[1,0,0]
	v_pk_fma_f32 v[86:87], v[134:135], v[142:143], v[86:87] neg_lo:[1,0,0] neg_hi:[1,0,0]
	v_pk_add_f32 v[2:3], v[2:3], v[84:85]
	v_pk_fma_f32 v[152:153], v[84:85], v[84:85], v[152:153]
	v_pk_add_f32 v[2:3], v[2:3], v[86:87]
	v_pk_fma_f32 v[152:153], v[86:87], v[86:87], v[152:153]
	v_cvt_pk_bf16_f32 v92, v92, v93
	v_cvt_pk_bf16_f32 v93, v94, v95
	v_cvt_pk_bf16_f32 v94, v84, v85
	v_cvt_pk_bf16_f32 v95, v86, v87
	global_store_dwordx4 v148, v[92:95], s[50:51] sc1
	v_and_b32_e32 v132, 0x7fffffff, v76
	v_and_b32_e32 v133, 0x7fffffff, v77
	v_and_b32_e32 v134, 0x7fffffff, v78
	v_and_b32_e32 v135, 0x7fffffff, v79
	v_pk_mul_f32 v[144:145], v[76:77], v[76:77]
	v_pk_mul_f32 v[146:147], v[78:79], v[78:79]
	v_pk_fma_f32 v[136:137], v[132:133], s[84:85], 1.0 op_sel_hi:[1,0,0]
	v_pk_fma_f32 v[138:139], v[134:135], s[84:85], 1.0 op_sel_hi:[1,0,0]
	v_pk_mul_f32 v[144:145], v[144:145], s[80:81] op_sel_hi:[1,0]
	v_pk_mul_f32 v[146:147], v[146:147], s[80:81] op_sel_hi:[1,0]
	v_rcp_f32_e32 v136, v136
	v_rcp_f32_e32 v137, v137
	v_rcp_f32_e32 v138, v138
	v_rcp_f32_e32 v139, v139
	v_exp_f32_e32 v144, v144
	v_exp_f32_e32 v145, v145
	v_exp_f32_e32 v146, v146
	v_exp_f32_e32 v147, v147
	v_pk_fma_f32 v[140:141], v[136:137], s[86:87], v[0:1] op_sel_hi:[1,0,0]
	v_pk_fma_f32 v[142:143], v[138:139], s[86:87], v[0:1] op_sel_hi:[1,0,0]
	v_pk_fma_f32 v[140:141], v[136:137], v[140:141], s[88:89] op_sel_hi:[1,1,0]
	v_pk_fma_f32 v[142:143], v[138:139], v[142:143], s[88:89] op_sel_hi:[1,1,0]
	v_pk_fma_f32 v[140:141], v[136:137], v[140:141], s[82:83] op_sel_hi:[1,1,0]
	v_pk_fma_f32 v[142:143], v[138:139], v[142:143], s[82:83] op_sel_hi:[1,1,0]
	v_pk_fma_f32 v[140:141], v[136:137], v[140:141], s[48:49] op_sel_hi:[1,1,0]
	v_pk_fma_f32 v[142:143], v[138:139], v[142:143], s[48:49] op_sel_hi:[1,1,0]
	v_pk_mul_f32 v[140:141], v[136:137], v[140:141]
	v_pk_mul_f32 v[142:143], v[138:139], v[142:143]
	v_pk_mul_f32 v[140:141], v[140:141], v[144:145]
	v_pk_mul_f32 v[142:143], v[142:143], v[146:147]
	v_max_f32_e32 v76, 0, v76
	v_max_f32_e32 v77, 0, v77
	v_max_f32_e32 v78, 0, v78
	v_max_f32_e32 v79, 0, v79
	v_pk_fma_f32 v[76:77], v[132:133], v[140:141], v[76:77] neg_lo:[1,0,0] neg_hi:[1,0,0]
	v_pk_fma_f32 v[78:79], v[134:135], v[142:143], v[78:79] neg_lo:[1,0,0] neg_hi:[1,0,0]
	v_pk_add_f32 v[2:3], v[2:3], v[76:77]
	v_pk_fma_f32 v[152:153], v[76:77], v[76:77], v[152:153]
	v_pk_add_f32 v[2:3], v[2:3], v[78:79]
	v_pk_fma_f32 v[152:153], v[78:79], v[78:79], v[152:153]
	v_and_b32_e32 v132, 0x7fffffff, v68
	v_and_b32_e32 v133, 0x7fffffff, v69
	v_and_b32_e32 v134, 0x7fffffff, v70
	v_and_b32_e32 v135, 0x7fffffff, v71
	v_pk_mul_f32 v[144:145], v[68:69], v[68:69]
	v_pk_mul_f32 v[146:147], v[70:71], v[70:71]
	v_pk_fma_f32 v[136:137], v[132:133], s[84:85], 1.0 op_sel_hi:[1,0,0]
	v_pk_fma_f32 v[138:139], v[134:135], s[84:85], 1.0 op_sel_hi:[1,0,0]
	v_pk_mul_f32 v[144:145], v[144:145], s[80:81] op_sel_hi:[1,0]
	v_pk_mul_f32 v[146:147], v[146:147], s[80:81] op_sel_hi:[1,0]
	v_rcp_f32_e32 v136, v136
	v_rcp_f32_e32 v137, v137
	v_rcp_f32_e32 v138, v138
	v_rcp_f32_e32 v139, v139
	v_exp_f32_e32 v144, v144
	v_exp_f32_e32 v145, v145
	v_exp_f32_e32 v146, v146
	v_exp_f32_e32 v147, v147
	v_pk_fma_f32 v[140:141], v[136:137], s[86:87], v[0:1] op_sel_hi:[1,0,0]
	v_pk_fma_f32 v[142:143], v[138:139], s[86:87], v[0:1] op_sel_hi:[1,0,0]
	v_pk_fma_f32 v[140:141], v[136:137], v[140:141], s[88:89] op_sel_hi:[1,1,0]
	v_pk_fma_f32 v[142:143], v[138:139], v[142:143], s[88:89] op_sel_hi:[1,1,0]
	v_pk_fma_f32 v[140:141], v[136:137], v[140:141], s[82:83] op_sel_hi:[1,1,0]
	v_pk_fma_f32 v[142:143], v[138:139], v[142:143], s[82:83] op_sel_hi:[1,1,0]
	v_pk_fma_f32 v[140:141], v[136:137], v[140:141], s[48:49] op_sel_hi:[1,1,0]
	v_pk_fma_f32 v[142:143], v[138:139], v[142:143], s[48:49] op_sel_hi:[1,1,0]
	v_pk_mul_f32 v[140:141], v[136:137], v[140:141]
	v_pk_mul_f32 v[142:143], v[138:139], v[142:143]
	v_pk_mul_f32 v[140:141], v[140:141], v[144:145]
	v_pk_mul_f32 v[142:143], v[142:143], v[146:147]
	v_max_f32_e32 v68, 0, v68
	v_max_f32_e32 v69, 0, v69
	v_max_f32_e32 v70, 0, v70
	v_max_f32_e32 v71, 0, v71
	v_pk_fma_f32 v[68:69], v[132:133], v[140:141], v[68:69] neg_lo:[1,0,0] neg_hi:[1,0,0]
	v_pk_fma_f32 v[70:71], v[134:135], v[142:143], v[70:71] neg_lo:[1,0,0] neg_hi:[1,0,0]
	v_pk_add_f32 v[2:3], v[2:3], v[68:69]
	v_pk_fma_f32 v[152:153], v[68:69], v[68:69], v[152:153]
	v_pk_add_f32 v[2:3], v[2:3], v[70:71]
	v_pk_fma_f32 v[152:153], v[70:71], v[70:71], v[152:153]
	v_cvt_pk_bf16_f32 v76, v76, v77
	v_cvt_pk_bf16_f32 v77, v78, v79
	v_cvt_pk_bf16_f32 v78, v68, v69
	v_cvt_pk_bf16_f32 v79, v70, v71
	global_store_dwordx4 v148, v[76:79], s[50:51] offset:256 sc1
	v_add_f32_e32 v2, v2, v3
	v_add_f32_e32 v3, v152, v153
	ds_bpermute_b32 v132, v150, v2
	ds_bpermute_b32 v133, v150, v3
	s_waitcnt lgkmcnt(0)
	v_pk_add_f32 v[2:3], v[2:3], v[132:133]
	ds_bpermute_b32 v132, v151, v2
	ds_bpermute_b32 v133, v151, v3
	s_waitcnt lgkmcnt(0)
	v_pk_add_f32 v[2:3], v[2:3], v[132:133]
	s_and_saveexec_b64 s[46:47], s[38:39]
	global_store_dwordx2 v149, v[2:3], s[66:67]
	s_mov_b64 exec, s[46:47]
	s_mul_i32 s30, s81, 5
	v_add_u32_e32 v148, s30, v148
	v_add_u32_e32 v149, 0x1400, v149
	s_cmp_lg_u32 s49, 0
	s_cbranch_scc1 .LBB0_326
	v_and_b32_e32 v132, 0x7fffffff, v64
	v_and_b32_e32 v133, 0x7fffffff, v65
	v_and_b32_e32 v134, 0x7fffffff, v66
	v_and_b32_e32 v135, 0x7fffffff, v67
	v_pk_mul_f32 v[144:145], v[64:65], v[64:65]
	v_pk_mul_f32 v[146:147], v[66:67], v[66:67]
	v_pk_fma_f32 v[136:137], v[132:133], s[84:85], 1.0 op_sel_hi:[1,0,0]
	v_pk_fma_f32 v[138:139], v[134:135], s[84:85], 1.0 op_sel_hi:[1,0,0]
	v_pk_mul_f32 v[144:145], v[144:145], s[80:81] op_sel_hi:[1,0]
	v_pk_mul_f32 v[146:147], v[146:147], s[80:81] op_sel_hi:[1,0]
	v_rcp_f32_e32 v136, v136
	v_rcp_f32_e32 v137, v137
	v_rcp_f32_e32 v138, v138
	v_rcp_f32_e32 v139, v139
	v_exp_f32_e32 v144, v144
	v_exp_f32_e32 v145, v145
	v_exp_f32_e32 v146, v146
	v_exp_f32_e32 v147, v147
	v_pk_fma_f32 v[140:141], v[136:137], s[86:87], v[0:1] op_sel_hi:[1,0,0]
	v_pk_fma_f32 v[142:143], v[138:139], s[86:87], v[0:1] op_sel_hi:[1,0,0]
	v_pk_fma_f32 v[140:141], v[136:137], v[140:141], s[88:89] op_sel_hi:[1,1,0]
	v_pk_fma_f32 v[142:143], v[138:139], v[142:143], s[88:89] op_sel_hi:[1,1,0]
	v_pk_fma_f32 v[140:141], v[136:137], v[140:141], s[82:83] op_sel_hi:[1,1,0]
	v_pk_fma_f32 v[142:143], v[138:139], v[142:143], s[82:83] op_sel_hi:[1,1,0]
	v_pk_fma_f32 v[140:141], v[136:137], v[140:141], s[48:49] op_sel_hi:[1,1,0]
	v_pk_fma_f32 v[142:143], v[138:139], v[142:143], s[48:49] op_sel_hi:[1,1,0]
	v_pk_mul_f32 v[140:141], v[136:137], v[140:141]
	v_pk_mul_f32 v[142:143], v[138:139], v[142:143]
	v_pk_mul_f32 v[140:141], v[140:141], v[144:145]
	v_pk_mul_f32 v[142:143], v[142:143], v[146:147]
	v_max_f32_e32 v64, 0, v64
	v_max_f32_e32 v65, 0, v65
	v_max_f32_e32 v66, 0, v66
	v_max_f32_e32 v67, 0, v67
	v_pk_fma_f32 v[64:65], v[132:133], v[140:141], v[64:65] neg_lo:[1,0,0] neg_hi:[1,0,0]
	v_pk_fma_f32 v[66:67], v[134:135], v[142:143], v[66:67] neg_lo:[1,0,0] neg_hi:[1,0,0]
	v_pk_add_f32 v[2:3], v[64:65], v[66:67]
	v_pk_mul_f32 v[152:153], v[64:65], v[64:65]
	v_pk_fma_f32 v[152:153], v[66:67], v[66:67], v[152:153]
	v_and_b32_e32 v132, 0x7fffffff, v56
	v_and_b32_e32 v133, 0x7fffffff, v57
	v_and_b32_e32 v134, 0x7fffffff, v58
	v_and_b32_e32 v135, 0x7fffffff, v59
	v_pk_mul_f32 v[144:145], v[56:57], v[56:57]
	v_pk_mul_f32 v[146:147], v[58:59], v[58:59]
	v_pk_fma_f32 v[136:137], v[132:133], s[84:85], 1.0 op_sel_hi:[1,0,0]
	v_pk_fma_f32 v[138:139], v[134:135], s[84:85], 1.0 op_sel_hi:[1,0,0]
	v_pk_mul_f32 v[144:145], v[144:145], s[80:81] op_sel_hi:[1,0]
	v_pk_mul_f32 v[146:147], v[146:147], s[80:81] op_sel_hi:[1,0]
	v_rcp_f32_e32 v136, v136
	v_rcp_f32_e32 v137, v137
	v_rcp_f32_e32 v138, v138
	v_rcp_f32_e32 v139, v139
	v_exp_f32_e32 v144, v144
	v_exp_f32_e32 v145, v145
	v_exp_f32_e32 v146, v146
	v_exp_f32_e32 v147, v147
	v_pk_fma_f32 v[140:141], v[136:137], s[86:87], v[0:1] op_sel_hi:[1,0,0]
	v_pk_fma_f32 v[142:143], v[138:139], s[86:87], v[0:1] op_sel_hi:[1,0,0]
	v_pk_fma_f32 v[140:141], v[136:137], v[140:141], s[88:89] op_sel_hi:[1,1,0]
	v_pk_fma_f32 v[142:143], v[138:139], v[142:143], s[88:89] op_sel_hi:[1,1,0]
	v_pk_fma_f32 v[140:141], v[136:137], v[140:141], s[82:83] op_sel_hi:[1,1,0]
	v_pk_fma_f32 v[142:143], v[138:139], v[142:143], s[82:83] op_sel_hi:[1,1,0]
	v_pk_fma_f32 v[140:141], v[136:137], v[140:141], s[48:49] op_sel_hi:[1,1,0]
	v_pk_fma_f32 v[142:143], v[138:139], v[142:143], s[48:49] op_sel_hi:[1,1,0]
	v_pk_mul_f32 v[140:141], v[136:137], v[140:141]
	v_pk_mul_f32 v[142:143], v[138:139], v[142:143]
	v_pk_mul_f32 v[140:141], v[140:141], v[144:145]
	v_pk_mul_f32 v[142:143], v[142:143], v[146:147]
	v_max_f32_e32 v56, 0, v56
	v_max_f32_e32 v57, 0, v57
	v_max_f32_e32 v58, 0, v58
	v_max_f32_e32 v59, 0, v59
	v_pk_fma_f32 v[56:57], v[132:133], v[140:141], v[56:57] neg_lo:[1,0,0] neg_hi:[1,0,0]
	v_pk_fma_f32 v[58:59], v[134:135], v[142:143], v[58:59] neg_lo:[1,0,0] neg_hi:[1,0,0]
	v_pk_add_f32 v[2:3], v[2:3], v[56:57]
	v_pk_fma_f32 v[152:153], v[56:57], v[56:57], v[152:153]
	v_pk_add_f32 v[2:3], v[2:3], v[58:59]
	v_pk_fma_f32 v[152:153], v[58:59], v[58:59], v[152:153]
	v_cvt_pk_bf16_f32 v64, v64, v65
	v_cvt_pk_bf16_f32 v65, v66, v67
	v_cvt_pk_bf16_f32 v66, v56, v57
	v_cvt_pk_bf16_f32 v67, v58, v59
	global_store_dwordx4 v148, v[64:67], s[50:51] sc1
	v_and_b32_e32 v132, 0x7fffffff, v48
	v_and_b32_e32 v133, 0x7fffffff, v49
	v_and_b32_e32 v134, 0x7fffffff, v50
	v_and_b32_e32 v135, 0x7fffffff, v51
	v_pk_mul_f32 v[144:145], v[48:49], v[48:49]
	v_pk_mul_f32 v[146:147], v[50:51], v[50:51]
	v_pk_fma_f32 v[136:137], v[132:133], s[84:85], 1.0 op_sel_hi:[1,0,0]
	v_pk_fma_f32 v[138:139], v[134:135], s[84:85], 1.0 op_sel_hi:[1,0,0]
	v_pk_mul_f32 v[144:145], v[144:145], s[80:81] op_sel_hi:[1,0]
	v_pk_mul_f32 v[146:147], v[146:147], s[80:81] op_sel_hi:[1,0]
	v_rcp_f32_e32 v136, v136
	v_rcp_f32_e32 v137, v137
	v_rcp_f32_e32 v138, v138
	v_rcp_f32_e32 v139, v139
	v_exp_f32_e32 v144, v144
	v_exp_f32_e32 v145, v145
	v_exp_f32_e32 v146, v146
	v_exp_f32_e32 v147, v147
	v_pk_fma_f32 v[140:141], v[136:137], s[86:87], v[0:1] op_sel_hi:[1,0,0]
	v_pk_fma_f32 v[142:143], v[138:139], s[86:87], v[0:1] op_sel_hi:[1,0,0]
	v_pk_fma_f32 v[140:141], v[136:137], v[140:141], s[88:89] op_sel_hi:[1,1,0]
	v_pk_fma_f32 v[142:143], v[138:139], v[142:143], s[88:89] op_sel_hi:[1,1,0]
	v_pk_fma_f32 v[140:141], v[136:137], v[140:141], s[82:83] op_sel_hi:[1,1,0]
	v_pk_fma_f32 v[142:143], v[138:139], v[142:143], s[82:83] op_sel_hi:[1,1,0]
	v_pk_fma_f32 v[140:141], v[136:137], v[140:141], s[48:49] op_sel_hi:[1,1,0]
	v_pk_fma_f32 v[142:143], v[138:139], v[142:143], s[48:49] op_sel_hi:[1,1,0]
	v_pk_mul_f32 v[140:141], v[136:137], v[140:141]
	v_pk_mul_f32 v[142:143], v[138:139], v[142:143]
	v_pk_mul_f32 v[140:141], v[140:141], v[144:145]
	v_pk_mul_f32 v[142:143], v[142:143], v[146:147]
	v_max_f32_e32 v48, 0, v48
	v_max_f32_e32 v49, 0, v49
	v_max_f32_e32 v50, 0, v50
	v_max_f32_e32 v51, 0, v51
	v_pk_fma_f32 v[48:49], v[132:133], v[140:141], v[48:49] neg_lo:[1,0,0] neg_hi:[1,0,0]
	v_pk_fma_f32 v[50:51], v[134:135], v[142:143], v[50:51] neg_lo:[1,0,0] neg_hi:[1,0,0]
	v_pk_add_f32 v[2:3], v[2:3], v[48:49]
	v_pk_fma_f32 v[152:153], v[48:49], v[48:49], v[152:153]
	v_pk_add_f32 v[2:3], v[2:3], v[50:51]
	v_pk_fma_f32 v[152:153], v[50:51], v[50:51], v[152:153]
	v_and_b32_e32 v132, 0x7fffffff, v40
	v_and_b32_e32 v133, 0x7fffffff, v41
	v_and_b32_e32 v134, 0x7fffffff, v42
	v_and_b32_e32 v135, 0x7fffffff, v43
	v_pk_mul_f32 v[144:145], v[40:41], v[40:41]
	v_pk_mul_f32 v[146:147], v[42:43], v[42:43]
	v_pk_fma_f32 v[136:137], v[132:133], s[84:85], 1.0 op_sel_hi:[1,0,0]
	v_pk_fma_f32 v[138:139], v[134:135], s[84:85], 1.0 op_sel_hi:[1,0,0]
	v_pk_mul_f32 v[144:145], v[144:145], s[80:81] op_sel_hi:[1,0]
	v_pk_mul_f32 v[146:147], v[146:147], s[80:81] op_sel_hi:[1,0]
	v_rcp_f32_e32 v136, v136
	v_rcp_f32_e32 v137, v137
	v_rcp_f32_e32 v138, v138
	v_rcp_f32_e32 v139, v139
	v_exp_f32_e32 v144, v144
	v_exp_f32_e32 v145, v145
	v_exp_f32_e32 v146, v146
	v_exp_f32_e32 v147, v147
	v_pk_fma_f32 v[140:141], v[136:137], s[86:87], v[0:1] op_sel_hi:[1,0,0]
	v_pk_fma_f32 v[142:143], v[138:139], s[86:87], v[0:1] op_sel_hi:[1,0,0]
	v_pk_fma_f32 v[140:141], v[136:137], v[140:141], s[88:89] op_sel_hi:[1,1,0]
	v_pk_fma_f32 v[142:143], v[138:139], v[142:143], s[88:89] op_sel_hi:[1,1,0]
	v_pk_fma_f32 v[140:141], v[136:137], v[140:141], s[82:83] op_sel_hi:[1,1,0]
	v_pk_fma_f32 v[142:143], v[138:139], v[142:143], s[82:83] op_sel_hi:[1,1,0]
	v_pk_fma_f32 v[140:141], v[136:137], v[140:141], s[48:49] op_sel_hi:[1,1,0]
	v_pk_fma_f32 v[142:143], v[138:139], v[142:143], s[48:49] op_sel_hi:[1,1,0]
	v_pk_mul_f32 v[140:141], v[136:137], v[140:141]
	v_pk_mul_f32 v[142:143], v[138:139], v[142:143]
	v_pk_mul_f32 v[140:141], v[140:141], v[144:145]
	v_pk_mul_f32 v[142:143], v[142:143], v[146:147]
	v_max_f32_e32 v40, 0, v40
	v_max_f32_e32 v41, 0, v41
	v_max_f32_e32 v42, 0, v42
	v_max_f32_e32 v43, 0, v43
	v_pk_fma_f32 v[40:41], v[132:133], v[140:141], v[40:41] neg_lo:[1,0,0] neg_hi:[1,0,0]
	v_pk_fma_f32 v[42:43], v[134:135], v[142:143], v[42:43] neg_lo:[1,0,0] neg_hi:[1,0,0]
	v_pk_add_f32 v[2:3], v[2:3], v[40:41]
	v_pk_fma_f32 v[152:153], v[40:41], v[40:41], v[152:153]
	v_pk_add_f32 v[2:3], v[2:3], v[42:43]
	v_pk_fma_f32 v[152:153], v[42:43], v[42:43], v[152:153]
	v_cvt_pk_bf16_f32 v48, v48, v49
	v_cvt_pk_bf16_f32 v49, v50, v51
	v_cvt_pk_bf16_f32 v50, v40, v41
	v_cvt_pk_bf16_f32 v51, v42, v43
	global_store_dwordx4 v148, v[48:51], s[50:51] offset:256 sc1
	v_add_f32_e32 v2, v2, v3
	v_add_f32_e32 v3, v152, v153
	ds_bpermute_b32 v132, v150, v2
	ds_bpermute_b32 v133, v150, v3
	s_waitcnt lgkmcnt(0)
	v_pk_add_f32 v[2:3], v[2:3], v[132:133]
	ds_bpermute_b32 v132, v151, v2
	ds_bpermute_b32 v133, v151, v3
	s_waitcnt lgkmcnt(0)
	v_pk_add_f32 v[2:3], v[2:3], v[132:133]
	s_and_saveexec_b64 s[46:47], s[38:39]
	global_store_dwordx2 v149, v[2:3], s[66:67]
	s_mov_b64 exec, s[46:47]
	v_add_u32_e32 v148, s81, v148
	v_add_u32_e32 v149, 0x400, v149
	v_and_b32_e32 v132, 0x7fffffff, v60
	v_and_b32_e32 v133, 0x7fffffff, v61
	v_and_b32_e32 v134, 0x7fffffff, v62
	v_and_b32_e32 v135, 0x7fffffff, v63
	v_pk_mul_f32 v[144:145], v[60:61], v[60:61]
	v_pk_mul_f32 v[146:147], v[62:63], v[62:63]
	v_pk_fma_f32 v[136:137], v[132:133], s[84:85], 1.0 op_sel_hi:[1,0,0]
	v_pk_fma_f32 v[138:139], v[134:135], s[84:85], 1.0 op_sel_hi:[1,0,0]
	v_pk_mul_f32 v[144:145], v[144:145], s[80:81] op_sel_hi:[1,0]
	v_pk_mul_f32 v[146:147], v[146:147], s[80:81] op_sel_hi:[1,0]
	v_rcp_f32_e32 v136, v136
	v_rcp_f32_e32 v137, v137
	v_rcp_f32_e32 v138, v138
	v_rcp_f32_e32 v139, v139
	v_exp_f32_e32 v144, v144
	v_exp_f32_e32 v145, v145
	v_exp_f32_e32 v146, v146
	v_exp_f32_e32 v147, v147
	v_pk_fma_f32 v[140:141], v[136:137], s[86:87], v[0:1] op_sel_hi:[1,0,0]
	v_pk_fma_f32 v[142:143], v[138:139], s[86:87], v[0:1] op_sel_hi:[1,0,0]
	v_pk_fma_f32 v[140:141], v[136:137], v[140:141], s[88:89] op_sel_hi:[1,1,0]
	v_pk_fma_f32 v[142:143], v[138:139], v[142:143], s[88:89] op_sel_hi:[1,1,0]
	v_pk_fma_f32 v[140:141], v[136:137], v[140:141], s[82:83] op_sel_hi:[1,1,0]
	v_pk_fma_f32 v[142:143], v[138:139], v[142:143], s[82:83] op_sel_hi:[1,1,0]
	v_pk_fma_f32 v[140:141], v[136:137], v[140:141], s[48:49] op_sel_hi:[1,1,0]
	v_pk_fma_f32 v[142:143], v[138:139], v[142:143], s[48:49] op_sel_hi:[1,1,0]
	v_pk_mul_f32 v[140:141], v[136:137], v[140:141]
	v_pk_mul_f32 v[142:143], v[138:139], v[142:143]
	v_pk_mul_f32 v[140:141], v[140:141], v[144:145]
	v_pk_mul_f32 v[142:143], v[142:143], v[146:147]
	v_max_f32_e32 v60, 0, v60
	v_max_f32_e32 v61, 0, v61
	v_max_f32_e32 v62, 0, v62
	v_max_f32_e32 v63, 0, v63
	v_pk_fma_f32 v[60:61], v[132:133], v[140:141], v[60:61] neg_lo:[1,0,0] neg_hi:[1,0,0]
	v_pk_fma_f32 v[62:63], v[134:135], v[142:143], v[62:63] neg_lo:[1,0,0] neg_hi:[1,0,0]
	v_pk_add_f32 v[2:3], v[60:61], v[62:63]
	v_pk_mul_f32 v[152:153], v[60:61], v[60:61]
	v_pk_fma_f32 v[152:153], v[62:63], v[62:63], v[152:153]
	v_and_b32_e32 v132, 0x7fffffff, v52
	v_and_b32_e32 v133, 0x7fffffff, v53
	v_and_b32_e32 v134, 0x7fffffff, v54
	v_and_b32_e32 v135, 0x7fffffff, v55
	v_pk_mul_f32 v[144:145], v[52:53], v[52:53]
	v_pk_mul_f32 v[146:147], v[54:55], v[54:55]
	v_pk_fma_f32 v[136:137], v[132:133], s[84:85], 1.0 op_sel_hi:[1,0,0]
	v_pk_fma_f32 v[138:139], v[134:135], s[84:85], 1.0 op_sel_hi:[1,0,0]
	v_pk_mul_f32 v[144:145], v[144:145], s[80:81] op_sel_hi:[1,0]
	v_pk_mul_f32 v[146:147], v[146:147], s[80:81] op_sel_hi:[1,0]
	v_rcp_f32_e32 v136, v136
	v_rcp_f32_e32 v137, v137
	v_rcp_f32_e32 v138, v138
	v_rcp_f32_e32 v139, v139
	v_exp_f32_e32 v144, v144
	v_exp_f32_e32 v145, v145
	v_exp_f32_e32 v146, v146
	v_exp_f32_e32 v147, v147
	v_pk_fma_f32 v[140:141], v[136:137], s[86:87], v[0:1] op_sel_hi:[1,0,0]
	v_pk_fma_f32 v[142:143], v[138:139], s[86:87], v[0:1] op_sel_hi:[1,0,0]
	v_pk_fma_f32 v[140:141], v[136:137], v[140:141], s[88:89] op_sel_hi:[1,1,0]
	v_pk_fma_f32 v[142:143], v[138:139], v[142:143], s[88:89] op_sel_hi:[1,1,0]
	v_pk_fma_f32 v[140:141], v[136:137], v[140:141], s[82:83] op_sel_hi:[1,1,0]
	v_pk_fma_f32 v[142:143], v[138:139], v[142:143], s[82:83] op_sel_hi:[1,1,0]
	v_pk_fma_f32 v[140:141], v[136:137], v[140:141], s[48:49] op_sel_hi:[1,1,0]
	v_pk_fma_f32 v[142:143], v[138:139], v[142:143], s[48:49] op_sel_hi:[1,1,0]
	v_pk_mul_f32 v[140:141], v[136:137], v[140:141]
	v_pk_mul_f32 v[142:143], v[138:139], v[142:143]
	v_pk_mul_f32 v[140:141], v[140:141], v[144:145]
	v_pk_mul_f32 v[142:143], v[142:143], v[146:147]
	v_max_f32_e32 v52, 0, v52
	v_max_f32_e32 v53, 0, v53
	v_max_f32_e32 v54, 0, v54
	v_max_f32_e32 v55, 0, v55
	v_pk_fma_f32 v[52:53], v[132:133], v[140:141], v[52:53] neg_lo:[1,0,0] neg_hi:[1,0,0]
	v_pk_fma_f32 v[54:55], v[134:135], v[142:143], v[54:55] neg_lo:[1,0,0] neg_hi:[1,0,0]
	v_pk_add_f32 v[2:3], v[2:3], v[52:53]
	v_pk_fma_f32 v[152:153], v[52:53], v[52:53], v[152:153]
	v_pk_add_f32 v[2:3], v[2:3], v[54:55]
	v_pk_fma_f32 v[152:153], v[54:55], v[54:55], v[152:153]
	v_cvt_pk_bf16_f32 v60, v60, v61
	v_cvt_pk_bf16_f32 v61, v62, v63
	v_cvt_pk_bf16_f32 v62, v52, v53
	v_cvt_pk_bf16_f32 v63, v54, v55
	global_store_dwordx4 v148, v[60:63], s[50:51] sc1
	v_and_b32_e32 v132, 0x7fffffff, v44
	v_and_b32_e32 v133, 0x7fffffff, v45
	v_and_b32_e32 v134, 0x7fffffff, v46
	v_and_b32_e32 v135, 0x7fffffff, v47
	v_pk_mul_f32 v[144:145], v[44:45], v[44:45]
	v_pk_mul_f32 v[146:147], v[46:47], v[46:47]
	v_pk_fma_f32 v[136:137], v[132:133], s[84:85], 1.0 op_sel_hi:[1,0,0]
	v_pk_fma_f32 v[138:139], v[134:135], s[84:85], 1.0 op_sel_hi:[1,0,0]
	v_pk_mul_f32 v[144:145], v[144:145], s[80:81] op_sel_hi:[1,0]
	v_pk_mul_f32 v[146:147], v[146:147], s[80:81] op_sel_hi:[1,0]
	v_rcp_f32_e32 v136, v136
	v_rcp_f32_e32 v137, v137
	v_rcp_f32_e32 v138, v138
	v_rcp_f32_e32 v139, v139
	v_exp_f32_e32 v144, v144
	v_exp_f32_e32 v145, v145
	v_exp_f32_e32 v146, v146
	v_exp_f32_e32 v147, v147
	v_pk_fma_f32 v[140:141], v[136:137], s[86:87], v[0:1] op_sel_hi:[1,0,0]
	v_pk_fma_f32 v[142:143], v[138:139], s[86:87], v[0:1] op_sel_hi:[1,0,0]
	v_pk_fma_f32 v[140:141], v[136:137], v[140:141], s[88:89] op_sel_hi:[1,1,0]
	v_pk_fma_f32 v[142:143], v[138:139], v[142:143], s[88:89] op_sel_hi:[1,1,0]
	v_pk_fma_f32 v[140:141], v[136:137], v[140:141], s[82:83] op_sel_hi:[1,1,0]
	v_pk_fma_f32 v[142:143], v[138:139], v[142:143], s[82:83] op_sel_hi:[1,1,0]
	v_pk_fma_f32 v[140:141], v[136:137], v[140:141], s[48:49] op_sel_hi:[1,1,0]
	v_pk_fma_f32 v[142:143], v[138:139], v[142:143], s[48:49] op_sel_hi:[1,1,0]
	v_pk_mul_f32 v[140:141], v[136:137], v[140:141]
	v_pk_mul_f32 v[142:143], v[138:139], v[142:143]
	v_pk_mul_f32 v[140:141], v[140:141], v[144:145]
	v_pk_mul_f32 v[142:143], v[142:143], v[146:147]
	v_max_f32_e32 v44, 0, v44
	v_max_f32_e32 v45, 0, v45
	v_max_f32_e32 v46, 0, v46
	v_max_f32_e32 v47, 0, v47
	v_pk_fma_f32 v[44:45], v[132:133], v[140:141], v[44:45] neg_lo:[1,0,0] neg_hi:[1,0,0]
	v_pk_fma_f32 v[46:47], v[134:135], v[142:143], v[46:47] neg_lo:[1,0,0] neg_hi:[1,0,0]
	v_pk_add_f32 v[2:3], v[2:3], v[44:45]
	v_pk_fma_f32 v[152:153], v[44:45], v[44:45], v[152:153]
	v_pk_add_f32 v[2:3], v[2:3], v[46:47]
	v_pk_fma_f32 v[152:153], v[46:47], v[46:47], v[152:153]
	v_and_b32_e32 v132, 0x7fffffff, v36
	v_and_b32_e32 v133, 0x7fffffff, v37
	v_and_b32_e32 v134, 0x7fffffff, v38
	v_and_b32_e32 v135, 0x7fffffff, v39
	v_pk_mul_f32 v[144:145], v[36:37], v[36:37]
	v_pk_mul_f32 v[146:147], v[38:39], v[38:39]
	v_pk_fma_f32 v[136:137], v[132:133], s[84:85], 1.0 op_sel_hi:[1,0,0]
	v_pk_fma_f32 v[138:139], v[134:135], s[84:85], 1.0 op_sel_hi:[1,0,0]
	v_pk_mul_f32 v[144:145], v[144:145], s[80:81] op_sel_hi:[1,0]
	v_pk_mul_f32 v[146:147], v[146:147], s[80:81] op_sel_hi:[1,0]
	v_rcp_f32_e32 v136, v136
	v_rcp_f32_e32 v137, v137
	v_rcp_f32_e32 v138, v138
	v_rcp_f32_e32 v139, v139
	v_exp_f32_e32 v144, v144
	v_exp_f32_e32 v145, v145
	v_exp_f32_e32 v146, v146
	v_exp_f32_e32 v147, v147
	v_pk_fma_f32 v[140:141], v[136:137], s[86:87], v[0:1] op_sel_hi:[1,0,0]
	v_pk_fma_f32 v[142:143], v[138:139], s[86:87], v[0:1] op_sel_hi:[1,0,0]
	v_pk_fma_f32 v[140:141], v[136:137], v[140:141], s[88:89] op_sel_hi:[1,1,0]
	v_pk_fma_f32 v[142:143], v[138:139], v[142:143], s[88:89] op_sel_hi:[1,1,0]
	v_pk_fma_f32 v[140:141], v[136:137], v[140:141], s[82:83] op_sel_hi:[1,1,0]
	v_pk_fma_f32 v[142:143], v[138:139], v[142:143], s[82:83] op_sel_hi:[1,1,0]
	v_pk_fma_f32 v[140:141], v[136:137], v[140:141], s[48:49] op_sel_hi:[1,1,0]
	v_pk_fma_f32 v[142:143], v[138:139], v[142:143], s[48:49] op_sel_hi:[1,1,0]
	v_pk_mul_f32 v[140:141], v[136:137], v[140:141]
	v_pk_mul_f32 v[142:143], v[138:139], v[142:143]
	v_pk_mul_f32 v[140:141], v[140:141], v[144:145]
	v_pk_mul_f32 v[142:143], v[142:143], v[146:147]
	v_max_f32_e32 v36, 0, v36
	v_max_f32_e32 v37, 0, v37
	v_max_f32_e32 v38, 0, v38
	v_max_f32_e32 v39, 0, v39
	v_pk_fma_f32 v[36:37], v[132:133], v[140:141], v[36:37] neg_lo:[1,0,0] neg_hi:[1,0,0]
	v_pk_fma_f32 v[38:39], v[134:135], v[142:143], v[38:39] neg_lo:[1,0,0] neg_hi:[1,0,0]
	v_pk_add_f32 v[2:3], v[2:3], v[36:37]
	v_pk_fma_f32 v[152:153], v[36:37], v[36:37], v[152:153]
	v_pk_add_f32 v[2:3], v[2:3], v[38:39]
	v_pk_fma_f32 v[152:153], v[38:39], v[38:39], v[152:153]
	v_cvt_pk_bf16_f32 v44, v44, v45
	v_cvt_pk_bf16_f32 v45, v46, v47
	v_cvt_pk_bf16_f32 v46, v36, v37
	v_cvt_pk_bf16_f32 v47, v38, v39
	global_store_dwordx4 v148, v[44:47], s[50:51] offset:256 sc1
	v_add_f32_e32 v2, v2, v3
	v_add_f32_e32 v3, v152, v153
	ds_bpermute_b32 v132, v150, v2
	ds_bpermute_b32 v133, v150, v3
	s_waitcnt lgkmcnt(0)
	v_pk_add_f32 v[2:3], v[2:3], v[132:133]
	ds_bpermute_b32 v132, v151, v2
	ds_bpermute_b32 v133, v151, v3
	s_waitcnt lgkmcnt(0)
	v_pk_add_f32 v[2:3], v[2:3], v[132:133]
	s_and_saveexec_b64 s[46:47], s[38:39]
	global_store_dwordx2 v149, v[2:3], s[66:67]
	s_mov_b64 exec, s[46:47]
	v_add_u32_e32 v148, s81, v148
	v_add_u32_e32 v149, 0x400, v149
	v_and_b32_e32 v132, 0x7fffffff, v32
	v_and_b32_e32 v133, 0x7fffffff, v33
	v_and_b32_e32 v134, 0x7fffffff, v34
	v_and_b32_e32 v135, 0x7fffffff, v35
	v_pk_mul_f32 v[144:145], v[32:33], v[32:33]
	v_pk_mul_f32 v[146:147], v[34:35], v[34:35]
	v_pk_fma_f32 v[136:137], v[132:133], s[84:85], 1.0 op_sel_hi:[1,0,0]
	v_pk_fma_f32 v[138:139], v[134:135], s[84:85], 1.0 op_sel_hi:[1,0,0]
	v_pk_mul_f32 v[144:145], v[144:145], s[80:81] op_sel_hi:[1,0]
	v_pk_mul_f32 v[146:147], v[146:147], s[80:81] op_sel_hi:[1,0]
	v_rcp_f32_e32 v136, v136
	v_rcp_f32_e32 v137, v137
	v_rcp_f32_e32 v138, v138
	v_rcp_f32_e32 v139, v139
	v_exp_f32_e32 v144, v144
	v_exp_f32_e32 v145, v145
	v_exp_f32_e32 v146, v146
	v_exp_f32_e32 v147, v147
	v_pk_fma_f32 v[140:141], v[136:137], s[86:87], v[0:1] op_sel_hi:[1,0,0]
	v_pk_fma_f32 v[142:143], v[138:139], s[86:87], v[0:1] op_sel_hi:[1,0,0]
	v_pk_fma_f32 v[140:141], v[136:137], v[140:141], s[88:89] op_sel_hi:[1,1,0]
	v_pk_fma_f32 v[142:143], v[138:139], v[142:143], s[88:89] op_sel_hi:[1,1,0]
	v_pk_fma_f32 v[140:141], v[136:137], v[140:141], s[82:83] op_sel_hi:[1,1,0]
	v_pk_fma_f32 v[142:143], v[138:139], v[142:143], s[82:83] op_sel_hi:[1,1,0]
	v_pk_fma_f32 v[140:141], v[136:137], v[140:141], s[48:49] op_sel_hi:[1,1,0]
	v_pk_fma_f32 v[142:143], v[138:139], v[142:143], s[48:49] op_sel_hi:[1,1,0]
	v_pk_mul_f32 v[140:141], v[136:137], v[140:141]
	v_pk_mul_f32 v[142:143], v[138:139], v[142:143]
	v_pk_mul_f32 v[140:141], v[140:141], v[144:145]
	v_pk_mul_f32 v[142:143], v[142:143], v[146:147]
	v_max_f32_e32 v32, 0, v32
	v_max_f32_e32 v33, 0, v33
	v_max_f32_e32 v34, 0, v34
	v_max_f32_e32 v35, 0, v35
	v_pk_fma_f32 v[32:33], v[132:133], v[140:141], v[32:33] neg_lo:[1,0,0] neg_hi:[1,0,0]
	v_pk_fma_f32 v[34:35], v[134:135], v[142:143], v[34:35] neg_lo:[1,0,0] neg_hi:[1,0,0]
	v_pk_add_f32 v[2:3], v[32:33], v[34:35]
	v_pk_mul_f32 v[152:153], v[32:33], v[32:33]
	v_pk_fma_f32 v[152:153], v[34:35], v[34:35], v[152:153]
	v_and_b32_e32 v132, 0x7fffffff, v24
	v_and_b32_e32 v133, 0x7fffffff, v25
	v_and_b32_e32 v134, 0x7fffffff, v26
	v_and_b32_e32 v135, 0x7fffffff, v27
	v_pk_mul_f32 v[144:145], v[24:25], v[24:25]
	v_pk_mul_f32 v[146:147], v[26:27], v[26:27]
	v_pk_fma_f32 v[136:137], v[132:133], s[84:85], 1.0 op_sel_hi:[1,0,0]
	v_pk_fma_f32 v[138:139], v[134:135], s[84:85], 1.0 op_sel_hi:[1,0,0]
	v_pk_mul_f32 v[144:145], v[144:145], s[80:81] op_sel_hi:[1,0]
	v_pk_mul_f32 v[146:147], v[146:147], s[80:81] op_sel_hi:[1,0]
	v_rcp_f32_e32 v136, v136
	v_rcp_f32_e32 v137, v137
	v_rcp_f32_e32 v138, v138
	v_rcp_f32_e32 v139, v139
	v_exp_f32_e32 v144, v144
	v_exp_f32_e32 v145, v145
	v_exp_f32_e32 v146, v146
	v_exp_f32_e32 v147, v147
	v_pk_fma_f32 v[140:141], v[136:137], s[86:87], v[0:1] op_sel_hi:[1,0,0]
	v_pk_fma_f32 v[142:143], v[138:139], s[86:87], v[0:1] op_sel_hi:[1,0,0]
	v_pk_fma_f32 v[140:141], v[136:137], v[140:141], s[88:89] op_sel_hi:[1,1,0]
	v_pk_fma_f32 v[142:143], v[138:139], v[142:143], s[88:89] op_sel_hi:[1,1,0]
	v_pk_fma_f32 v[140:141], v[136:137], v[140:141], s[82:83] op_sel_hi:[1,1,0]
	v_pk_fma_f32 v[142:143], v[138:139], v[142:143], s[82:83] op_sel_hi:[1,1,0]
	v_pk_fma_f32 v[140:141], v[136:137], v[140:141], s[48:49] op_sel_hi:[1,1,0]
	v_pk_fma_f32 v[142:143], v[138:139], v[142:143], s[48:49] op_sel_hi:[1,1,0]
	v_pk_mul_f32 v[140:141], v[136:137], v[140:141]
	v_pk_mul_f32 v[142:143], v[138:139], v[142:143]
	v_pk_mul_f32 v[140:141], v[140:141], v[144:145]
	v_pk_mul_f32 v[142:143], v[142:143], v[146:147]
	v_max_f32_e32 v24, 0, v24
	v_max_f32_e32 v25, 0, v25
	v_max_f32_e32 v26, 0, v26
	v_max_f32_e32 v27, 0, v27
	v_pk_fma_f32 v[24:25], v[132:133], v[140:141], v[24:25] neg_lo:[1,0,0] neg_hi:[1,0,0]
	v_pk_fma_f32 v[26:27], v[134:135], v[142:143], v[26:27] neg_lo:[1,0,0] neg_hi:[1,0,0]
	v_pk_add_f32 v[2:3], v[2:3], v[24:25]
	v_pk_fma_f32 v[152:153], v[24:25], v[24:25], v[152:153]
	v_pk_add_f32 v[2:3], v[2:3], v[26:27]
	v_pk_fma_f32 v[152:153], v[26:27], v[26:27], v[152:153]
	v_cvt_pk_bf16_f32 v32, v32, v33
	v_cvt_pk_bf16_f32 v33, v34, v35
	v_cvt_pk_bf16_f32 v34, v24, v25
	v_cvt_pk_bf16_f32 v35, v26, v27
	global_store_dwordx4 v148, v[32:35], s[50:51] sc1
	v_and_b32_e32 v132, 0x7fffffff, v16
	v_and_b32_e32 v133, 0x7fffffff, v17
	v_and_b32_e32 v134, 0x7fffffff, v18
	v_and_b32_e32 v135, 0x7fffffff, v19
	v_pk_mul_f32 v[144:145], v[16:17], v[16:17]
	v_pk_mul_f32 v[146:147], v[18:19], v[18:19]
	v_pk_fma_f32 v[136:137], v[132:133], s[84:85], 1.0 op_sel_hi:[1,0,0]
	v_pk_fma_f32 v[138:139], v[134:135], s[84:85], 1.0 op_sel_hi:[1,0,0]
	v_pk_mul_f32 v[144:145], v[144:145], s[80:81] op_sel_hi:[1,0]
	v_pk_mul_f32 v[146:147], v[146:147], s[80:81] op_sel_hi:[1,0]
	v_rcp_f32_e32 v136, v136
	v_rcp_f32_e32 v137, v137
	v_rcp_f32_e32 v138, v138
	v_rcp_f32_e32 v139, v139
	v_exp_f32_e32 v144, v144
	v_exp_f32_e32 v145, v145
	v_exp_f32_e32 v146, v146
	v_exp_f32_e32 v147, v147
	v_pk_fma_f32 v[140:141], v[136:137], s[86:87], v[0:1] op_sel_hi:[1,0,0]
	v_pk_fma_f32 v[142:143], v[138:139], s[86:87], v[0:1] op_sel_hi:[1,0,0]
	v_pk_fma_f32 v[140:141], v[136:137], v[140:141], s[88:89] op_sel_hi:[1,1,0]
	v_pk_fma_f32 v[142:143], v[138:139], v[142:143], s[88:89] op_sel_hi:[1,1,0]
	v_pk_fma_f32 v[140:141], v[136:137], v[140:141], s[82:83] op_sel_hi:[1,1,0]
	v_pk_fma_f32 v[142:143], v[138:139], v[142:143], s[82:83] op_sel_hi:[1,1,0]
	v_pk_fma_f32 v[140:141], v[136:137], v[140:141], s[48:49] op_sel_hi:[1,1,0]
	v_pk_fma_f32 v[142:143], v[138:139], v[142:143], s[48:49] op_sel_hi:[1,1,0]
	v_pk_mul_f32 v[140:141], v[136:137], v[140:141]
	v_pk_mul_f32 v[142:143], v[138:139], v[142:143]
	v_pk_mul_f32 v[140:141], v[140:141], v[144:145]
	v_pk_mul_f32 v[142:143], v[142:143], v[146:147]
	v_max_f32_e32 v16, 0, v16
	v_max_f32_e32 v17, 0, v17
	v_max_f32_e32 v18, 0, v18
	v_max_f32_e32 v19, 0, v19
	v_pk_fma_f32 v[16:17], v[132:133], v[140:141], v[16:17] neg_lo:[1,0,0] neg_hi:[1,0,0]
	v_pk_fma_f32 v[18:19], v[134:135], v[142:143], v[18:19] neg_lo:[1,0,0] neg_hi:[1,0,0]
	v_pk_add_f32 v[2:3], v[2:3], v[16:17]
	v_pk_fma_f32 v[152:153], v[16:17], v[16:17], v[152:153]
	v_pk_add_f32 v[2:3], v[2:3], v[18:19]
	v_pk_fma_f32 v[152:153], v[18:19], v[18:19], v[152:153]
	v_and_b32_e32 v132, 0x7fffffff, v8
	v_and_b32_e32 v133, 0x7fffffff, v9
	v_and_b32_e32 v134, 0x7fffffff, v10
	v_and_b32_e32 v135, 0x7fffffff, v11
	v_pk_mul_f32 v[144:145], v[8:9], v[8:9]
	v_pk_mul_f32 v[146:147], v[10:11], v[10:11]
	v_pk_fma_f32 v[136:137], v[132:133], s[84:85], 1.0 op_sel_hi:[1,0,0]
	v_pk_fma_f32 v[138:139], v[134:135], s[84:85], 1.0 op_sel_hi:[1,0,0]
	v_pk_mul_f32 v[144:145], v[144:145], s[80:81] op_sel_hi:[1,0]
	v_pk_mul_f32 v[146:147], v[146:147], s[80:81] op_sel_hi:[1,0]
	v_rcp_f32_e32 v136, v136
	v_rcp_f32_e32 v137, v137
	v_rcp_f32_e32 v138, v138
	v_rcp_f32_e32 v139, v139
	v_exp_f32_e32 v144, v144
	v_exp_f32_e32 v145, v145
	v_exp_f32_e32 v146, v146
	v_exp_f32_e32 v147, v147
	v_pk_fma_f32 v[140:141], v[136:137], s[86:87], v[0:1] op_sel_hi:[1,0,0]
	v_pk_fma_f32 v[142:143], v[138:139], s[86:87], v[0:1] op_sel_hi:[1,0,0]
	v_pk_fma_f32 v[140:141], v[136:137], v[140:141], s[88:89] op_sel_hi:[1,1,0]
	v_pk_fma_f32 v[142:143], v[138:139], v[142:143], s[88:89] op_sel_hi:[1,1,0]
	v_pk_fma_f32 v[140:141], v[136:137], v[140:141], s[82:83] op_sel_hi:[1,1,0]
	v_pk_fma_f32 v[142:143], v[138:139], v[142:143], s[82:83] op_sel_hi:[1,1,0]
	v_pk_fma_f32 v[140:141], v[136:137], v[140:141], s[48:49] op_sel_hi:[1,1,0]
	v_pk_fma_f32 v[142:143], v[138:139], v[142:143], s[48:49] op_sel_hi:[1,1,0]
	v_pk_mul_f32 v[140:141], v[136:137], v[140:141]
	v_pk_mul_f32 v[142:143], v[138:139], v[142:143]
	v_pk_mul_f32 v[140:141], v[140:141], v[144:145]
	v_pk_mul_f32 v[142:143], v[142:143], v[146:147]
	v_max_f32_e32 v8, 0, v8
	v_max_f32_e32 v9, 0, v9
	v_max_f32_e32 v10, 0, v10
	v_max_f32_e32 v11, 0, v11
	v_pk_fma_f32 v[8:9], v[132:133], v[140:141], v[8:9] neg_lo:[1,0,0] neg_hi:[1,0,0]
	v_pk_fma_f32 v[10:11], v[134:135], v[142:143], v[10:11] neg_lo:[1,0,0] neg_hi:[1,0,0]
	v_pk_add_f32 v[2:3], v[2:3], v[8:9]
	v_pk_fma_f32 v[152:153], v[8:9], v[8:9], v[152:153]
	v_pk_add_f32 v[2:3], v[2:3], v[10:11]
	v_pk_fma_f32 v[152:153], v[10:11], v[10:11], v[152:153]
	v_cvt_pk_bf16_f32 v16, v16, v17
	v_cvt_pk_bf16_f32 v17, v18, v19
	v_cvt_pk_bf16_f32 v18, v8, v9
	v_cvt_pk_bf16_f32 v19, v10, v11
	global_store_dwordx4 v148, v[16:19], s[50:51] offset:256 sc1
	v_add_f32_e32 v2, v2, v3
	v_add_f32_e32 v3, v152, v153
	ds_bpermute_b32 v132, v150, v2
	ds_bpermute_b32 v133, v150, v3
	s_waitcnt lgkmcnt(0)
	v_pk_add_f32 v[2:3], v[2:3], v[132:133]
	ds_bpermute_b32 v132, v151, v2
	ds_bpermute_b32 v133, v151, v3
	s_waitcnt lgkmcnt(0)
	v_pk_add_f32 v[2:3], v[2:3], v[132:133]
	s_and_saveexec_b64 s[46:47], s[38:39]
	global_store_dwordx2 v149, v[2:3], s[66:67]
	s_mov_b64 exec, s[46:47]
	v_add_u32_e32 v148, s81, v148
	v_add_u32_e32 v149, 0x400, v149
	v_and_b32_e32 v132, 0x7fffffff, v28
	v_and_b32_e32 v133, 0x7fffffff, v29
	v_and_b32_e32 v134, 0x7fffffff, v30
	v_and_b32_e32 v135, 0x7fffffff, v31
	v_pk_mul_f32 v[144:145], v[28:29], v[28:29]
	v_pk_mul_f32 v[146:147], v[30:31], v[30:31]
	v_pk_fma_f32 v[136:137], v[132:133], s[84:85], 1.0 op_sel_hi:[1,0,0]
	v_pk_fma_f32 v[138:139], v[134:135], s[84:85], 1.0 op_sel_hi:[1,0,0]
	v_pk_mul_f32 v[144:145], v[144:145], s[80:81] op_sel_hi:[1,0]
	v_pk_mul_f32 v[146:147], v[146:147], s[80:81] op_sel_hi:[1,0]
	v_rcp_f32_e32 v136, v136
	v_rcp_f32_e32 v137, v137
	v_rcp_f32_e32 v138, v138
	v_rcp_f32_e32 v139, v139
	v_exp_f32_e32 v144, v144
	v_exp_f32_e32 v145, v145
	v_exp_f32_e32 v146, v146
	v_exp_f32_e32 v147, v147
	v_pk_fma_f32 v[140:141], v[136:137], s[86:87], v[0:1] op_sel_hi:[1,0,0]
	v_pk_fma_f32 v[142:143], v[138:139], s[86:87], v[0:1] op_sel_hi:[1,0,0]
	v_pk_fma_f32 v[140:141], v[136:137], v[140:141], s[88:89] op_sel_hi:[1,1,0]
	v_pk_fma_f32 v[142:143], v[138:139], v[142:143], s[88:89] op_sel_hi:[1,1,0]
	v_pk_fma_f32 v[140:141], v[136:137], v[140:141], s[82:83] op_sel_hi:[1,1,0]
	v_pk_fma_f32 v[142:143], v[138:139], v[142:143], s[82:83] op_sel_hi:[1,1,0]
	v_pk_fma_f32 v[140:141], v[136:137], v[140:141], s[48:49] op_sel_hi:[1,1,0]
	v_pk_fma_f32 v[142:143], v[138:139], v[142:143], s[48:49] op_sel_hi:[1,1,0]
	v_pk_mul_f32 v[140:141], v[136:137], v[140:141]
	v_pk_mul_f32 v[142:143], v[138:139], v[142:143]
	v_pk_mul_f32 v[140:141], v[140:141], v[144:145]
	v_pk_mul_f32 v[142:143], v[142:143], v[146:147]
	v_max_f32_e32 v28, 0, v28
	v_max_f32_e32 v29, 0, v29
	v_max_f32_e32 v30, 0, v30
	v_max_f32_e32 v31, 0, v31
	v_pk_fma_f32 v[28:29], v[132:133], v[140:141], v[28:29] neg_lo:[1,0,0] neg_hi:[1,0,0]
	v_pk_fma_f32 v[30:31], v[134:135], v[142:143], v[30:31] neg_lo:[1,0,0] neg_hi:[1,0,0]
	v_pk_add_f32 v[2:3], v[28:29], v[30:31]
	v_pk_mul_f32 v[152:153], v[28:29], v[28:29]
	v_pk_fma_f32 v[152:153], v[30:31], v[30:31], v[152:153]
	v_and_b32_e32 v132, 0x7fffffff, v20
	v_and_b32_e32 v133, 0x7fffffff, v21
	v_and_b32_e32 v134, 0x7fffffff, v22
	v_and_b32_e32 v135, 0x7fffffff, v23
	v_pk_mul_f32 v[144:145], v[20:21], v[20:21]
	v_pk_mul_f32 v[146:147], v[22:23], v[22:23]
	v_pk_fma_f32 v[136:137], v[132:133], s[84:85], 1.0 op_sel_hi:[1,0,0]
	v_pk_fma_f32 v[138:139], v[134:135], s[84:85], 1.0 op_sel_hi:[1,0,0]
	v_pk_mul_f32 v[144:145], v[144:145], s[80:81] op_sel_hi:[1,0]
	v_pk_mul_f32 v[146:147], v[146:147], s[80:81] op_sel_hi:[1,0]
	v_rcp_f32_e32 v136, v136
	v_rcp_f32_e32 v137, v137
	v_rcp_f32_e32 v138, v138
	v_rcp_f32_e32 v139, v139
	v_exp_f32_e32 v144, v144
	v_exp_f32_e32 v145, v145
	v_exp_f32_e32 v146, v146
	v_exp_f32_e32 v147, v147
	v_pk_fma_f32 v[140:141], v[136:137], s[86:87], v[0:1] op_sel_hi:[1,0,0]
	v_pk_fma_f32 v[142:143], v[138:139], s[86:87], v[0:1] op_sel_hi:[1,0,0]
	v_pk_fma_f32 v[140:141], v[136:137], v[140:141], s[88:89] op_sel_hi:[1,1,0]
	v_pk_fma_f32 v[142:143], v[138:139], v[142:143], s[88:89] op_sel_hi:[1,1,0]
	v_pk_fma_f32 v[140:141], v[136:137], v[140:141], s[82:83] op_sel_hi:[1,1,0]
	v_pk_fma_f32 v[142:143], v[138:139], v[142:143], s[82:83] op_sel_hi:[1,1,0]
	v_pk_fma_f32 v[140:141], v[136:137], v[140:141], s[48:49] op_sel_hi:[1,1,0]
	v_pk_fma_f32 v[142:143], v[138:139], v[142:143], s[48:49] op_sel_hi:[1,1,0]
	v_pk_mul_f32 v[140:141], v[136:137], v[140:141]
	v_pk_mul_f32 v[142:143], v[138:139], v[142:143]
	v_pk_mul_f32 v[140:141], v[140:141], v[144:145]
	v_pk_mul_f32 v[142:143], v[142:143], v[146:147]
	v_max_f32_e32 v20, 0, v20
	v_max_f32_e32 v21, 0, v21
	v_max_f32_e32 v22, 0, v22
	v_max_f32_e32 v23, 0, v23
	v_pk_fma_f32 v[20:21], v[132:133], v[140:141], v[20:21] neg_lo:[1,0,0] neg_hi:[1,0,0]
	v_pk_fma_f32 v[22:23], v[134:135], v[142:143], v[22:23] neg_lo:[1,0,0] neg_hi:[1,0,0]
	v_pk_add_f32 v[2:3], v[2:3], v[20:21]
	v_pk_fma_f32 v[152:153], v[20:21], v[20:21], v[152:153]
	v_pk_add_f32 v[2:3], v[2:3], v[22:23]
	v_pk_fma_f32 v[152:153], v[22:23], v[22:23], v[152:153]
	v_cvt_pk_bf16_f32 v28, v28, v29
	v_cvt_pk_bf16_f32 v29, v30, v31
	v_cvt_pk_bf16_f32 v30, v20, v21
	v_cvt_pk_bf16_f32 v31, v22, v23
	global_store_dwordx4 v148, v[28:31], s[50:51] sc1
	v_and_b32_e32 v132, 0x7fffffff, v12
	v_and_b32_e32 v133, 0x7fffffff, v13
	v_and_b32_e32 v134, 0x7fffffff, v14
	v_and_b32_e32 v135, 0x7fffffff, v15
	v_pk_mul_f32 v[144:145], v[12:13], v[12:13]
	v_pk_mul_f32 v[146:147], v[14:15], v[14:15]
	v_pk_fma_f32 v[136:137], v[132:133], s[84:85], 1.0 op_sel_hi:[1,0,0]
	v_pk_fma_f32 v[138:139], v[134:135], s[84:85], 1.0 op_sel_hi:[1,0,0]
	v_pk_mul_f32 v[144:145], v[144:145], s[80:81] op_sel_hi:[1,0]
	v_pk_mul_f32 v[146:147], v[146:147], s[80:81] op_sel_hi:[1,0]
	v_rcp_f32_e32 v136, v136
	v_rcp_f32_e32 v137, v137
	v_rcp_f32_e32 v138, v138
	v_rcp_f32_e32 v139, v139
	v_exp_f32_e32 v144, v144
	v_exp_f32_e32 v145, v145
	v_exp_f32_e32 v146, v146
	v_exp_f32_e32 v147, v147
	v_pk_fma_f32 v[140:141], v[136:137], s[86:87], v[0:1] op_sel_hi:[1,0,0]
	v_pk_fma_f32 v[142:143], v[138:139], s[86:87], v[0:1] op_sel_hi:[1,0,0]
	v_pk_fma_f32 v[140:141], v[136:137], v[140:141], s[88:89] op_sel_hi:[1,1,0]
	v_pk_fma_f32 v[142:143], v[138:139], v[142:143], s[88:89] op_sel_hi:[1,1,0]
	v_pk_fma_f32 v[140:141], v[136:137], v[140:141], s[82:83] op_sel_hi:[1,1,0]
	v_pk_fma_f32 v[142:143], v[138:139], v[142:143], s[82:83] op_sel_hi:[1,1,0]
	v_pk_fma_f32 v[140:141], v[136:137], v[140:141], s[48:49] op_sel_hi:[1,1,0]
	v_pk_fma_f32 v[142:143], v[138:139], v[142:143], s[48:49] op_sel_hi:[1,1,0]
	v_pk_mul_f32 v[140:141], v[136:137], v[140:141]
	v_pk_mul_f32 v[142:143], v[138:139], v[142:143]
	v_pk_mul_f32 v[140:141], v[140:141], v[144:145]
	v_pk_mul_f32 v[142:143], v[142:143], v[146:147]
	v_max_f32_e32 v12, 0, v12
	v_max_f32_e32 v13, 0, v13
	v_max_f32_e32 v14, 0, v14
	v_max_f32_e32 v15, 0, v15
	v_pk_fma_f32 v[12:13], v[132:133], v[140:141], v[12:13] neg_lo:[1,0,0] neg_hi:[1,0,0]
	v_pk_fma_f32 v[14:15], v[134:135], v[142:143], v[14:15] neg_lo:[1,0,0] neg_hi:[1,0,0]
	v_pk_add_f32 v[2:3], v[2:3], v[12:13]
	v_pk_fma_f32 v[152:153], v[12:13], v[12:13], v[152:153]
	v_pk_add_f32 v[2:3], v[2:3], v[14:15]
	v_pk_fma_f32 v[152:153], v[14:15], v[14:15], v[152:153]
	v_and_b32_e32 v132, 0x7fffffff, v4
	v_and_b32_e32 v133, 0x7fffffff, v5
	v_and_b32_e32 v134, 0x7fffffff, v6
	v_and_b32_e32 v135, 0x7fffffff, v7
	v_pk_mul_f32 v[144:145], v[4:5], v[4:5]
	v_pk_mul_f32 v[146:147], v[6:7], v[6:7]
	v_pk_fma_f32 v[136:137], v[132:133], s[84:85], 1.0 op_sel_hi:[1,0,0]
	v_pk_fma_f32 v[138:139], v[134:135], s[84:85], 1.0 op_sel_hi:[1,0,0]
	v_pk_mul_f32 v[144:145], v[144:145], s[80:81] op_sel_hi:[1,0]
	v_pk_mul_f32 v[146:147], v[146:147], s[80:81] op_sel_hi:[1,0]
	v_rcp_f32_e32 v136, v136
	v_rcp_f32_e32 v137, v137
	v_rcp_f32_e32 v138, v138
	v_rcp_f32_e32 v139, v139
	v_exp_f32_e32 v144, v144
	v_exp_f32_e32 v145, v145
	v_exp_f32_e32 v146, v146
	v_exp_f32_e32 v147, v147
	v_pk_fma_f32 v[140:141], v[136:137], s[86:87], v[0:1] op_sel_hi:[1,0,0]
	v_pk_fma_f32 v[142:143], v[138:139], s[86:87], v[0:1] op_sel_hi:[1,0,0]
	v_pk_fma_f32 v[140:141], v[136:137], v[140:141], s[88:89] op_sel_hi:[1,1,0]
	v_pk_fma_f32 v[142:143], v[138:139], v[142:143], s[88:89] op_sel_hi:[1,1,0]
	v_pk_fma_f32 v[140:141], v[136:137], v[140:141], s[82:83] op_sel_hi:[1,1,0]
	v_pk_fma_f32 v[142:143], v[138:139], v[142:143], s[82:83] op_sel_hi:[1,1,0]
	v_pk_fma_f32 v[140:141], v[136:137], v[140:141], s[48:49] op_sel_hi:[1,1,0]
	v_pk_fma_f32 v[142:143], v[138:139], v[142:143], s[48:49] op_sel_hi:[1,1,0]
	v_pk_mul_f32 v[140:141], v[136:137], v[140:141]
	v_pk_mul_f32 v[142:143], v[138:139], v[142:143]
	v_pk_mul_f32 v[140:141], v[140:141], v[144:145]
	v_pk_mul_f32 v[142:143], v[142:143], v[146:147]
	v_max_f32_e32 v4, 0, v4
	v_max_f32_e32 v5, 0, v5
	v_max_f32_e32 v6, 0, v6
	v_max_f32_e32 v7, 0, v7
	v_pk_fma_f32 v[4:5], v[132:133], v[140:141], v[4:5] neg_lo:[1,0,0] neg_hi:[1,0,0]
	v_pk_fma_f32 v[6:7], v[134:135], v[142:143], v[6:7] neg_lo:[1,0,0] neg_hi:[1,0,0]
	v_pk_add_f32 v[2:3], v[2:3], v[4:5]
	v_pk_fma_f32 v[152:153], v[4:5], v[4:5], v[152:153]
	v_pk_add_f32 v[2:3], v[2:3], v[6:7]
	v_pk_fma_f32 v[152:153], v[6:7], v[6:7], v[152:153]
	v_cvt_pk_bf16_f32 v12, v12, v13
	v_cvt_pk_bf16_f32 v13, v14, v15
	v_cvt_pk_bf16_f32 v14, v4, v5
	v_cvt_pk_bf16_f32 v15, v6, v7
	global_store_dwordx4 v148, v[12:15], s[50:51] offset:256 sc1
	v_add_f32_e32 v2, v2, v3
	v_add_f32_e32 v3, v152, v153
	ds_bpermute_b32 v132, v150, v2
	ds_bpermute_b32 v133, v150, v3
	s_waitcnt lgkmcnt(0)
	v_pk_add_f32 v[2:3], v[2:3], v[132:133]
	ds_bpermute_b32 v132, v151, v2
	ds_bpermute_b32 v133, v151, v3
	s_waitcnt lgkmcnt(0)
	v_pk_add_f32 v[2:3], v[2:3], v[132:133]
	s_and_saveexec_b64 s[46:47], s[38:39]
	global_store_dwordx2 v149, v[2:3], s[66:67]
	s_mov_b64 exec, s[46:47]
	s_branch .LBB0_326
.Lepi_gelu6:
	v_and_b32_e32 v132, 0x7fffffff, v128
	v_and_b32_e32 v133, 0x7fffffff, v129
	v_and_b32_e32 v134, 0x7fffffff, v130
	v_and_b32_e32 v135, 0x7fffffff, v131
	v_pk_mul_f32 v[144:145], v[128:129], v[128:129]
	v_pk_mul_f32 v[146:147], v[130:131], v[130:131]
	v_pk_fma_f32 v[136:137], v[132:133], s[84:85], 1.0 op_sel_hi:[1,0,0]
	v_pk_fma_f32 v[138:139], v[134:135], s[84:85], 1.0 op_sel_hi:[1,0,0]
	v_pk_mul_f32 v[144:145], v[144:145], s[80:81] op_sel_hi:[1,0]
	v_pk_mul_f32 v[146:147], v[146:147], s[80:81] op_sel_hi:[1,0]
	v_rcp_f32_e32 v136, v136
	v_rcp_f32_e32 v137, v137
	v_rcp_f32_e32 v138, v138
	v_rcp_f32_e32 v139, v139
	v_exp_f32_e32 v144, v144
	v_exp_f32_e32 v145, v145
	v_exp_f32_e32 v146, v146
	v_exp_f32_e32 v147, v147
	v_pk_fma_f32 v[140:141], v[136:137], s[86:87], v[0:1] op_sel_hi:[1,0,0]
	v_pk_fma_f32 v[142:143], v[138:139], s[86:87], v[0:1] op_sel_hi:[1,0,0]
	v_pk_fma_f32 v[140:141], v[136:137], v[140:141], s[88:89] op_sel_hi:[1,1,0]
	v_pk_fma_f32 v[142:143], v[138:139], v[142:143], s[88:89] op_sel_hi:[1,1,0]
	v_pk_fma_f32 v[140:141], v[136:137], v[140:141], s[82:83] op_sel_hi:[1,1,0]
	v_pk_fma_f32 v[142:143], v[138:139], v[142:143], s[82:83] op_sel_hi:[1,1,0]
	v_pk_fma_f32 v[140:141], v[136:137], v[140:141], s[48:49] op_sel_hi:[1,1,0]
	v_pk_fma_f32 v[142:143], v[138:139], v[142:143], s[48:49] op_sel_hi:[1,1,0]
	v_pk_mul_f32 v[140:141], v[136:137], v[140:141]
	v_pk_mul_f32 v[142:143], v[138:139], v[142:143]
	v_pk_mul_f32 v[140:141], v[140:141], v[144:145]
	v_pk_mul_f32 v[142:143], v[142:143], v[146:147]
	v_max_f32_e32 v128, 0, v128
	v_max_f32_e32 v129, 0, v129
	v_max_f32_e32 v130, 0, v130
	v_max_f32_e32 v131, 0, v131
	v_pk_fma_f32 v[128:129], v[132:133], v[140:141], v[128:129] neg_lo:[1,0,0] neg_hi:[1,0,0]
	v_pk_fma_f32 v[130:131], v[134:135], v[142:143], v[130:131] neg_lo:[1,0,0] neg_hi:[1,0,0]
	v_and_b32_e32 v132, 0x7fffffff, v120
	v_and_b32_e32 v133, 0x7fffffff, v121
	v_and_b32_e32 v134, 0x7fffffff, v122
	v_and_b32_e32 v135, 0x7fffffff, v123
	v_pk_mul_f32 v[144:145], v[120:121], v[120:121]
	v_pk_mul_f32 v[146:147], v[122:123], v[122:123]
	v_pk_fma_f32 v[136:137], v[132:133], s[84:85], 1.0 op_sel_hi:[1,0,0]
	v_pk_fma_f32 v[138:139], v[134:135], s[84:85], 1.0 op_sel_hi:[1,0,0]
	v_pk_mul_f32 v[144:145], v[144:145], s[80:81] op_sel_hi:[1,0]
	v_pk_mul_f32 v[146:147], v[146:147], s[80:81] op_sel_hi:[1,0]
	v_rcp_f32_e32 v136, v136
	v_rcp_f32_e32 v137, v137
	v_rcp_f32_e32 v138, v138
	v_rcp_f32_e32 v139, v139
	v_exp_f32_e32 v144, v144
	v_exp_f32_e32 v145, v145
	v_exp_f32_e32 v146, v146
	v_exp_f32_e32 v147, v147
	v_pk_fma_f32 v[140:141], v[136:137], s[86:87], v[0:1] op_sel_hi:[1,0,0]
	v_pk_fma_f32 v[142:143], v[138:139], s[86:87], v[0:1] op_sel_hi:[1,0,0]
	v_pk_fma_f32 v[140:141], v[136:137], v[140:141], s[88:89] op_sel_hi:[1,1,0]
	v_pk_fma_f32 v[142:143], v[138:139], v[142:143], s[88:89] op_sel_hi:[1,1,0]
	v_pk_fma_f32 v[140:141], v[136:137], v[140:141], s[82:83] op_sel_hi:[1,1,0]
	v_pk_fma_f32 v[142:143], v[138:139], v[142:143], s[82:83] op_sel_hi:[1,1,0]
	v_pk_fma_f32 v[140:141], v[136:137], v[140:141], s[48:49] op_sel_hi:[1,1,0]
	v_pk_fma_f32 v[142:143], v[138:139], v[142:143], s[48:49] op_sel_hi:[1,1,0]
	v_pk_mul_f32 v[140:141], v[136:137], v[140:141]
	v_pk_mul_f32 v[142:143], v[138:139], v[142:143]
	v_pk_mul_f32 v[140:141], v[140:141], v[144:145]
	v_pk_mul_f32 v[142:143], v[142:143], v[146:147]
	v_max_f32_e32 v120, 0, v120
	v_max_f32_e32 v121, 0, v121
	v_max_f32_e32 v122, 0, v122
	v_max_f32_e32 v123, 0, v123
	v_pk_fma_f32 v[120:121], v[132:133], v[140:141], v[120:121] neg_lo:[1,0,0] neg_hi:[1,0,0]
	v_pk_fma_f32 v[122:123], v[134:135], v[142:143], v[122:123] neg_lo:[1,0,0] neg_hi:[1,0,0]
	v_cvt_pk_bf16_f32 v128, v128, v129
	v_cvt_pk_bf16_f32 v129, v130, v131
	v_cvt_pk_bf16_f32 v130, v120, v121
	v_cvt_pk_bf16_f32 v131, v122, v123
	global_store_dwordx4 v148, v[128:131], s[50:51] sc1
	v_and_b32_e32 v132, 0x7fffffff, v112
	v_and_b32_e32 v133, 0x7fffffff, v113
	v_and_b32_e32 v134, 0x7fffffff, v114
	v_and_b32_e32 v135, 0x7fffffff, v115
	v_pk_mul_f32 v[144:145], v[112:113], v[112:113]
	v_pk_mul_f32 v[146:147], v[114:115], v[114:115]
	v_pk_fma_f32 v[136:137], v[132:133], s[84:85], 1.0 op_sel_hi:[1,0,0]
	v_pk_fma_f32 v[138:139], v[134:135], s[84:85], 1.0 op_sel_hi:[1,0,0]
	v_pk_mul_f32 v[144:145], v[144:145], s[80:81] op_sel_hi:[1,0]
	v_pk_mul_f32 v[146:147], v[146:147], s[80:81] op_sel_hi:[1,0]
	v_rcp_f32_e32 v136, v136
	v_rcp_f32_e32 v137, v137
	v_rcp_f32_e32 v138, v138
	v_rcp_f32_e32 v139, v139
	v_exp_f32_e32 v144, v144
	v_exp_f32_e32 v145, v145
	v_exp_f32_e32 v146, v146
	v_exp_f32_e32 v147, v147
	v_pk_fma_f32 v[140:141], v[136:137], s[86:87], v[0:1] op_sel_hi:[1,0,0]
	v_pk_fma_f32 v[142:143], v[138:139], s[86:87], v[0:1] op_sel_hi:[1,0,0]
	v_pk_fma_f32 v[140:141], v[136:137], v[140:141], s[88:89] op_sel_hi:[1,1,0]
	v_pk_fma_f32 v[142:143], v[138:139], v[142:143], s[88:89] op_sel_hi:[1,1,0]
	v_pk_fma_f32 v[140:141], v[136:137], v[140:141], s[82:83] op_sel_hi:[1,1,0]
	v_pk_fma_f32 v[142:143], v[138:139], v[142:143], s[82:83] op_sel_hi:[1,1,0]
	v_pk_fma_f32 v[140:141], v[136:137], v[140:141], s[48:49] op_sel_hi:[1,1,0]
	v_pk_fma_f32 v[142:143], v[138:139], v[142:143], s[48:49] op_sel_hi:[1,1,0]
	v_pk_mul_f32 v[140:141], v[136:137], v[140:141]
	v_pk_mul_f32 v[142:143], v[138:139], v[142:143]
	v_pk_mul_f32 v[140:141], v[140:141], v[144:145]
	v_pk_mul_f32 v[142:143], v[142:143], v[146:147]
	v_max_f32_e32 v112, 0, v112
	v_max_f32_e32 v113, 0, v113
	v_max_f32_e32 v114, 0, v114
	v_max_f32_e32 v115, 0, v115
	v_pk_fma_f32 v[112:113], v[132:133], v[140:141], v[112:113] neg_lo:[1,0,0] neg_hi:[1,0,0]
	v_pk_fma_f32 v[114:115], v[134:135], v[142:143], v[114:115] neg_lo:[1,0,0] neg_hi:[1,0,0]
	v_and_b32_e32 v132, 0x7fffffff, v104
	v_and_b32_e32 v133, 0x7fffffff, v105
	v_and_b32_e32 v134, 0x7fffffff, v106
	v_and_b32_e32 v135, 0x7fffffff, v107
	v_pk_mul_f32 v[144:145], v[104:105], v[104:105]
	v_pk_mul_f32 v[146:147], v[106:107], v[106:107]
	v_pk_fma_f32 v[136:137], v[132:133], s[84:85], 1.0 op_sel_hi:[1,0,0]
	v_pk_fma_f32 v[138:139], v[134:135], s[84:85], 1.0 op_sel_hi:[1,0,0]
	v_pk_mul_f32 v[144:145], v[144:145], s[80:81] op_sel_hi:[1,0]
	v_pk_mul_f32 v[146:147], v[146:147], s[80:81] op_sel_hi:[1,0]
	v_rcp_f32_e32 v136, v136
	v_rcp_f32_e32 v137, v137
	v_rcp_f32_e32 v138, v138
	v_rcp_f32_e32 v139, v139
	v_exp_f32_e32 v144, v144
	v_exp_f32_e32 v145, v145
	v_exp_f32_e32 v146, v146
	v_exp_f32_e32 v147, v147
	v_pk_fma_f32 v[140:141], v[136:137], s[86:87], v[0:1] op_sel_hi:[1,0,0]
	v_pk_fma_f32 v[142:143], v[138:139], s[86:87], v[0:1] op_sel_hi:[1,0,0]
	v_pk_fma_f32 v[140:141], v[136:137], v[140:141], s[88:89] op_sel_hi:[1,1,0]
	v_pk_fma_f32 v[142:143], v[138:139], v[142:143], s[88:89] op_sel_hi:[1,1,0]
	v_pk_fma_f32 v[140:141], v[136:137], v[140:141], s[82:83] op_sel_hi:[1,1,0]
	v_pk_fma_f32 v[142:143], v[138:139], v[142:143], s[82:83] op_sel_hi:[1,1,0]
	v_pk_fma_f32 v[140:141], v[136:137], v[140:141], s[48:49] op_sel_hi:[1,1,0]
	v_pk_fma_f32 v[142:143], v[138:139], v[142:143], s[48:49] op_sel_hi:[1,1,0]
	v_pk_mul_f32 v[140:141], v[136:137], v[140:141]
	v_pk_mul_f32 v[142:143], v[138:139], v[142:143]
	v_pk_mul_f32 v[140:141], v[140:141], v[144:145]
	v_pk_mul_f32 v[142:143], v[142:143], v[146:147]
	v_max_f32_e32 v104, 0, v104
	v_max_f32_e32 v105, 0, v105
	v_max_f32_e32 v106, 0, v106
	v_max_f32_e32 v107, 0, v107
	v_pk_fma_f32 v[104:105], v[132:133], v[140:141], v[104:105] neg_lo:[1,0,0] neg_hi:[1,0,0]
	v_pk_fma_f32 v[106:107], v[134:135], v[142:143], v[106:107] neg_lo:[1,0,0] neg_hi:[1,0,0]
	v_cvt_pk_bf16_f32 v112, v112, v113
	v_cvt_pk_bf16_f32 v113, v114, v115
	v_cvt_pk_bf16_f32 v114, v104, v105
	v_cvt_pk_bf16_f32 v115, v106, v107
	global_store_dwordx4 v148, v[112:115], s[50:51] offset:256 sc1
	v_add_u32_e32 v148, s81, v148
	v_and_b32_e32 v132, 0x7fffffff, v124
	v_and_b32_e32 v133, 0x7fffffff, v125
	v_and_b32_e32 v134, 0x7fffffff, v126
	v_and_b32_e32 v135, 0x7fffffff, v127
	v_pk_mul_f32 v[144:145], v[124:125], v[124:125]
	v_pk_mul_f32 v[146:147], v[126:127], v[126:127]
	v_pk_fma_f32 v[136:137], v[132:133], s[84:85], 1.0 op_sel_hi:[1,0,0]
	v_pk_fma_f32 v[138:139], v[134:135], s[84:85], 1.0 op_sel_hi:[1,0,0]
	v_pk_mul_f32 v[144:145], v[144:145], s[80:81] op_sel_hi:[1,0]
	v_pk_mul_f32 v[146:147], v[146:147], s[80:81] op_sel_hi:[1,0]
	v_rcp_f32_e32 v136, v136
	v_rcp_f32_e32 v137, v137
	v_rcp_f32_e32 v138, v138
	v_rcp_f32_e32 v139, v139
	v_exp_f32_e32 v144, v144
	v_exp_f32_e32 v145, v145
	v_exp_f32_e32 v146, v146
	v_exp_f32_e32 v147, v147
	v_pk_fma_f32 v[140:141], v[136:137], s[86:87], v[0:1] op_sel_hi:[1,0,0]
	v_pk_fma_f32 v[142:143], v[138:139], s[86:87], v[0:1] op_sel_hi:[1,0,0]
	v_pk_fma_f32 v[140:141], v[136:137], v[140:141], s[88:89] op_sel_hi:[1,1,0]
	v_pk_fma_f32 v[142:143], v[138:139], v[142:143], s[88:89] op_sel_hi:[1,1,0]
	v_pk_fma_f32 v[140:141], v[136:137], v[140:141], s[82:83] op_sel_hi:[1,1,0]
	v_pk_fma_f32 v[142:143], v[138:139], v[142:143], s[82:83] op_sel_hi:[1,1,0]
	v_pk_fma_f32 v[140:141], v[136:137], v[140:141], s[48:49] op_sel_hi:[1,1,0]
	v_pk_fma_f32 v[142:143], v[138:139], v[142:143], s[48:49] op_sel_hi:[1,1,0]
	v_pk_mul_f32 v[140:141], v[136:137], v[140:141]
	v_pk_mul_f32 v[142:143], v[138:139], v[142:143]
	v_pk_mul_f32 v[140:141], v[140:141], v[144:145]
	v_pk_mul_f32 v[142:143], v[142:143], v[146:147]
	v_max_f32_e32 v124, 0, v124
	v_max_f32_e32 v125, 0, v125
	v_max_f32_e32 v126, 0, v126
	v_max_f32_e32 v127, 0, v127
	v_pk_fma_f32 v[124:125], v[132:133], v[140:141], v[124:125] neg_lo:[1,0,0] neg_hi:[1,0,0]
	v_pk_fma_f32 v[126:127], v[134:135], v[142:143], v[126:127] neg_lo:[1,0,0] neg_hi:[1,0,0]
	v_and_b32_e32 v132, 0x7fffffff, v116
	v_and_b32_e32 v133, 0x7fffffff, v117
	v_and_b32_e32 v134, 0x7fffffff, v118
	v_and_b32_e32 v135, 0x7fffffff, v119
	v_pk_mul_f32 v[144:145], v[116:117], v[116:117]
	v_pk_mul_f32 v[146:147], v[118:119], v[118:119]
	v_pk_fma_f32 v[136:137], v[132:133], s[84:85], 1.0 op_sel_hi:[1,0,0]
	v_pk_fma_f32 v[138:139], v[134:135], s[84:85], 1.0 op_sel_hi:[1,0,0]
	v_pk_mul_f32 v[144:145], v[144:145], s[80:81] op_sel_hi:[1,0]
	v_pk_mul_f32 v[146:147], v[146:147], s[80:81] op_sel_hi:[1,0]
	v_rcp_f32_e32 v136, v136
	v_rcp_f32_e32 v137, v137
	v_rcp_f32_e32 v138, v138
	v_rcp_f32_e32 v139, v139
	v_exp_f32_e32 v144, v144
	v_exp_f32_e32 v145, v145
	v_exp_f32_e32 v146, v146
	v_exp_f32_e32 v147, v147
	v_pk_fma_f32 v[140:141], v[136:137], s[86:87], v[0:1] op_sel_hi:[1,0,0]
	v_pk_fma_f32 v[142:143], v[138:139], s[86:87], v[0:1] op_sel_hi:[1,0,0]
	v_pk_fma_f32 v[140:141], v[136:137], v[140:141], s[88:89] op_sel_hi:[1,1,0]
	v_pk_fma_f32 v[142:143], v[138:139], v[142:143], s[88:89] op_sel_hi:[1,1,0]
	v_pk_fma_f32 v[140:141], v[136:137], v[140:141], s[82:83] op_sel_hi:[1,1,0]
	v_pk_fma_f32 v[142:143], v[138:139], v[142:143], s[82:83] op_sel_hi:[1,1,0]
	v_pk_fma_f32 v[140:141], v[136:137], v[140:141], s[48:49] op_sel_hi:[1,1,0]
	v_pk_fma_f32 v[142:143], v[138:139], v[142:143], s[48:49] op_sel_hi:[1,1,0]
	v_pk_mul_f32 v[140:141], v[136:137], v[140:141]
	v_pk_mul_f32 v[142:143], v[138:139], v[142:143]
	v_pk_mul_f32 v[140:141], v[140:141], v[144:145]
	v_pk_mul_f32 v[142:143], v[142:143], v[146:147]
	v_max_f32_e32 v116, 0, v116
	v_max_f32_e32 v117, 0, v117
	v_max_f32_e32 v118, 0, v118
	v_max_f32_e32 v119, 0, v119
	v_pk_fma_f32 v[116:117], v[132:133], v[140:141], v[116:117] neg_lo:[1,0,0] neg_hi:[1,0,0]
	v_pk_fma_f32 v[118:119], v[134:135], v[142:143], v[118:119] neg_lo:[1,0,0] neg_hi:[1,0,0]
	v_cvt_pk_bf16_f32 v124, v124, v125
	v_cvt_pk_bf16_f32 v125, v126, v127
	v_cvt_pk_bf16_f32 v126, v116, v117
	v_cvt_pk_bf16_f32 v127, v118, v119
	global_store_dwordx4 v148, v[124:127], s[50:51] sc1
	v_and_b32_e32 v132, 0x7fffffff, v108
	v_and_b32_e32 v133, 0x7fffffff, v109
	v_and_b32_e32 v134, 0x7fffffff, v110
	v_and_b32_e32 v135, 0x7fffffff, v111
	v_pk_mul_f32 v[144:145], v[108:109], v[108:109]
	v_pk_mul_f32 v[146:147], v[110:111], v[110:111]
	v_pk_fma_f32 v[136:137], v[132:133], s[84:85], 1.0 op_sel_hi:[1,0,0]
	v_pk_fma_f32 v[138:139], v[134:135], s[84:85], 1.0 op_sel_hi:[1,0,0]
	v_pk_mul_f32 v[144:145], v[144:145], s[80:81] op_sel_hi:[1,0]
	v_pk_mul_f32 v[146:147], v[146:147], s[80:81] op_sel_hi:[1,0]
	v_rcp_f32_e32 v136, v136
	v_rcp_f32_e32 v137, v137
	v_rcp_f32_e32 v138, v138
	v_rcp_f32_e32 v139, v139
	v_exp_f32_e32 v144, v144
	v_exp_f32_e32 v145, v145
	v_exp_f32_e32 v146, v146
	v_exp_f32_e32 v147, v147
	v_pk_fma_f32 v[140:141], v[136:137], s[86:87], v[0:1] op_sel_hi:[1,0,0]
	v_pk_fma_f32 v[142:143], v[138:139], s[86:87], v[0:1] op_sel_hi:[1,0,0]
	v_pk_fma_f32 v[140:141], v[136:137], v[140:141], s[88:89] op_sel_hi:[1,1,0]
	v_pk_fma_f32 v[142:143], v[138:139], v[142:143], s[88:89] op_sel_hi:[1,1,0]
	v_pk_fma_f32 v[140:141], v[136:137], v[140:141], s[82:83] op_sel_hi:[1,1,0]
	v_pk_fma_f32 v[142:143], v[138:139], v[142:143], s[82:83] op_sel_hi:[1,1,0]
	v_pk_fma_f32 v[140:141], v[136:137], v[140:141], s[48:49] op_sel_hi:[1,1,0]
	v_pk_fma_f32 v[142:143], v[138:139], v[142:143], s[48:49] op_sel_hi:[1,1,0]
	v_pk_mul_f32 v[140:141], v[136:137], v[140:141]
	v_pk_mul_f32 v[142:143], v[138:139], v[142:143]
	v_pk_mul_f32 v[140:141], v[140:141], v[144:145]
	v_pk_mul_f32 v[142:143], v[142:143], v[146:147]
	v_max_f32_e32 v108, 0, v108
	v_max_f32_e32 v109, 0, v109
	v_max_f32_e32 v110, 0, v110
	v_max_f32_e32 v111, 0, v111
	v_pk_fma_f32 v[108:109], v[132:133], v[140:141], v[108:109] neg_lo:[1,0,0] neg_hi:[1,0,0]
	v_pk_fma_f32 v[110:111], v[134:135], v[142:143], v[110:111] neg_lo:[1,0,0] neg_hi:[1,0,0]
	v_and_b32_e32 v132, 0x7fffffff, v100
	v_and_b32_e32 v133, 0x7fffffff, v101
	v_and_b32_e32 v134, 0x7fffffff, v102
	v_and_b32_e32 v135, 0x7fffffff, v103
	v_pk_mul_f32 v[144:145], v[100:101], v[100:101]
	v_pk_mul_f32 v[146:147], v[102:103], v[102:103]
	v_pk_fma_f32 v[136:137], v[132:133], s[84:85], 1.0 op_sel_hi:[1,0,0]
	v_pk_fma_f32 v[138:139], v[134:135], s[84:85], 1.0 op_sel_hi:[1,0,0]
	v_pk_mul_f32 v[144:145], v[144:145], s[80:81] op_sel_hi:[1,0]
	v_pk_mul_f32 v[146:147], v[146:147], s[80:81] op_sel_hi:[1,0]
	v_rcp_f32_e32 v136, v136
	v_rcp_f32_e32 v137, v137
	v_rcp_f32_e32 v138, v138
	v_rcp_f32_e32 v139, v139
	v_exp_f32_e32 v144, v144
	v_exp_f32_e32 v145, v145
	v_exp_f32_e32 v146, v146
	v_exp_f32_e32 v147, v147
	v_pk_fma_f32 v[140:141], v[136:137], s[86:87], v[0:1] op_sel_hi:[1,0,0]
	v_pk_fma_f32 v[142:143], v[138:139], s[86:87], v[0:1] op_sel_hi:[1,0,0]
	v_pk_fma_f32 v[140:141], v[136:137], v[140:141], s[88:89] op_sel_hi:[1,1,0]
	v_pk_fma_f32 v[142:143], v[138:139], v[142:143], s[88:89] op_sel_hi:[1,1,0]
	v_pk_fma_f32 v[140:141], v[136:137], v[140:141], s[82:83] op_sel_hi:[1,1,0]
	v_pk_fma_f32 v[142:143], v[138:139], v[142:143], s[82:83] op_sel_hi:[1,1,0]
	v_pk_fma_f32 v[140:141], v[136:137], v[140:141], s[48:49] op_sel_hi:[1,1,0]
	v_pk_fma_f32 v[142:143], v[138:139], v[142:143], s[48:49] op_sel_hi:[1,1,0]
	v_pk_mul_f32 v[140:141], v[136:137], v[140:141]
	v_pk_mul_f32 v[142:143], v[138:139], v[142:143]
	v_pk_mul_f32 v[140:141], v[140:141], v[144:145]
	v_pk_mul_f32 v[142:143], v[142:143], v[146:147]
	v_max_f32_e32 v100, 0, v100
	v_max_f32_e32 v101, 0, v101
	v_max_f32_e32 v102, 0, v102
	v_max_f32_e32 v103, 0, v103
	v_pk_fma_f32 v[100:101], v[132:133], v[140:141], v[100:101] neg_lo:[1,0,0] neg_hi:[1,0,0]
	v_pk_fma_f32 v[102:103], v[134:135], v[142:143], v[102:103] neg_lo:[1,0,0] neg_hi:[1,0,0]
	v_cvt_pk_bf16_f32 v108, v108, v109
	v_cvt_pk_bf16_f32 v109, v110, v111
	v_cvt_pk_bf16_f32 v110, v100, v101
	v_cvt_pk_bf16_f32 v111, v102, v103
	global_store_dwordx4 v148, v[108:111], s[50:51] offset:256 sc1
	v_add_u32_e32 v148, s81, v148
	v_and_b32_e32 v132, 0x7fffffff, v96
	v_and_b32_e32 v133, 0x7fffffff, v97
	v_and_b32_e32 v134, 0x7fffffff, v98
	v_and_b32_e32 v135, 0x7fffffff, v99
	v_pk_mul_f32 v[144:145], v[96:97], v[96:97]
	v_pk_mul_f32 v[146:147], v[98:99], v[98:99]
	v_pk_fma_f32 v[136:137], v[132:133], s[84:85], 1.0 op_sel_hi:[1,0,0]
	v_pk_fma_f32 v[138:139], v[134:135], s[84:85], 1.0 op_sel_hi:[1,0,0]
	v_pk_mul_f32 v[144:145], v[144:145], s[80:81] op_sel_hi:[1,0]
	v_pk_mul_f32 v[146:147], v[146:147], s[80:81] op_sel_hi:[1,0]
	v_rcp_f32_e32 v136, v136
	v_rcp_f32_e32 v137, v137
	v_rcp_f32_e32 v138, v138
	v_rcp_f32_e32 v139, v139
	v_exp_f32_e32 v144, v144
	v_exp_f32_e32 v145, v145
	v_exp_f32_e32 v146, v146
	v_exp_f32_e32 v147, v147
	v_pk_fma_f32 v[140:141], v[136:137], s[86:87], v[0:1] op_sel_hi:[1,0,0]
	v_pk_fma_f32 v[142:143], v[138:139], s[86:87], v[0:1] op_sel_hi:[1,0,0]
	v_pk_fma_f32 v[140:141], v[136:137], v[140:141], s[88:89] op_sel_hi:[1,1,0]
	v_pk_fma_f32 v[142:143], v[138:139], v[142:143], s[88:89] op_sel_hi:[1,1,0]
	v_pk_fma_f32 v[140:141], v[136:137], v[140:141], s[82:83] op_sel_hi:[1,1,0]
	v_pk_fma_f32 v[142:143], v[138:139], v[142:143], s[82:83] op_sel_hi:[1,1,0]
	v_pk_fma_f32 v[140:141], v[136:137], v[140:141], s[48:49] op_sel_hi:[1,1,0]
	v_pk_fma_f32 v[142:143], v[138:139], v[142:143], s[48:49] op_sel_hi:[1,1,0]
	v_pk_mul_f32 v[140:141], v[136:137], v[140:141]
	v_pk_mul_f32 v[142:143], v[138:139], v[142:143]
	v_pk_mul_f32 v[140:141], v[140:141], v[144:145]
	v_pk_mul_f32 v[142:143], v[142:143], v[146:147]
	v_max_f32_e32 v96, 0, v96
	v_max_f32_e32 v97, 0, v97
	v_max_f32_e32 v98, 0, v98
	v_max_f32_e32 v99, 0, v99
	v_pk_fma_f32 v[96:97], v[132:133], v[140:141], v[96:97] neg_lo:[1,0,0] neg_hi:[1,0,0]
	v_pk_fma_f32 v[98:99], v[134:135], v[142:143], v[98:99] neg_lo:[1,0,0] neg_hi:[1,0,0]
	v_and_b32_e32 v132, 0x7fffffff, v88
	v_and_b32_e32 v133, 0x7fffffff, v89
	v_and_b32_e32 v134, 0x7fffffff, v90
	v_and_b32_e32 v135, 0x7fffffff, v91
	v_pk_mul_f32 v[144:145], v[88:89], v[88:89]
	v_pk_mul_f32 v[146:147], v[90:91], v[90:91]
	v_pk_fma_f32 v[136:137], v[132:133], s[84:85], 1.0 op_sel_hi:[1,0,0]
	v_pk_fma_f32 v[138:139], v[134:135], s[84:85], 1.0 op_sel_hi:[1,0,0]
	v_pk_mul_f32 v[144:145], v[144:145], s[80:81] op_sel_hi:[1,0]
	v_pk_mul_f32 v[146:147], v[146:147], s[80:81] op_sel_hi:[1,0]
	v_rcp_f32_e32 v136, v136
	v_rcp_f32_e32 v137, v137
	v_rcp_f32_e32 v138, v138
	v_rcp_f32_e32 v139, v139
	v_exp_f32_e32 v144, v144
	v_exp_f32_e32 v145, v145
	v_exp_f32_e32 v146, v146
	v_exp_f32_e32 v147, v147
	v_pk_fma_f32 v[140:141], v[136:137], s[86:87], v[0:1] op_sel_hi:[1,0,0]
	v_pk_fma_f32 v[142:143], v[138:139], s[86:87], v[0:1] op_sel_hi:[1,0,0]
	v_pk_fma_f32 v[140:141], v[136:137], v[140:141], s[88:89] op_sel_hi:[1,1,0]
	v_pk_fma_f32 v[142:143], v[138:139], v[142:143], s[88:89] op_sel_hi:[1,1,0]
	v_pk_fma_f32 v[140:141], v[136:137], v[140:141], s[82:83] op_sel_hi:[1,1,0]
	v_pk_fma_f32 v[142:143], v[138:139], v[142:143], s[82:83] op_sel_hi:[1,1,0]
	v_pk_fma_f32 v[140:141], v[136:137], v[140:141], s[48:49] op_sel_hi:[1,1,0]
	v_pk_fma_f32 v[142:143], v[138:139], v[142:143], s[48:49] op_sel_hi:[1,1,0]
	v_pk_mul_f32 v[140:141], v[136:137], v[140:141]
	v_pk_mul_f32 v[142:143], v[138:139], v[142:143]
	v_pk_mul_f32 v[140:141], v[140:141], v[144:145]
	v_pk_mul_f32 v[142:143], v[142:143], v[146:147]
	v_max_f32_e32 v88, 0, v88
	v_max_f32_e32 v89, 0, v89
	v_max_f32_e32 v90, 0, v90
	v_max_f32_e32 v91, 0, v91
	v_pk_fma_f32 v[88:89], v[132:133], v[140:141], v[88:89] neg_lo:[1,0,0] neg_hi:[1,0,0]
	v_pk_fma_f32 v[90:91], v[134:135], v[142:143], v[90:91] neg_lo:[1,0,0] neg_hi:[1,0,0]
	v_cvt_pk_bf16_f32 v96, v96, v97
	v_cvt_pk_bf16_f32 v97, v98, v99
	v_cvt_pk_bf16_f32 v98, v88, v89
	v_cvt_pk_bf16_f32 v99, v90, v91
	global_store_dwordx4 v148, v[96:99], s[50:51] sc1
	v_and_b32_e32 v132, 0x7fffffff, v80
	v_and_b32_e32 v133, 0x7fffffff, v81
	v_and_b32_e32 v134, 0x7fffffff, v82
	v_and_b32_e32 v135, 0x7fffffff, v83
	v_pk_mul_f32 v[144:145], v[80:81], v[80:81]
	v_pk_mul_f32 v[146:147], v[82:83], v[82:83]
	v_pk_fma_f32 v[136:137], v[132:133], s[84:85], 1.0 op_sel_hi:[1,0,0]
	v_pk_fma_f32 v[138:139], v[134:135], s[84:85], 1.0 op_sel_hi:[1,0,0]
	v_pk_mul_f32 v[144:145], v[144:145], s[80:81] op_sel_hi:[1,0]
	v_pk_mul_f32 v[146:147], v[146:147], s[80:81] op_sel_hi:[1,0]
	v_rcp_f32_e32 v136, v136
	v_rcp_f32_e32 v137, v137
	v_rcp_f32_e32 v138, v138
	v_rcp_f32_e32 v139, v139
	v_exp_f32_e32 v144, v144
	v_exp_f32_e32 v145, v145
	v_exp_f32_e32 v146, v146
	v_exp_f32_e32 v147, v147
	v_pk_fma_f32 v[140:141], v[136:137], s[86:87], v[0:1] op_sel_hi:[1,0,0]
	v_pk_fma_f32 v[142:143], v[138:139], s[86:87], v[0:1] op_sel_hi:[1,0,0]
	v_pk_fma_f32 v[140:141], v[136:137], v[140:141], s[88:89] op_sel_hi:[1,1,0]
	v_pk_fma_f32 v[142:143], v[138:139], v[142:143], s[88:89] op_sel_hi:[1,1,0]
	v_pk_fma_f32 v[140:141], v[136:137], v[140:141], s[82:83] op_sel_hi:[1,1,0]
	v_pk_fma_f32 v[142:143], v[138:139], v[142:143], s[82:83] op_sel_hi:[1,1,0]
	v_pk_fma_f32 v[140:141], v[136:137], v[140:141], s[48:49] op_sel_hi:[1,1,0]
	v_pk_fma_f32 v[142:143], v[138:139], v[142:143], s[48:49] op_sel_hi:[1,1,0]
	v_pk_mul_f32 v[140:141], v[136:137], v[140:141]
	v_pk_mul_f32 v[142:143], v[138:139], v[142:143]
	v_pk_mul_f32 v[140:141], v[140:141], v[144:145]
	v_pk_mul_f32 v[142:143], v[142:143], v[146:147]
	v_max_f32_e32 v80, 0, v80
	v_max_f32_e32 v81, 0, v81
	v_max_f32_e32 v82, 0, v82
	v_max_f32_e32 v83, 0, v83
	v_pk_fma_f32 v[80:81], v[132:133], v[140:141], v[80:81] neg_lo:[1,0,0] neg_hi:[1,0,0]
	v_pk_fma_f32 v[82:83], v[134:135], v[142:143], v[82:83] neg_lo:[1,0,0] neg_hi:[1,0,0]
	v_and_b32_e32 v132, 0x7fffffff, v72
	v_and_b32_e32 v133, 0x7fffffff, v73
	v_and_b32_e32 v134, 0x7fffffff, v74
	v_and_b32_e32 v135, 0x7fffffff, v75
	v_pk_mul_f32 v[144:145], v[72:73], v[72:73]
	v_pk_mul_f32 v[146:147], v[74:75], v[74:75]
	v_pk_fma_f32 v[136:137], v[132:133], s[84:85], 1.0 op_sel_hi:[1,0,0]
	v_pk_fma_f32 v[138:139], v[134:135], s[84:85], 1.0 op_sel_hi:[1,0,0]
	v_pk_mul_f32 v[144:145], v[144:145], s[80:81] op_sel_hi:[1,0]
	v_pk_mul_f32 v[146:147], v[146:147], s[80:81] op_sel_hi:[1,0]
	v_rcp_f32_e32 v136, v136
	v_rcp_f32_e32 v137, v137
	v_rcp_f32_e32 v138, v138
	v_rcp_f32_e32 v139, v139
	v_exp_f32_e32 v144, v144
	v_exp_f32_e32 v145, v145
	v_exp_f32_e32 v146, v146
	v_exp_f32_e32 v147, v147
	v_pk_fma_f32 v[140:141], v[136:137], s[86:87], v[0:1] op_sel_hi:[1,0,0]
	v_pk_fma_f32 v[142:143], v[138:139], s[86:87], v[0:1] op_sel_hi:[1,0,0]
	v_pk_fma_f32 v[140:141], v[136:137], v[140:141], s[88:89] op_sel_hi:[1,1,0]
	v_pk_fma_f32 v[142:143], v[138:139], v[142:143], s[88:89] op_sel_hi:[1,1,0]
	v_pk_fma_f32 v[140:141], v[136:137], v[140:141], s[82:83] op_sel_hi:[1,1,0]
	v_pk_fma_f32 v[142:143], v[138:139], v[142:143], s[82:83] op_sel_hi:[1,1,0]
	v_pk_fma_f32 v[140:141], v[136:137], v[140:141], s[48:49] op_sel_hi:[1,1,0]
	v_pk_fma_f32 v[142:143], v[138:139], v[142:143], s[48:49] op_sel_hi:[1,1,0]
	v_pk_mul_f32 v[140:141], v[136:137], v[140:141]
	v_pk_mul_f32 v[142:143], v[138:139], v[142:143]
	v_pk_mul_f32 v[140:141], v[140:141], v[144:145]
	v_pk_mul_f32 v[142:143], v[142:143], v[146:147]
	v_max_f32_e32 v72, 0, v72
	v_max_f32_e32 v73, 0, v73
	v_max_f32_e32 v74, 0, v74
	v_max_f32_e32 v75, 0, v75
	v_pk_fma_f32 v[72:73], v[132:133], v[140:141], v[72:73] neg_lo:[1,0,0] neg_hi:[1,0,0]
	v_pk_fma_f32 v[74:75], v[134:135], v[142:143], v[74:75] neg_lo:[1,0,0] neg_hi:[1,0,0]
	v_cvt_pk_bf16_f32 v80, v80, v81
	v_cvt_pk_bf16_f32 v81, v82, v83
	v_cvt_pk_bf16_f32 v82, v72, v73
	v_cvt_pk_bf16_f32 v83, v74, v75
	global_store_dwordx4 v148, v[80:83], s[50:51] offset:256 sc1
	v_add_u32_e32 v148, s81, v148
	v_and_b32_e32 v132, 0x7fffffff, v92
	v_and_b32_e32 v133, 0x7fffffff, v93
	v_and_b32_e32 v134, 0x7fffffff, v94
	v_and_b32_e32 v135, 0x7fffffff, v95
	v_pk_mul_f32 v[144:145], v[92:93], v[92:93]
	v_pk_mul_f32 v[146:147], v[94:95], v[94:95]
	v_pk_fma_f32 v[136:137], v[132:133], s[84:85], 1.0 op_sel_hi:[1,0,0]
	v_pk_fma_f32 v[138:139], v[134:135], s[84:85], 1.0 op_sel_hi:[1,0,0]
	v_pk_mul_f32 v[144:145], v[144:145], s[80:81] op_sel_hi:[1,0]
	v_pk_mul_f32 v[146:147], v[146:147], s[80:81] op_sel_hi:[1,0]
	v_rcp_f32_e32 v136, v136
	v_rcp_f32_e32 v137, v137
	v_rcp_f32_e32 v138, v138
	v_rcp_f32_e32 v139, v139
	v_exp_f32_e32 v144, v144
	v_exp_f32_e32 v145, v145
	v_exp_f32_e32 v146, v146
	v_exp_f32_e32 v147, v147
	v_pk_fma_f32 v[140:141], v[136:137], s[86:87], v[0:1] op_sel_hi:[1,0,0]
	v_pk_fma_f32 v[142:143], v[138:139], s[86:87], v[0:1] op_sel_hi:[1,0,0]
	v_pk_fma_f32 v[140:141], v[136:137], v[140:141], s[88:89] op_sel_hi:[1,1,0]
	v_pk_fma_f32 v[142:143], v[138:139], v[142:143], s[88:89] op_sel_hi:[1,1,0]
	v_pk_fma_f32 v[140:141], v[136:137], v[140:141], s[82:83] op_sel_hi:[1,1,0]
	v_pk_fma_f32 v[142:143], v[138:139], v[142:143], s[82:83] op_sel_hi:[1,1,0]
	v_pk_fma_f32 v[140:141], v[136:137], v[140:141], s[48:49] op_sel_hi:[1,1,0]
	v_pk_fma_f32 v[142:143], v[138:139], v[142:143], s[48:49] op_sel_hi:[1,1,0]
	v_pk_mul_f32 v[140:141], v[136:137], v[140:141]
	v_pk_mul_f32 v[142:143], v[138:139], v[142:143]
	v_pk_mul_f32 v[140:141], v[140:141], v[144:145]
	v_pk_mul_f32 v[142:143], v[142:143], v[146:147]
	v_max_f32_e32 v92, 0, v92
	v_max_f32_e32 v93, 0, v93
	v_max_f32_e32 v94, 0, v94
	v_max_f32_e32 v95, 0, v95
	v_pk_fma_f32 v[92:93], v[132:133], v[140:141], v[92:93] neg_lo:[1,0,0] neg_hi:[1,0,0]
	v_pk_fma_f32 v[94:95], v[134:135], v[142:143], v[94:95] neg_lo:[1,0,0] neg_hi:[1,0,0]
	v_and_b32_e32 v132, 0x7fffffff, v84
	v_and_b32_e32 v133, 0x7fffffff, v85
	v_and_b32_e32 v134, 0x7fffffff, v86
	v_and_b32_e32 v135, 0x7fffffff, v87
	v_pk_mul_f32 v[144:145], v[84:85], v[84:85]
	v_pk_mul_f32 v[146:147], v[86:87], v[86:87]
	v_pk_fma_f32 v[136:137], v[132:133], s[84:85], 1.0 op_sel_hi:[1,0,0]
	v_pk_fma_f32 v[138:139], v[134:135], s[84:85], 1.0 op_sel_hi:[1,0,0]
	v_pk_mul_f32 v[144:145], v[144:145], s[80:81] op_sel_hi:[1,0]
	v_pk_mul_f32 v[146:147], v[146:147], s[80:81] op_sel_hi:[1,0]
	v_rcp_f32_e32 v136, v136
	v_rcp_f32_e32 v137, v137
	v_rcp_f32_e32 v138, v138
	v_rcp_f32_e32 v139, v139
	v_exp_f32_e32 v144, v144
	v_exp_f32_e32 v145, v145
	v_exp_f32_e32 v146, v146
	v_exp_f32_e32 v147, v147
	v_pk_fma_f32 v[140:141], v[136:137], s[86:87], v[0:1] op_sel_hi:[1,0,0]
	v_pk_fma_f32 v[142:143], v[138:139], s[86:87], v[0:1] op_sel_hi:[1,0,0]
	v_pk_fma_f32 v[140:141], v[136:137], v[140:141], s[88:89] op_sel_hi:[1,1,0]
	v_pk_fma_f32 v[142:143], v[138:139], v[142:143], s[88:89] op_sel_hi:[1,1,0]
	v_pk_fma_f32 v[140:141], v[136:137], v[140:141], s[82:83] op_sel_hi:[1,1,0]
	v_pk_fma_f32 v[142:143], v[138:139], v[142:143], s[82:83] op_sel_hi:[1,1,0]
	v_pk_fma_f32 v[140:141], v[136:137], v[140:141], s[48:49] op_sel_hi:[1,1,0]
	v_pk_fma_f32 v[142:143], v[138:139], v[142:143], s[48:49] op_sel_hi:[1,1,0]
	v_pk_mul_f32 v[140:141], v[136:137], v[140:141]
	v_pk_mul_f32 v[142:143], v[138:139], v[142:143]
	v_pk_mul_f32 v[140:141], v[140:141], v[144:145]
	v_pk_mul_f32 v[142:143], v[142:143], v[146:147]
	v_max_f32_e32 v84, 0, v84
	v_max_f32_e32 v85, 0, v85
	v_max_f32_e32 v86, 0, v86
	v_max_f32_e32 v87, 0, v87
	v_pk_fma_f32 v[84:85], v[132:133], v[140:141], v[84:85] neg_lo:[1,0,0] neg_hi:[1,0,0]
	v_pk_fma_f32 v[86:87], v[134:135], v[142:143], v[86:87] neg_lo:[1,0,0] neg_hi:[1,0,0]
	v_cvt_pk_bf16_f32 v92, v92, v93
	v_cvt_pk_bf16_f32 v93, v94, v95
	v_cvt_pk_bf16_f32 v94, v84, v85
	v_cvt_pk_bf16_f32 v95, v86, v87
	global_store_dwordx4 v148, v[92:95], s[50:51] sc1
	v_and_b32_e32 v132, 0x7fffffff, v76
	v_and_b32_e32 v133, 0x7fffffff, v77
	v_and_b32_e32 v134, 0x7fffffff, v78
	v_and_b32_e32 v135, 0x7fffffff, v79
	v_pk_mul_f32 v[144:145], v[76:77], v[76:77]
	v_pk_mul_f32 v[146:147], v[78:79], v[78:79]
	v_pk_fma_f32 v[136:137], v[132:133], s[84:85], 1.0 op_sel_hi:[1,0,0]
	v_pk_fma_f32 v[138:139], v[134:135], s[84:85], 1.0 op_sel_hi:[1,0,0]
	v_pk_mul_f32 v[144:145], v[144:145], s[80:81] op_sel_hi:[1,0]
	v_pk_mul_f32 v[146:147], v[146:147], s[80:81] op_sel_hi:[1,0]
	v_rcp_f32_e32 v136, v136
	v_rcp_f32_e32 v137, v137
	v_rcp_f32_e32 v138, v138
	v_rcp_f32_e32 v139, v139
	v_exp_f32_e32 v144, v144
	v_exp_f32_e32 v145, v145
	v_exp_f32_e32 v146, v146
	v_exp_f32_e32 v147, v147
	v_pk_fma_f32 v[140:141], v[136:137], s[86:87], v[0:1] op_sel_hi:[1,0,0]
	v_pk_fma_f32 v[142:143], v[138:139], s[86:87], v[0:1] op_sel_hi:[1,0,0]
	v_pk_fma_f32 v[140:141], v[136:137], v[140:141], s[88:89] op_sel_hi:[1,1,0]
	v_pk_fma_f32 v[142:143], v[138:139], v[142:143], s[88:89] op_sel_hi:[1,1,0]
	v_pk_fma_f32 v[140:141], v[136:137], v[140:141], s[82:83] op_sel_hi:[1,1,0]
	v_pk_fma_f32 v[142:143], v[138:139], v[142:143], s[82:83] op_sel_hi:[1,1,0]
	v_pk_fma_f32 v[140:141], v[136:137], v[140:141], s[48:49] op_sel_hi:[1,1,0]
	v_pk_fma_f32 v[142:143], v[138:139], v[142:143], s[48:49] op_sel_hi:[1,1,0]
	v_pk_mul_f32 v[140:141], v[136:137], v[140:141]
	v_pk_mul_f32 v[142:143], v[138:139], v[142:143]
	v_pk_mul_f32 v[140:141], v[140:141], v[144:145]
	v_pk_mul_f32 v[142:143], v[142:143], v[146:147]
	v_max_f32_e32 v76, 0, v76
	v_max_f32_e32 v77, 0, v77
	v_max_f32_e32 v78, 0, v78
	v_max_f32_e32 v79, 0, v79
	v_pk_fma_f32 v[76:77], v[132:133], v[140:141], v[76:77] neg_lo:[1,0,0] neg_hi:[1,0,0]
	v_pk_fma_f32 v[78:79], v[134:135], v[142:143], v[78:79] neg_lo:[1,0,0] neg_hi:[1,0,0]
	v_and_b32_e32 v132, 0x7fffffff, v68
	v_and_b32_e32 v133, 0x7fffffff, v69
	v_and_b32_e32 v134, 0x7fffffff, v70
	v_and_b32_e32 v135, 0x7fffffff, v71
	v_pk_mul_f32 v[144:145], v[68:69], v[68:69]
	v_pk_mul_f32 v[146:147], v[70:71], v[70:71]
	v_pk_fma_f32 v[136:137], v[132:133], s[84:85], 1.0 op_sel_hi:[1,0,0]
	v_pk_fma_f32 v[138:139], v[134:135], s[84:85], 1.0 op_sel_hi:[1,0,0]
	v_pk_mul_f32 v[144:145], v[144:145], s[80:81] op_sel_hi:[1,0]
	v_pk_mul_f32 v[146:147], v[146:147], s[80:81] op_sel_hi:[1,0]
	v_rcp_f32_e32 v136, v136
	v_rcp_f32_e32 v137, v137
	v_rcp_f32_e32 v138, v138
	v_rcp_f32_e32 v139, v139
	v_exp_f32_e32 v144, v144
	v_exp_f32_e32 v145, v145
	v_exp_f32_e32 v146, v146
	v_exp_f32_e32 v147, v147
	v_pk_fma_f32 v[140:141], v[136:137], s[86:87], v[0:1] op_sel_hi:[1,0,0]
	v_pk_fma_f32 v[142:143], v[138:139], s[86:87], v[0:1] op_sel_hi:[1,0,0]
	v_pk_fma_f32 v[140:141], v[136:137], v[140:141], s[88:89] op_sel_hi:[1,1,0]
	v_pk_fma_f32 v[142:143], v[138:139], v[142:143], s[88:89] op_sel_hi:[1,1,0]
	v_pk_fma_f32 v[140:141], v[136:137], v[140:141], s[82:83] op_sel_hi:[1,1,0]
	v_pk_fma_f32 v[142:143], v[138:139], v[142:143], s[82:83] op_sel_hi:[1,1,0]
	v_pk_fma_f32 v[140:141], v[136:137], v[140:141], s[48:49] op_sel_hi:[1,1,0]
	v_pk_fma_f32 v[142:143], v[138:139], v[142:143], s[48:49] op_sel_hi:[1,1,0]
	v_pk_mul_f32 v[140:141], v[136:137], v[140:141]
	v_pk_mul_f32 v[142:143], v[138:139], v[142:143]
	v_pk_mul_f32 v[140:141], v[140:141], v[144:145]
	v_pk_mul_f32 v[142:143], v[142:143], v[146:147]
	v_max_f32_e32 v68, 0, v68
	v_max_f32_e32 v69, 0, v69
	v_max_f32_e32 v70, 0, v70
	v_max_f32_e32 v71, 0, v71
	v_pk_fma_f32 v[68:69], v[132:133], v[140:141], v[68:69] neg_lo:[1,0,0] neg_hi:[1,0,0]
	v_pk_fma_f32 v[70:71], v[134:135], v[142:143], v[70:71] neg_lo:[1,0,0] neg_hi:[1,0,0]
	v_cvt_pk_bf16_f32 v76, v76, v77
	v_cvt_pk_bf16_f32 v77, v78, v79
	v_cvt_pk_bf16_f32 v78, v68, v69
	v_cvt_pk_bf16_f32 v79, v70, v71
	global_store_dwordx4 v148, v[76:79], s[50:51] offset:256 sc1
	s_mul_i32 s30, s81, 5
	v_add_u32_e32 v148, s30, v148
	s_cmp_lg_u32 s49, 0
	s_cbranch_scc1 .LBB0_326
	v_and_b32_e32 v132, 0x7fffffff, v64
	v_and_b32_e32 v133, 0x7fffffff, v65
	v_and_b32_e32 v134, 0x7fffffff, v66
	v_and_b32_e32 v135, 0x7fffffff, v67
	v_pk_mul_f32 v[144:145], v[64:65], v[64:65]
	v_pk_mul_f32 v[146:147], v[66:67], v[66:67]
	v_pk_fma_f32 v[136:137], v[132:133], s[84:85], 1.0 op_sel_hi:[1,0,0]
	v_pk_fma_f32 v[138:139], v[134:135], s[84:85], 1.0 op_sel_hi:[1,0,0]
	v_pk_mul_f32 v[144:145], v[144:145], s[80:81] op_sel_hi:[1,0]
	v_pk_mul_f32 v[146:147], v[146:147], s[80:81] op_sel_hi:[1,0]
	v_rcp_f32_e32 v136, v136
	v_rcp_f32_e32 v137, v137
	v_rcp_f32_e32 v138, v138
	v_rcp_f32_e32 v139, v139
	v_exp_f32_e32 v144, v144
	v_exp_f32_e32 v145, v145
	v_exp_f32_e32 v146, v146
	v_exp_f32_e32 v147, v147
	v_pk_fma_f32 v[140:141], v[136:137], s[86:87], v[0:1] op_sel_hi:[1,0,0]
	v_pk_fma_f32 v[142:143], v[138:139], s[86:87], v[0:1] op_sel_hi:[1,0,0]
	v_pk_fma_f32 v[140:141], v[136:137], v[140:141], s[88:89] op_sel_hi:[1,1,0]
	v_pk_fma_f32 v[142:143], v[138:139], v[142:143], s[88:89] op_sel_hi:[1,1,0]
	v_pk_fma_f32 v[140:141], v[136:137], v[140:141], s[82:83] op_sel_hi:[1,1,0]
	v_pk_fma_f32 v[142:143], v[138:139], v[142:143], s[82:83] op_sel_hi:[1,1,0]
	v_pk_fma_f32 v[140:141], v[136:137], v[140:141], s[48:49] op_sel_hi:[1,1,0]
	v_pk_fma_f32 v[142:143], v[138:139], v[142:143], s[48:49] op_sel_hi:[1,1,0]
	v_pk_mul_f32 v[140:141], v[136:137], v[140:141]
	v_pk_mul_f32 v[142:143], v[138:139], v[142:143]
	v_pk_mul_f32 v[140:141], v[140:141], v[144:145]
	v_pk_mul_f32 v[142:143], v[142:143], v[146:147]
	v_max_f32_e32 v64, 0, v64
	v_max_f32_e32 v65, 0, v65
	v_max_f32_e32 v66, 0, v66
	v_max_f32_e32 v67, 0, v67
	v_pk_fma_f32 v[64:65], v[132:133], v[140:141], v[64:65] neg_lo:[1,0,0] neg_hi:[1,0,0]
	v_pk_fma_f32 v[66:67], v[134:135], v[142:143], v[66:67] neg_lo:[1,0,0] neg_hi:[1,0,0]
	v_and_b32_e32 v132, 0x7fffffff, v56
	v_and_b32_e32 v133, 0x7fffffff, v57
	v_and_b32_e32 v134, 0x7fffffff, v58
	v_and_b32_e32 v135, 0x7fffffff, v59
	v_pk_mul_f32 v[144:145], v[56:57], v[56:57]
	v_pk_mul_f32 v[146:147], v[58:59], v[58:59]
	v_pk_fma_f32 v[136:137], v[132:133], s[84:85], 1.0 op_sel_hi:[1,0,0]
	v_pk_fma_f32 v[138:139], v[134:135], s[84:85], 1.0 op_sel_hi:[1,0,0]
	v_pk_mul_f32 v[144:145], v[144:145], s[80:81] op_sel_hi:[1,0]
	v_pk_mul_f32 v[146:147], v[146:147], s[80:81] op_sel_hi:[1,0]
	v_rcp_f32_e32 v136, v136
	v_rcp_f32_e32 v137, v137
	v_rcp_f32_e32 v138, v138
	v_rcp_f32_e32 v139, v139
	v_exp_f32_e32 v144, v144
	v_exp_f32_e32 v145, v145
	v_exp_f32_e32 v146, v146
	v_exp_f32_e32 v147, v147
	v_pk_fma_f32 v[140:141], v[136:137], s[86:87], v[0:1] op_sel_hi:[1,0,0]
	v_pk_fma_f32 v[142:143], v[138:139], s[86:87], v[0:1] op_sel_hi:[1,0,0]
	v_pk_fma_f32 v[140:141], v[136:137], v[140:141], s[88:89] op_sel_hi:[1,1,0]
	v_pk_fma_f32 v[142:143], v[138:139], v[142:143], s[88:89] op_sel_hi:[1,1,0]
	v_pk_fma_f32 v[140:141], v[136:137], v[140:141], s[82:83] op_sel_hi:[1,1,0]
	v_pk_fma_f32 v[142:143], v[138:139], v[142:143], s[82:83] op_sel_hi:[1,1,0]
	v_pk_fma_f32 v[140:141], v[136:137], v[140:141], s[48:49] op_sel_hi:[1,1,0]
	v_pk_fma_f32 v[142:143], v[138:139], v[142:143], s[48:49] op_sel_hi:[1,1,0]
	v_pk_mul_f32 v[140:141], v[136:137], v[140:141]
	v_pk_mul_f32 v[142:143], v[138:139], v[142:143]
	v_pk_mul_f32 v[140:141], v[140:141], v[144:145]
	v_pk_mul_f32 v[142:143], v[142:143], v[146:147]
	v_max_f32_e32 v56, 0, v56
	v_max_f32_e32 v57, 0, v57
	v_max_f32_e32 v58, 0, v58
	v_max_f32_e32 v59, 0, v59
	v_pk_fma_f32 v[56:57], v[132:133], v[140:141], v[56:57] neg_lo:[1,0,0] neg_hi:[1,0,0]
	v_pk_fma_f32 v[58:59], v[134:135], v[142:143], v[58:59] neg_lo:[1,0,0] neg_hi:[1,0,0]
	v_cvt_pk_bf16_f32 v64, v64, v65
	v_cvt_pk_bf16_f32 v65, v66, v67
	v_cvt_pk_bf16_f32 v66, v56, v57
	v_cvt_pk_bf16_f32 v67, v58, v59
	global_store_dwordx4 v148, v[64:67], s[50:51] sc1
	v_and_b32_e32 v132, 0x7fffffff, v48
	v_and_b32_e32 v133, 0x7fffffff, v49
	v_and_b32_e32 v134, 0x7fffffff, v50
	v_and_b32_e32 v135, 0x7fffffff, v51
	v_pk_mul_f32 v[144:145], v[48:49], v[48:49]
	v_pk_mul_f32 v[146:147], v[50:51], v[50:51]
	v_pk_fma_f32 v[136:137], v[132:133], s[84:85], 1.0 op_sel_hi:[1,0,0]
	v_pk_fma_f32 v[138:139], v[134:135], s[84:85], 1.0 op_sel_hi:[1,0,0]
	v_pk_mul_f32 v[144:145], v[144:145], s[80:81] op_sel_hi:[1,0]
	v_pk_mul_f32 v[146:147], v[146:147], s[80:81] op_sel_hi:[1,0]
	v_rcp_f32_e32 v136, v136
	v_rcp_f32_e32 v137, v137
	v_rcp_f32_e32 v138, v138
	v_rcp_f32_e32 v139, v139
	v_exp_f32_e32 v144, v144
	v_exp_f32_e32 v145, v145
	v_exp_f32_e32 v146, v146
	v_exp_f32_e32 v147, v147
	v_pk_fma_f32 v[140:141], v[136:137], s[86:87], v[0:1] op_sel_hi:[1,0,0]
	v_pk_fma_f32 v[142:143], v[138:139], s[86:87], v[0:1] op_sel_hi:[1,0,0]
	v_pk_fma_f32 v[140:141], v[136:137], v[140:141], s[88:89] op_sel_hi:[1,1,0]
	v_pk_fma_f32 v[142:143], v[138:139], v[142:143], s[88:89] op_sel_hi:[1,1,0]
	v_pk_fma_f32 v[140:141], v[136:137], v[140:141], s[82:83] op_sel_hi:[1,1,0]
	v_pk_fma_f32 v[142:143], v[138:139], v[142:143], s[82:83] op_sel_hi:[1,1,0]
	v_pk_fma_f32 v[140:141], v[136:137], v[140:141], s[48:49] op_sel_hi:[1,1,0]
	v_pk_fma_f32 v[142:143], v[138:139], v[142:143], s[48:49] op_sel_hi:[1,1,0]
	v_pk_mul_f32 v[140:141], v[136:137], v[140:141]
	v_pk_mul_f32 v[142:143], v[138:139], v[142:143]
	v_pk_mul_f32 v[140:141], v[140:141], v[144:145]
	v_pk_mul_f32 v[142:143], v[142:143], v[146:147]
	v_max_f32_e32 v48, 0, v48
	v_max_f32_e32 v49, 0, v49
	v_max_f32_e32 v50, 0, v50
	v_max_f32_e32 v51, 0, v51
	v_pk_fma_f32 v[48:49], v[132:133], v[140:141], v[48:49] neg_lo:[1,0,0] neg_hi:[1,0,0]
	v_pk_fma_f32 v[50:51], v[134:135], v[142:143], v[50:51] neg_lo:[1,0,0] neg_hi:[1,0,0]
	v_and_b32_e32 v132, 0x7fffffff, v40
	v_and_b32_e32 v133, 0x7fffffff, v41
	v_and_b32_e32 v134, 0x7fffffff, v42
	v_and_b32_e32 v135, 0x7fffffff, v43
	v_pk_mul_f32 v[144:145], v[40:41], v[40:41]
	v_pk_mul_f32 v[146:147], v[42:43], v[42:43]
	v_pk_fma_f32 v[136:137], v[132:133], s[84:85], 1.0 op_sel_hi:[1,0,0]
	v_pk_fma_f32 v[138:139], v[134:135], s[84:85], 1.0 op_sel_hi:[1,0,0]
	v_pk_mul_f32 v[144:145], v[144:145], s[80:81] op_sel_hi:[1,0]
	v_pk_mul_f32 v[146:147], v[146:147], s[80:81] op_sel_hi:[1,0]
	v_rcp_f32_e32 v136, v136
	v_rcp_f32_e32 v137, v137
	v_rcp_f32_e32 v138, v138
	v_rcp_f32_e32 v139, v139
	v_exp_f32_e32 v144, v144
	v_exp_f32_e32 v145, v145
	v_exp_f32_e32 v146, v146
	v_exp_f32_e32 v147, v147
	v_pk_fma_f32 v[140:141], v[136:137], s[86:87], v[0:1] op_sel_hi:[1,0,0]
	v_pk_fma_f32 v[142:143], v[138:139], s[86:87], v[0:1] op_sel_hi:[1,0,0]
	v_pk_fma_f32 v[140:141], v[136:137], v[140:141], s[88:89] op_sel_hi:[1,1,0]
	v_pk_fma_f32 v[142:143], v[138:139], v[142:143], s[88:89] op_sel_hi:[1,1,0]
	v_pk_fma_f32 v[140:141], v[136:137], v[140:141], s[82:83] op_sel_hi:[1,1,0]
	v_pk_fma_f32 v[142:143], v[138:139], v[142:143], s[82:83] op_sel_hi:[1,1,0]
	v_pk_fma_f32 v[140:141], v[136:137], v[140:141], s[48:49] op_sel_hi:[1,1,0]
	v_pk_fma_f32 v[142:143], v[138:139], v[142:143], s[48:49] op_sel_hi:[1,1,0]
	v_pk_mul_f32 v[140:141], v[136:137], v[140:141]
	v_pk_mul_f32 v[142:143], v[138:139], v[142:143]
	v_pk_mul_f32 v[140:141], v[140:141], v[144:145]
	v_pk_mul_f32 v[142:143], v[142:143], v[146:147]
	v_max_f32_e32 v40, 0, v40
	v_max_f32_e32 v41, 0, v41
	v_max_f32_e32 v42, 0, v42
	v_max_f32_e32 v43, 0, v43
	v_pk_fma_f32 v[40:41], v[132:133], v[140:141], v[40:41] neg_lo:[1,0,0] neg_hi:[1,0,0]
	v_pk_fma_f32 v[42:43], v[134:135], v[142:143], v[42:43] neg_lo:[1,0,0] neg_hi:[1,0,0]
	v_cvt_pk_bf16_f32 v48, v48, v49
	v_cvt_pk_bf16_f32 v49, v50, v51
	v_cvt_pk_bf16_f32 v50, v40, v41
	v_cvt_pk_bf16_f32 v51, v42, v43
	global_store_dwordx4 v148, v[48:51], s[50:51] offset:256 sc1
	v_add_u32_e32 v148, s81, v148
	v_and_b32_e32 v132, 0x7fffffff, v60
	v_and_b32_e32 v133, 0x7fffffff, v61
	v_and_b32_e32 v134, 0x7fffffff, v62
	v_and_b32_e32 v135, 0x7fffffff, v63
	v_pk_mul_f32 v[144:145], v[60:61], v[60:61]
	v_pk_mul_f32 v[146:147], v[62:63], v[62:63]
	v_pk_fma_f32 v[136:137], v[132:133], s[84:85], 1.0 op_sel_hi:[1,0,0]
	v_pk_fma_f32 v[138:139], v[134:135], s[84:85], 1.0 op_sel_hi:[1,0,0]
	v_pk_mul_f32 v[144:145], v[144:145], s[80:81] op_sel_hi:[1,0]
	v_pk_mul_f32 v[146:147], v[146:147], s[80:81] op_sel_hi:[1,0]
	v_rcp_f32_e32 v136, v136
	v_rcp_f32_e32 v137, v137
	v_rcp_f32_e32 v138, v138
	v_rcp_f32_e32 v139, v139
	v_exp_f32_e32 v144, v144
	v_exp_f32_e32 v145, v145
	v_exp_f32_e32 v146, v146
	v_exp_f32_e32 v147, v147
	v_pk_fma_f32 v[140:141], v[136:137], s[86:87], v[0:1] op_sel_hi:[1,0,0]
	v_pk_fma_f32 v[142:143], v[138:139], s[86:87], v[0:1] op_sel_hi:[1,0,0]
	v_pk_fma_f32 v[140:141], v[136:137], v[140:141], s[88:89] op_sel_hi:[1,1,0]
	v_pk_fma_f32 v[142:143], v[138:139], v[142:143], s[88:89] op_sel_hi:[1,1,0]
	v_pk_fma_f32 v[140:141], v[136:137], v[140:141], s[82:83] op_sel_hi:[1,1,0]
	v_pk_fma_f32 v[142:143], v[138:139], v[142:143], s[82:83] op_sel_hi:[1,1,0]
	v_pk_fma_f32 v[140:141], v[136:137], v[140:141], s[48:49] op_sel_hi:[1,1,0]
	v_pk_fma_f32 v[142:143], v[138:139], v[142:143], s[48:49] op_sel_hi:[1,1,0]
	v_pk_mul_f32 v[140:141], v[136:137], v[140:141]
	v_pk_mul_f32 v[142:143], v[138:139], v[142:143]
	v_pk_mul_f32 v[140:141], v[140:141], v[144:145]
	v_pk_mul_f32 v[142:143], v[142:143], v[146:147]
	v_max_f32_e32 v60, 0, v60
	v_max_f32_e32 v61, 0, v61
	v_max_f32_e32 v62, 0, v62
	v_max_f32_e32 v63, 0, v63
	v_pk_fma_f32 v[60:61], v[132:133], v[140:141], v[60:61] neg_lo:[1,0,0] neg_hi:[1,0,0]
	v_pk_fma_f32 v[62:63], v[134:135], v[142:143], v[62:63] neg_lo:[1,0,0] neg_hi:[1,0,0]
	v_and_b32_e32 v132, 0x7fffffff, v52
	v_and_b32_e32 v133, 0x7fffffff, v53
	v_and_b32_e32 v134, 0x7fffffff, v54
	v_and_b32_e32 v135, 0x7fffffff, v55
	v_pk_mul_f32 v[144:145], v[52:53], v[52:53]
	v_pk_mul_f32 v[146:147], v[54:55], v[54:55]
	v_pk_fma_f32 v[136:137], v[132:133], s[84:85], 1.0 op_sel_hi:[1,0,0]
	v_pk_fma_f32 v[138:139], v[134:135], s[84:85], 1.0 op_sel_hi:[1,0,0]
	v_pk_mul_f32 v[144:145], v[144:145], s[80:81] op_sel_hi:[1,0]
	v_pk_mul_f32 v[146:147], v[146:147], s[80:81] op_sel_hi:[1,0]
	v_rcp_f32_e32 v136, v136
	v_rcp_f32_e32 v137, v137
	v_rcp_f32_e32 v138, v138
	v_rcp_f32_e32 v139, v139
	v_exp_f32_e32 v144, v144
	v_exp_f32_e32 v145, v145
	v_exp_f32_e32 v146, v146
	v_exp_f32_e32 v147, v147
	v_pk_fma_f32 v[140:141], v[136:137], s[86:87], v[0:1] op_sel_hi:[1,0,0]
	v_pk_fma_f32 v[142:143], v[138:139], s[86:87], v[0:1] op_sel_hi:[1,0,0]
	v_pk_fma_f32 v[140:141], v[136:137], v[140:141], s[88:89] op_sel_hi:[1,1,0]
	v_pk_fma_f32 v[142:143], v[138:139], v[142:143], s[88:89] op_sel_hi:[1,1,0]
	v_pk_fma_f32 v[140:141], v[136:137], v[140:141], s[82:83] op_sel_hi:[1,1,0]
	v_pk_fma_f32 v[142:143], v[138:139], v[142:143], s[82:83] op_sel_hi:[1,1,0]
	v_pk_fma_f32 v[140:141], v[136:137], v[140:141], s[48:49] op_sel_hi:[1,1,0]
	v_pk_fma_f32 v[142:143], v[138:139], v[142:143], s[48:49] op_sel_hi:[1,1,0]
	v_pk_mul_f32 v[140:141], v[136:137], v[140:141]
	v_pk_mul_f32 v[142:143], v[138:139], v[142:143]
	v_pk_mul_f32 v[140:141], v[140:141], v[144:145]
	v_pk_mul_f32 v[142:143], v[142:143], v[146:147]
	v_max_f32_e32 v52, 0, v52
	v_max_f32_e32 v53, 0, v53
	v_max_f32_e32 v54, 0, v54
	v_max_f32_e32 v55, 0, v55
	v_pk_fma_f32 v[52:53], v[132:133], v[140:141], v[52:53] neg_lo:[1,0,0] neg_hi:[1,0,0]
	v_pk_fma_f32 v[54:55], v[134:135], v[142:143], v[54:55] neg_lo:[1,0,0] neg_hi:[1,0,0]
	v_cvt_pk_bf16_f32 v60, v60, v61
	v_cvt_pk_bf16_f32 v61, v62, v63
	v_cvt_pk_bf16_f32 v62, v52, v53
	v_cvt_pk_bf16_f32 v63, v54, v55
	global_store_dwordx4 v148, v[60:63], s[50:51] sc1
	v_and_b32_e32 v132, 0x7fffffff, v44
	v_and_b32_e32 v133, 0x7fffffff, v45
	v_and_b32_e32 v134, 0x7fffffff, v46
	v_and_b32_e32 v135, 0x7fffffff, v47
	v_pk_mul_f32 v[144:145], v[44:45], v[44:45]
	v_pk_mul_f32 v[146:147], v[46:47], v[46:47]
	v_pk_fma_f32 v[136:137], v[132:133], s[84:85], 1.0 op_sel_hi:[1,0,0]
	v_pk_fma_f32 v[138:139], v[134:135], s[84:85], 1.0 op_sel_hi:[1,0,0]
	v_pk_mul_f32 v[144:145], v[144:145], s[80:81] op_sel_hi:[1,0]
	v_pk_mul_f32 v[146:147], v[146:147], s[80:81] op_sel_hi:[1,0]
	v_rcp_f32_e32 v136, v136
	v_rcp_f32_e32 v137, v137
	v_rcp_f32_e32 v138, v138
	v_rcp_f32_e32 v139, v139
	v_exp_f32_e32 v144, v144
	v_exp_f32_e32 v145, v145
	v_exp_f32_e32 v146, v146
	v_exp_f32_e32 v147, v147
	v_pk_fma_f32 v[140:141], v[136:137], s[86:87], v[0:1] op_sel_hi:[1,0,0]
	v_pk_fma_f32 v[142:143], v[138:139], s[86:87], v[0:1] op_sel_hi:[1,0,0]
	v_pk_fma_f32 v[140:141], v[136:137], v[140:141], s[88:89] op_sel_hi:[1,1,0]
	v_pk_fma_f32 v[142:143], v[138:139], v[142:143], s[88:89] op_sel_hi:[1,1,0]
	v_pk_fma_f32 v[140:141], v[136:137], v[140:141], s[82:83] op_sel_hi:[1,1,0]
	v_pk_fma_f32 v[142:143], v[138:139], v[142:143], s[82:83] op_sel_hi:[1,1,0]
	v_pk_fma_f32 v[140:141], v[136:137], v[140:141], s[48:49] op_sel_hi:[1,1,0]
	v_pk_fma_f32 v[142:143], v[138:139], v[142:143], s[48:49] op_sel_hi:[1,1,0]
	v_pk_mul_f32 v[140:141], v[136:137], v[140:141]
	v_pk_mul_f32 v[142:143], v[138:139], v[142:143]
	v_pk_mul_f32 v[140:141], v[140:141], v[144:145]
	v_pk_mul_f32 v[142:143], v[142:143], v[146:147]
	v_max_f32_e32 v44, 0, v44
	v_max_f32_e32 v45, 0, v45
	v_max_f32_e32 v46, 0, v46
	v_max_f32_e32 v47, 0, v47
	v_pk_fma_f32 v[44:45], v[132:133], v[140:141], v[44:45] neg_lo:[1,0,0] neg_hi:[1,0,0]
	v_pk_fma_f32 v[46:47], v[134:135], v[142:143], v[46:47] neg_lo:[1,0,0] neg_hi:[1,0,0]
	v_and_b32_e32 v132, 0x7fffffff, v36
	v_and_b32_e32 v133, 0x7fffffff, v37
	v_and_b32_e32 v134, 0x7fffffff, v38
	v_and_b32_e32 v135, 0x7fffffff, v39
	v_pk_mul_f32 v[144:145], v[36:37], v[36:37]
	v_pk_mul_f32 v[146:147], v[38:39], v[38:39]
	v_pk_fma_f32 v[136:137], v[132:133], s[84:85], 1.0 op_sel_hi:[1,0,0]
	v_pk_fma_f32 v[138:139], v[134:135], s[84:85], 1.0 op_sel_hi:[1,0,0]
	v_pk_mul_f32 v[144:145], v[144:145], s[80:81] op_sel_hi:[1,0]
	v_pk_mul_f32 v[146:147], v[146:147], s[80:81] op_sel_hi:[1,0]
	v_rcp_f32_e32 v136, v136
	v_rcp_f32_e32 v137, v137
	v_rcp_f32_e32 v138, v138
	v_rcp_f32_e32 v139, v139
	v_exp_f32_e32 v144, v144
	v_exp_f32_e32 v145, v145
	v_exp_f32_e32 v146, v146
	v_exp_f32_e32 v147, v147
	v_pk_fma_f32 v[140:141], v[136:137], s[86:87], v[0:1] op_sel_hi:[1,0,0]
	v_pk_fma_f32 v[142:143], v[138:139], s[86:87], v[0:1] op_sel_hi:[1,0,0]
	v_pk_fma_f32 v[140:141], v[136:137], v[140:141], s[88:89] op_sel_hi:[1,1,0]
	v_pk_fma_f32 v[142:143], v[138:139], v[142:143], s[88:89] op_sel_hi:[1,1,0]
	v_pk_fma_f32 v[140:141], v[136:137], v[140:141], s[82:83] op_sel_hi:[1,1,0]
	v_pk_fma_f32 v[142:143], v[138:139], v[142:143], s[82:83] op_sel_hi:[1,1,0]
	v_pk_fma_f32 v[140:141], v[136:137], v[140:141], s[48:49] op_sel_hi:[1,1,0]
	v_pk_fma_f32 v[142:143], v[138:139], v[142:143], s[48:49] op_sel_hi:[1,1,0]
	v_pk_mul_f32 v[140:141], v[136:137], v[140:141]
	v_pk_mul_f32 v[142:143], v[138:139], v[142:143]
	v_pk_mul_f32 v[140:141], v[140:141], v[144:145]
	v_pk_mul_f32 v[142:143], v[142:143], v[146:147]
	v_max_f32_e32 v36, 0, v36
	v_max_f32_e32 v37, 0, v37
	v_max_f32_e32 v38, 0, v38
	v_max_f32_e32 v39, 0, v39
	v_pk_fma_f32 v[36:37], v[132:133], v[140:141], v[36:37] neg_lo:[1,0,0] neg_hi:[1,0,0]
	v_pk_fma_f32 v[38:39], v[134:135], v[142:143], v[38:39] neg_lo:[1,0,0] neg_hi:[1,0,0]
	v_cvt_pk_bf16_f32 v44, v44, v45
	v_cvt_pk_bf16_f32 v45, v46, v47
	v_cvt_pk_bf16_f32 v46, v36, v37
	v_cvt_pk_bf16_f32 v47, v38, v39
	global_store_dwordx4 v148, v[44:47], s[50:51] offset:256 sc1
	v_add_u32_e32 v148, s81, v148
	v_and_b32_e32 v132, 0x7fffffff, v32
	v_and_b32_e32 v133, 0x7fffffff, v33
	v_and_b32_e32 v134, 0x7fffffff, v34
	v_and_b32_e32 v135, 0x7fffffff, v35
	v_pk_mul_f32 v[144:145], v[32:33], v[32:33]
	v_pk_mul_f32 v[146:147], v[34:35], v[34:35]
	v_pk_fma_f32 v[136:137], v[132:133], s[84:85], 1.0 op_sel_hi:[1,0,0]
	v_pk_fma_f32 v[138:139], v[134:135], s[84:85], 1.0 op_sel_hi:[1,0,0]
	v_pk_mul_f32 v[144:145], v[144:145], s[80:81] op_sel_hi:[1,0]
	v_pk_mul_f32 v[146:147], v[146:147], s[80:81] op_sel_hi:[1,0]
	v_rcp_f32_e32 v136, v136
	v_rcp_f32_e32 v137, v137
	v_rcp_f32_e32 v138, v138
	v_rcp_f32_e32 v139, v139
	v_exp_f32_e32 v144, v144
	v_exp_f32_e32 v145, v145
	v_exp_f32_e32 v146, v146
	v_exp_f32_e32 v147, v147
	v_pk_fma_f32 v[140:141], v[136:137], s[86:87], v[0:1] op_sel_hi:[1,0,0]
	v_pk_fma_f32 v[142:143], v[138:139], s[86:87], v[0:1] op_sel_hi:[1,0,0]
	v_pk_fma_f32 v[140:141], v[136:137], v[140:141], s[88:89] op_sel_hi:[1,1,0]
	v_pk_fma_f32 v[142:143], v[138:139], v[142:143], s[88:89] op_sel_hi:[1,1,0]
	v_pk_fma_f32 v[140:141], v[136:137], v[140:141], s[82:83] op_sel_hi:[1,1,0]
	v_pk_fma_f32 v[142:143], v[138:139], v[142:143], s[82:83] op_sel_hi:[1,1,0]
	v_pk_fma_f32 v[140:141], v[136:137], v[140:141], s[48:49] op_sel_hi:[1,1,0]
	v_pk_fma_f32 v[142:143], v[138:139], v[142:143], s[48:49] op_sel_hi:[1,1,0]
	v_pk_mul_f32 v[140:141], v[136:137], v[140:141]
	v_pk_mul_f32 v[142:143], v[138:139], v[142:143]
	v_pk_mul_f32 v[140:141], v[140:141], v[144:145]
	v_pk_mul_f32 v[142:143], v[142:143], v[146:147]
	v_max_f32_e32 v32, 0, v32
	v_max_f32_e32 v33, 0, v33
	v_max_f32_e32 v34, 0, v34
	v_max_f32_e32 v35, 0, v35
	v_pk_fma_f32 v[32:33], v[132:133], v[140:141], v[32:33] neg_lo:[1,0,0] neg_hi:[1,0,0]
	v_pk_fma_f32 v[34:35], v[134:135], v[142:143], v[34:35] neg_lo:[1,0,0] neg_hi:[1,0,0]
	v_and_b32_e32 v132, 0x7fffffff, v24
	v_and_b32_e32 v133, 0x7fffffff, v25
	v_and_b32_e32 v134, 0x7fffffff, v26
	v_and_b32_e32 v135, 0x7fffffff, v27
	v_pk_mul_f32 v[144:145], v[24:25], v[24:25]
	v_pk_mul_f32 v[146:147], v[26:27], v[26:27]
	v_pk_fma_f32 v[136:137], v[132:133], s[84:85], 1.0 op_sel_hi:[1,0,0]
	v_pk_fma_f32 v[138:139], v[134:135], s[84:85], 1.0 op_sel_hi:[1,0,0]
	v_pk_mul_f32 v[144:145], v[144:145], s[80:81] op_sel_hi:[1,0]
	v_pk_mul_f32 v[146:147], v[146:147], s[80:81] op_sel_hi:[1,0]
	v_rcp_f32_e32 v136, v136
	v_rcp_f32_e32 v137, v137
	v_rcp_f32_e32 v138, v138
	v_rcp_f32_e32 v139, v139
	v_exp_f32_e32 v144, v144
	v_exp_f32_e32 v145, v145
	v_exp_f32_e32 v146, v146
	v_exp_f32_e32 v147, v147
	v_pk_fma_f32 v[140:141], v[136:137], s[86:87], v[0:1] op_sel_hi:[1,0,0]
	v_pk_fma_f32 v[142:143], v[138:139], s[86:87], v[0:1] op_sel_hi:[1,0,0]
	v_pk_fma_f32 v[140:141], v[136:137], v[140:141], s[88:89] op_sel_hi:[1,1,0]
	v_pk_fma_f32 v[142:143], v[138:139], v[142:143], s[88:89] op_sel_hi:[1,1,0]
	v_pk_fma_f32 v[140:141], v[136:137], v[140:141], s[82:83] op_sel_hi:[1,1,0]
	v_pk_fma_f32 v[142:143], v[138:139], v[142:143], s[82:83] op_sel_hi:[1,1,0]
	v_pk_fma_f32 v[140:141], v[136:137], v[140:141], s[48:49] op_sel_hi:[1,1,0]
	v_pk_fma_f32 v[142:143], v[138:139], v[142:143], s[48:49] op_sel_hi:[1,1,0]
	v_pk_mul_f32 v[140:141], v[136:137], v[140:141]
	v_pk_mul_f32 v[142:143], v[138:139], v[142:143]
	v_pk_mul_f32 v[140:141], v[140:141], v[144:145]
	v_pk_mul_f32 v[142:143], v[142:143], v[146:147]
	v_max_f32_e32 v24, 0, v24
	v_max_f32_e32 v25, 0, v25
	v_max_f32_e32 v26, 0, v26
	v_max_f32_e32 v27, 0, v27
	v_pk_fma_f32 v[24:25], v[132:133], v[140:141], v[24:25] neg_lo:[1,0,0] neg_hi:[1,0,0]
	v_pk_fma_f32 v[26:27], v[134:135], v[142:143], v[26:27] neg_lo:[1,0,0] neg_hi:[1,0,0]
	v_cvt_pk_bf16_f32 v32, v32, v33
	v_cvt_pk_bf16_f32 v33, v34, v35
	v_cvt_pk_bf16_f32 v34, v24, v25
	v_cvt_pk_bf16_f32 v35, v26, v27
	global_store_dwordx4 v148, v[32:35], s[50:51] sc1
	v_and_b32_e32 v132, 0x7fffffff, v16
	v_and_b32_e32 v133, 0x7fffffff, v17
	v_and_b32_e32 v134, 0x7fffffff, v18
	v_and_b32_e32 v135, 0x7fffffff, v19
	v_pk_mul_f32 v[144:145], v[16:17], v[16:17]
	v_pk_mul_f32 v[146:147], v[18:19], v[18:19]
	v_pk_fma_f32 v[136:137], v[132:133], s[84:85], 1.0 op_sel_hi:[1,0,0]
	v_pk_fma_f32 v[138:139], v[134:135], s[84:85], 1.0 op_sel_hi:[1,0,0]
	v_pk_mul_f32 v[144:145], v[144:145], s[80:81] op_sel_hi:[1,0]
	v_pk_mul_f32 v[146:147], v[146:147], s[80:81] op_sel_hi:[1,0]
	v_rcp_f32_e32 v136, v136
	v_rcp_f32_e32 v137, v137
	v_rcp_f32_e32 v138, v138
	v_rcp_f32_e32 v139, v139
	v_exp_f32_e32 v144, v144
	v_exp_f32_e32 v145, v145
	v_exp_f32_e32 v146, v146
	v_exp_f32_e32 v147, v147
	v_pk_fma_f32 v[140:141], v[136:137], s[86:87], v[0:1] op_sel_hi:[1,0,0]
	v_pk_fma_f32 v[142:143], v[138:139], s[86:87], v[0:1] op_sel_hi:[1,0,0]
	v_pk_fma_f32 v[140:141], v[136:137], v[140:141], s[88:89] op_sel_hi:[1,1,0]
	v_pk_fma_f32 v[142:143], v[138:139], v[142:143], s[88:89] op_sel_hi:[1,1,0]
	v_pk_fma_f32 v[140:141], v[136:137], v[140:141], s[82:83] op_sel_hi:[1,1,0]
	v_pk_fma_f32 v[142:143], v[138:139], v[142:143], s[82:83] op_sel_hi:[1,1,0]
	v_pk_fma_f32 v[140:141], v[136:137], v[140:141], s[48:49] op_sel_hi:[1,1,0]
	v_pk_fma_f32 v[142:143], v[138:139], v[142:143], s[48:49] op_sel_hi:[1,1,0]
	v_pk_mul_f32 v[140:141], v[136:137], v[140:141]
	v_pk_mul_f32 v[142:143], v[138:139], v[142:143]
	v_pk_mul_f32 v[140:141], v[140:141], v[144:145]
	v_pk_mul_f32 v[142:143], v[142:143], v[146:147]
	v_max_f32_e32 v16, 0, v16
	v_max_f32_e32 v17, 0, v17
	v_max_f32_e32 v18, 0, v18
	v_max_f32_e32 v19, 0, v19
	v_pk_fma_f32 v[16:17], v[132:133], v[140:141], v[16:17] neg_lo:[1,0,0] neg_hi:[1,0,0]
	v_pk_fma_f32 v[18:19], v[134:135], v[142:143], v[18:19] neg_lo:[1,0,0] neg_hi:[1,0,0]
	v_and_b32_e32 v132, 0x7fffffff, v8
	v_and_b32_e32 v133, 0x7fffffff, v9
	v_and_b32_e32 v134, 0x7fffffff, v10
	v_and_b32_e32 v135, 0x7fffffff, v11
	v_pk_mul_f32 v[144:145], v[8:9], v[8:9]
	v_pk_mul_f32 v[146:147], v[10:11], v[10:11]
	v_pk_fma_f32 v[136:137], v[132:133], s[84:85], 1.0 op_sel_hi:[1,0,0]
	v_pk_fma_f32 v[138:139], v[134:135], s[84:85], 1.0 op_sel_hi:[1,0,0]
	v_pk_mul_f32 v[144:145], v[144:145], s[80:81] op_sel_hi:[1,0]
	v_pk_mul_f32 v[146:147], v[146:147], s[80:81] op_sel_hi:[1,0]
	v_rcp_f32_e32 v136, v136
	v_rcp_f32_e32 v137, v137
	v_rcp_f32_e32 v138, v138
	v_rcp_f32_e32 v139, v139
	v_exp_f32_e32 v144, v144
	v_exp_f32_e32 v145, v145
	v_exp_f32_e32 v146, v146
	v_exp_f32_e32 v147, v147
	v_pk_fma_f32 v[140:141], v[136:137], s[86:87], v[0:1] op_sel_hi:[1,0,0]
	v_pk_fma_f32 v[142:143], v[138:139], s[86:87], v[0:1] op_sel_hi:[1,0,0]
	v_pk_fma_f32 v[140:141], v[136:137], v[140:141], s[88:89] op_sel_hi:[1,1,0]
	v_pk_fma_f32 v[142:143], v[138:139], v[142:143], s[88:89] op_sel_hi:[1,1,0]
	v_pk_fma_f32 v[140:141], v[136:137], v[140:141], s[82:83] op_sel_hi:[1,1,0]
	v_pk_fma_f32 v[142:143], v[138:139], v[142:143], s[82:83] op_sel_hi:[1,1,0]
	v_pk_fma_f32 v[140:141], v[136:137], v[140:141], s[48:49] op_sel_hi:[1,1,0]
	v_pk_fma_f32 v[142:143], v[138:139], v[142:143], s[48:49] op_sel_hi:[1,1,0]
	v_pk_mul_f32 v[140:141], v[136:137], v[140:141]
	v_pk_mul_f32 v[142:143], v[138:139], v[142:143]
	v_pk_mul_f32 v[140:141], v[140:141], v[144:145]
	v_pk_mul_f32 v[142:143], v[142:143], v[146:147]
	v_max_f32_e32 v8, 0, v8
	v_max_f32_e32 v9, 0, v9
	v_max_f32_e32 v10, 0, v10
	v_max_f32_e32 v11, 0, v11
	v_pk_fma_f32 v[8:9], v[132:133], v[140:141], v[8:9] neg_lo:[1,0,0] neg_hi:[1,0,0]
	v_pk_fma_f32 v[10:11], v[134:135], v[142:143], v[10:11] neg_lo:[1,0,0] neg_hi:[1,0,0]
	v_cvt_pk_bf16_f32 v16, v16, v17
	v_cvt_pk_bf16_f32 v17, v18, v19
	v_cvt_pk_bf16_f32 v18, v8, v9
	v_cvt_pk_bf16_f32 v19, v10, v11
	global_store_dwordx4 v148, v[16:19], s[50:51] offset:256 sc1
	v_add_u32_e32 v148, s81, v148
	v_and_b32_e32 v132, 0x7fffffff, v28
	v_and_b32_e32 v133, 0x7fffffff, v29
	v_and_b32_e32 v134, 0x7fffffff, v30
	v_and_b32_e32 v135, 0x7fffffff, v31
	v_pk_mul_f32 v[144:145], v[28:29], v[28:29]
	v_pk_mul_f32 v[146:147], v[30:31], v[30:31]
	v_pk_fma_f32 v[136:137], v[132:133], s[84:85], 1.0 op_sel_hi:[1,0,0]
	v_pk_fma_f32 v[138:139], v[134:135], s[84:85], 1.0 op_sel_hi:[1,0,0]
	v_pk_mul_f32 v[144:145], v[144:145], s[80:81] op_sel_hi:[1,0]
	v_pk_mul_f32 v[146:147], v[146:147], s[80:81] op_sel_hi:[1,0]
	v_rcp_f32_e32 v136, v136
	v_rcp_f32_e32 v137, v137
	v_rcp_f32_e32 v138, v138
	v_rcp_f32_e32 v139, v139
	v_exp_f32_e32 v144, v144
	v_exp_f32_e32 v145, v145
	v_exp_f32_e32 v146, v146
	v_exp_f32_e32 v147, v147
	v_pk_fma_f32 v[140:141], v[136:137], s[86:87], v[0:1] op_sel_hi:[1,0,0]
	v_pk_fma_f32 v[142:143], v[138:139], s[86:87], v[0:1] op_sel_hi:[1,0,0]
	v_pk_fma_f32 v[140:141], v[136:137], v[140:141], s[88:89] op_sel_hi:[1,1,0]
	v_pk_fma_f32 v[142:143], v[138:139], v[142:143], s[88:89] op_sel_hi:[1,1,0]
	v_pk_fma_f32 v[140:141], v[136:137], v[140:141], s[82:83] op_sel_hi:[1,1,0]
	v_pk_fma_f32 v[142:143], v[138:139], v[142:143], s[82:83] op_sel_hi:[1,1,0]
	v_pk_fma_f32 v[140:141], v[136:137], v[140:141], s[48:49] op_sel_hi:[1,1,0]
	v_pk_fma_f32 v[142:143], v[138:139], v[142:143], s[48:49] op_sel_hi:[1,1,0]
	v_pk_mul_f32 v[140:141], v[136:137], v[140:141]
	v_pk_mul_f32 v[142:143], v[138:139], v[142:143]
	v_pk_mul_f32 v[140:141], v[140:141], v[144:145]
	v_pk_mul_f32 v[142:143], v[142:143], v[146:147]
	v_max_f32_e32 v28, 0, v28
	v_max_f32_e32 v29, 0, v29
	v_max_f32_e32 v30, 0, v30
	v_max_f32_e32 v31, 0, v31
	v_pk_fma_f32 v[28:29], v[132:133], v[140:141], v[28:29] neg_lo:[1,0,0] neg_hi:[1,0,0]
	v_pk_fma_f32 v[30:31], v[134:135], v[142:143], v[30:31] neg_lo:[1,0,0] neg_hi:[1,0,0]
	v_and_b32_e32 v132, 0x7fffffff, v20
	v_and_b32_e32 v133, 0x7fffffff, v21
	v_and_b32_e32 v134, 0x7fffffff, v22
	v_and_b32_e32 v135, 0x7fffffff, v23
	v_pk_mul_f32 v[144:145], v[20:21], v[20:21]
	v_pk_mul_f32 v[146:147], v[22:23], v[22:23]
	v_pk_fma_f32 v[136:137], v[132:133], s[84:85], 1.0 op_sel_hi:[1,0,0]
	v_pk_fma_f32 v[138:139], v[134:135], s[84:85], 1.0 op_sel_hi:[1,0,0]
	v_pk_mul_f32 v[144:145], v[144:145], s[80:81] op_sel_hi:[1,0]
	v_pk_mul_f32 v[146:147], v[146:147], s[80:81] op_sel_hi:[1,0]
	v_rcp_f32_e32 v136, v136
	v_rcp_f32_e32 v137, v137
	v_rcp_f32_e32 v138, v138
	v_rcp_f32_e32 v139, v139
	v_exp_f32_e32 v144, v144
	v_exp_f32_e32 v145, v145
	v_exp_f32_e32 v146, v146
	v_exp_f32_e32 v147, v147
	v_pk_fma_f32 v[140:141], v[136:137], s[86:87], v[0:1] op_sel_hi:[1,0,0]
	v_pk_fma_f32 v[142:143], v[138:139], s[86:87], v[0:1] op_sel_hi:[1,0,0]
	v_pk_fma_f32 v[140:141], v[136:137], v[140:141], s[88:89] op_sel_hi:[1,1,0]
	v_pk_fma_f32 v[142:143], v[138:139], v[142:143], s[88:89] op_sel_hi:[1,1,0]
	v_pk_fma_f32 v[140:141], v[136:137], v[140:141], s[82:83] op_sel_hi:[1,1,0]
	v_pk_fma_f32 v[142:143], v[138:139], v[142:143], s[82:83] op_sel_hi:[1,1,0]
	v_pk_fma_f32 v[140:141], v[136:137], v[140:141], s[48:49] op_sel_hi:[1,1,0]
	v_pk_fma_f32 v[142:143], v[138:139], v[142:143], s[48:49] op_sel_hi:[1,1,0]
	v_pk_mul_f32 v[140:141], v[136:137], v[140:141]
	v_pk_mul_f32 v[142:143], v[138:139], v[142:143]
	v_pk_mul_f32 v[140:141], v[140:141], v[144:145]
	v_pk_mul_f32 v[142:143], v[142:143], v[146:147]
	v_max_f32_e32 v20, 0, v20
	v_max_f32_e32 v21, 0, v21
	v_max_f32_e32 v22, 0, v22
	v_max_f32_e32 v23, 0, v23
	v_pk_fma_f32 v[20:21], v[132:133], v[140:141], v[20:21] neg_lo:[1,0,0] neg_hi:[1,0,0]
	v_pk_fma_f32 v[22:23], v[134:135], v[142:143], v[22:23] neg_lo:[1,0,0] neg_hi:[1,0,0]
	v_cvt_pk_bf16_f32 v28, v28, v29
	v_cvt_pk_bf16_f32 v29, v30, v31
	v_cvt_pk_bf16_f32 v30, v20, v21
	v_cvt_pk_bf16_f32 v31, v22, v23
	global_store_dwordx4 v148, v[28:31], s[50:51] sc1
	v_and_b32_e32 v132, 0x7fffffff, v12
	v_and_b32_e32 v133, 0x7fffffff, v13
	v_and_b32_e32 v134, 0x7fffffff, v14
	v_and_b32_e32 v135, 0x7fffffff, v15
	v_pk_mul_f32 v[144:145], v[12:13], v[12:13]
	v_pk_mul_f32 v[146:147], v[14:15], v[14:15]
	v_pk_fma_f32 v[136:137], v[132:133], s[84:85], 1.0 op_sel_hi:[1,0,0]
	v_pk_fma_f32 v[138:139], v[134:135], s[84:85], 1.0 op_sel_hi:[1,0,0]
	v_pk_mul_f32 v[144:145], v[144:145], s[80:81] op_sel_hi:[1,0]
	v_pk_mul_f32 v[146:147], v[146:147], s[80:81] op_sel_hi:[1,0]
	v_rcp_f32_e32 v136, v136
	v_rcp_f32_e32 v137, v137
	v_rcp_f32_e32 v138, v138
	v_rcp_f32_e32 v139, v139
	v_exp_f32_e32 v144, v144
	v_exp_f32_e32 v145, v145
	v_exp_f32_e32 v146, v146
	v_exp_f32_e32 v147, v147
	v_pk_fma_f32 v[140:141], v[136:137], s[86:87], v[0:1] op_sel_hi:[1,0,0]
	v_pk_fma_f32 v[142:143], v[138:139], s[86:87], v[0:1] op_sel_hi:[1,0,0]
	v_pk_fma_f32 v[140:141], v[136:137], v[140:141], s[88:89] op_sel_hi:[1,1,0]
	v_pk_fma_f32 v[142:143], v[138:139], v[142:143], s[88:89] op_sel_hi:[1,1,0]
	v_pk_fma_f32 v[140:141], v[136:137], v[140:141], s[82:83] op_sel_hi:[1,1,0]
	v_pk_fma_f32 v[142:143], v[138:139], v[142:143], s[82:83] op_sel_hi:[1,1,0]
	v_pk_fma_f32 v[140:141], v[136:137], v[140:141], s[48:49] op_sel_hi:[1,1,0]
	v_pk_fma_f32 v[142:143], v[138:139], v[142:143], s[48:49] op_sel_hi:[1,1,0]
	v_pk_mul_f32 v[140:141], v[136:137], v[140:141]
	v_pk_mul_f32 v[142:143], v[138:139], v[142:143]
	v_pk_mul_f32 v[140:141], v[140:141], v[144:145]
	v_pk_mul_f32 v[142:143], v[142:143], v[146:147]
	v_max_f32_e32 v12, 0, v12
	v_max_f32_e32 v13, 0, v13
	v_max_f32_e32 v14, 0, v14
	v_max_f32_e32 v15, 0, v15
	v_pk_fma_f32 v[12:13], v[132:133], v[140:141], v[12:13] neg_lo:[1,0,0] neg_hi:[1,0,0]
	v_pk_fma_f32 v[14:15], v[134:135], v[142:143], v[14:15] neg_lo:[1,0,0] neg_hi:[1,0,0]
	v_and_b32_e32 v132, 0x7fffffff, v4
	v_and_b32_e32 v133, 0x7fffffff, v5
	v_and_b32_e32 v134, 0x7fffffff, v6
	v_and_b32_e32 v135, 0x7fffffff, v7
	v_pk_mul_f32 v[144:145], v[4:5], v[4:5]
	v_pk_mul_f32 v[146:147], v[6:7], v[6:7]
	v_pk_fma_f32 v[136:137], v[132:133], s[84:85], 1.0 op_sel_hi:[1,0,0]
	v_pk_fma_f32 v[138:139], v[134:135], s[84:85], 1.0 op_sel_hi:[1,0,0]
	v_pk_mul_f32 v[144:145], v[144:145], s[80:81] op_sel_hi:[1,0]
	v_pk_mul_f32 v[146:147], v[146:147], s[80:81] op_sel_hi:[1,0]
	v_rcp_f32_e32 v136, v136
	v_rcp_f32_e32 v137, v137
	v_rcp_f32_e32 v138, v138
	v_rcp_f32_e32 v139, v139
	v_exp_f32_e32 v144, v144
	v_exp_f32_e32 v145, v145
	v_exp_f32_e32 v146, v146
	v_exp_f32_e32 v147, v147
	v_pk_fma_f32 v[140:141], v[136:137], s[86:87], v[0:1] op_sel_hi:[1,0,0]
	v_pk_fma_f32 v[142:143], v[138:139], s[86:87], v[0:1] op_sel_hi:[1,0,0]
	v_pk_fma_f32 v[140:141], v[136:137], v[140:141], s[88:89] op_sel_hi:[1,1,0]
	v_pk_fma_f32 v[142:143], v[138:139], v[142:143], s[88:89] op_sel_hi:[1,1,0]
	v_pk_fma_f32 v[140:141], v[136:137], v[140:141], s[82:83] op_sel_hi:[1,1,0]
	v_pk_fma_f32 v[142:143], v[138:139], v[142:143], s[82:83] op_sel_hi:[1,1,0]
	v_pk_fma_f32 v[140:141], v[136:137], v[140:141], s[48:49] op_sel_hi:[1,1,0]
	v_pk_fma_f32 v[142:143], v[138:139], v[142:143], s[48:49] op_sel_hi:[1,1,0]
	v_pk_mul_f32 v[140:141], v[136:137], v[140:141]
	v_pk_mul_f32 v[142:143], v[138:139], v[142:143]
	v_pk_mul_f32 v[140:141], v[140:141], v[144:145]
	v_pk_mul_f32 v[142:143], v[142:143], v[146:147]
	v_max_f32_e32 v4, 0, v4
	v_max_f32_e32 v5, 0, v5
	v_max_f32_e32 v6, 0, v6
	v_max_f32_e32 v7, 0, v7
	v_pk_fma_f32 v[4:5], v[132:133], v[140:141], v[4:5] neg_lo:[1,0,0] neg_hi:[1,0,0]
	v_pk_fma_f32 v[6:7], v[134:135], v[142:143], v[6:7] neg_lo:[1,0,0] neg_hi:[1,0,0]
	v_cvt_pk_bf16_f32 v12, v12, v13
	v_cvt_pk_bf16_f32 v13, v14, v15
	v_cvt_pk_bf16_f32 v14, v4, v5
	v_cvt_pk_bf16_f32 v15, v6, v7
	global_store_dwordx4 v148, v[12:15], s[50:51] offset:256 sc1
	s_branch .LBB0_326
